# baseline (speedup 1.0000x reference)
; template <int D, int ROT0, int HALF, bool GAIN, bool KEEP = true>
; DI void chunk_nr(u16* p, const float* __restrict__ gain, const float* __restrict__ tab) {
;     ...
;   if (GAIN) {
;     float ss = 0.f;
; #pragma unroll
;     for (int v = 0; v < NV; ++v) {
;       const f32x8 f = bf8_to_f32(RAWV(v));
; #pragma unroll
;       for (int e = 0; e < 8; ++e) ss += f[e] * f[e];
;       if (!KEEP && (v & 7) == 7) __builtin_amdgcn_sched_barrier(0);
;     }
; DI void postproc2_phase(const Params& p, int layer) {
;     ...
;       u16* kp = p.MLAK + (long)tok * 768 + (slot - 4) * 192;
;       const u16* kr = p.PROJ + (long)tok * PW + BKR;
; #pragma unroll
;       for (int v = 0; v < 8; ++v) *(u32x4*)(kp + 128 + v * 8) = *(const u32x4*)(kr + v * 8);
;       chunk_nr<192, 128, 32, true, false>(kp, p.mla_qk_norm + layer * 384 + 192, tb);
.LBB0_191:
	v_ashrrev_i32_e32 v0, 31, v27
	v_lshrrev_b32_e32 v0, 18, v0
	v_lshl_add_u64 v[2:3], v[26:27], 0, v[0:1]
	v_and_b32_e32 v0, 0xffffc000, v2
	v_sub_co_u32_e32 v0, vcc, v26, v0
	v_readfirstlane_b32 s9, v27
	v_ashrrev_i16_e32 v2, 15, v0
	s_ashr_i32 s10, s9, 31
	v_lshrrev_b16_e32 v2, 4, v2
	v_readfirstlane_b32 s8, v26
	s_lshr_b32 s10, s10, 18
	v_add_u16_e32 v2, v0, v2
	s_add_u32 s10, s8, s10
	v_and_b32_e32 v2, 0xfffff000, v2
	s_addc_u32 s11, s9, 0
	v_sub_u16_e32 v2, v0, v2
	s_ashr_i64 s[12:13], s[10:11], 14
	v_mul_hi_i32_i24_sdwa v3, sext(v2), s59 dst_sel:DWORD dst_unused:UNUSED_PAD src0_sel:WORD_0 src1_sel:DWORD
	v_mul_i32_i24_sdwa v2, sext(v2), s59 dst_sel:DWORD dst_unused:UNUSED_PAD src0_sel:WORD_0 src1_sel:DWORD
	v_cmp_gt_i64_e32 vcc, s[8:9], v[192:193]
	v_lshl_add_u64 v[28:29], s[44:45], 0, v[2:3]
	v_mul_hi_i32_i24_e32 v31, 0x600, v0
	v_mul_i32_i24_e32 v30, 0x600, v0
	s_mov_b64 s[10:11], -1
	s_mul_i32 s9, s12, 0xc0
	s_cbranch_vccz .LBB0_193
	v_readlane_b32 s12, v249, 6
	v_readlane_b32 s10, v249, 29
	v_readlane_b32 s14, v249, 8
	v_readlane_b32 s15, v249, 9
	v_readlane_b32 s18, v249, 12
	v_readlane_b32 s19, v249, 13
	v_readlane_b32 s11, v249, 30
	s_mov_b32 s15, s11
	v_lshl_add_u64 v[2:3], s[18:19], 0, v[30:31]
	s_add_i32 s14, s9, 0xfffffd00
	v_readlane_b32 s13, v249, 7
	v_lshl_add_u64 v[32:33], s[14:15], 1, v[2:3]
	v_mul_hi_i32_i24_e32 v3, 0x2600, v0
	v_mul_i32_i24_e32 v2, 0x2600, v0
	v_lshl_add_u64 v[2:3], s[12:13], 0, v[2:3]
	s_waitcnt vmcnt(0)
	v_add_co_u32_e32 v6, vcc, 0x2000, v2
	v_readlane_b32 s16, v249, 10
	s_nop 0
	v_addc_co_u32_e32 v7, vcc, 0, v3, vcc
	global_load_dwordx4 v[8:11], v[6:7], off offset:1152
	global_load_dwordx4 v[12:15], v[6:7], off offset:1168
	global_load_dwordx4 v[16:19], v[6:7], off offset:1184
	global_load_dwordx4 v[20:23], v[6:7], off offset:1200
	global_load_dwordx4 v[36:39], v[6:7], off offset:1216
	global_load_dwordx4 v[40:43], v[6:7], off offset:1232
	global_load_dwordx4 v[44:47], v[6:7], off offset:1248
	global_load_dwordx4 v[48:51], v[6:7], off offset:1264
	v_readlane_b32 s17, v249, 11
	v_writelane_b32 v249, s10, 29
	v_writelane_b32 v249, s11, 30
	s_waitcnt vmcnt(0)
	global_store_dwordx4 v[32:33], v[8:11], off offset:256
	global_store_dwordx4 v[32:33], v[12:15], off offset:272
	global_store_dwordx4 v[32:33], v[16:19], off offset:288
	global_store_dwordx4 v[32:33], v[20:23], off offset:304
	global_store_dwordx4 v[32:33], v[36:39], off offset:320
	global_store_dwordx4 v[32:33], v[40:43], off offset:336
	global_store_dwordx4 v[32:33], v[44:47], off offset:352
	global_store_dwordx4 v[32:33], v[48:51], off offset:368
	global_load_dwordx4 v[2:5], v[32:33], off offset:48
	global_load_dwordx4 v[6:9], v[32:33], off offset:32
	global_load_dwordx4 v[10:13], v[32:33], off offset:16
	global_load_dwordx4 v[14:17], v[32:33], off
	global_load_dwordx4 v[52:55], v[32:33], off offset:112
	global_load_dwordx4 v[56:59], v[32:33], off offset:96
	global_load_dwordx4 v[60:63], v[32:33], off offset:80
	global_load_dwordx4 v[64:67], v[32:33], off offset:64
	global_load_dwordx4 v[68:71], v[32:33], off offset:176
	global_load_dwordx4 v[72:75], v[32:33], off offset:160
	global_load_dwordx4 v[76:79], v[32:33], off offset:144
	global_load_dwordx4 v[80:83], v[32:33], off offset:128
	global_load_dwordx4 v[110:113], v[32:33], off offset:240
	global_load_dwordx4 v[114:117], v[32:33], off offset:224
	global_load_dwordx4 v[118:121], v[32:33], off offset:208
	global_load_dwordx4 v[122:125], v[32:33], off offset:192
	global_load_dwordx4 v[126:129], v[32:33], off offset:304
	global_load_dwordx4 v[130:133], v[32:33], off offset:288
	global_load_dwordx4 v[134:137], v[32:33], off offset:272
	global_load_dwordx4 v[138:141], v[32:33], off offset:256
	global_load_dwordx4 v[142:145], v[32:33], off offset:368
	global_load_dwordx4 v[146:149], v[32:33], off offset:352
	global_load_dwordx4 v[150:153], v[32:33], off offset:336
	global_load_dwordx4 v[154:157], v[32:33], off offset:320
	s_waitcnt vmcnt(20)
	v_and_b32_e32 v0, 0xffff0000, v14
	v_lshlrev_b32_e32 v18, 16, v14
	v_mul_f32_e32 v0, v0, v0
	v_lshlrev_b32_e32 v14, 16, v15
	v_fmac_f32_e32 v0, v18, v18
	v_and_b32_e32 v15, 0xffff0000, v15
	v_fmac_f32_e32 v0, v14, v14
	v_lshlrev_b32_e32 v19, 16, v16
	v_fmac_f32_e32 v0, v15, v15
	v_and_b32_e32 v16, 0xffff0000, v16
	v_fmac_f32_e32 v0, v19, v19
	v_lshlrev_b32_e32 v20, 16, v17
	v_fmac_f32_e32 v0, v16, v16
	v_and_b32_e32 v17, 0xffff0000, v17
	v_fmac_f32_e32 v0, v20, v20
	v_fmac_f32_e32 v0, v17, v17
	v_lshlrev_b32_e32 v14, 16, v10
	v_and_b32_e32 v10, 0xffff0000, v10
	v_fmac_f32_e32 v0, v14, v14
	v_lshlrev_b32_e32 v15, 16, v11
	v_fmac_f32_e32 v0, v10, v10
	v_and_b32_e32 v11, 0xffff0000, v11
	v_fmac_f32_e32 v0, v15, v15
	v_lshlrev_b32_e32 v16, 16, v12
	v_fmac_f32_e32 v0, v11, v11
	v_and_b32_e32 v12, 0xffff0000, v12
	v_fmac_f32_e32 v0, v16, v16
	v_lshlrev_b32_e32 v17, 16, v13
	v_fmac_f32_e32 v0, v12, v12
	v_and_b32_e32 v13, 0xffff0000, v13
	v_fmac_f32_e32 v0, v17, v17
	v_fmac_f32_e32 v0, v13, v13
	v_lshlrev_b32_e32 v10, 16, v6
	v_and_b32_e32 v6, 0xffff0000, v6
	v_fmac_f32_e32 v0, v10, v10
	v_lshlrev_b32_e32 v11, 16, v7
	v_fmac_f32_e32 v0, v6, v6
	v_and_b32_e32 v7, 0xffff0000, v7
	v_fmac_f32_e32 v0, v11, v11
	v_lshlrev_b32_e32 v12, 16, v8
	v_fmac_f32_e32 v0, v7, v7
	v_and_b32_e32 v8, 0xffff0000, v8
	v_fmac_f32_e32 v0, v12, v12
	v_lshlrev_b32_e32 v13, 16, v9
	v_fmac_f32_e32 v0, v8, v8
	v_and_b32_e32 v9, 0xffff0000, v9
	v_fmac_f32_e32 v0, v13, v13
	v_fmac_f32_e32 v0, v9, v9
	v_lshlrev_b32_e32 v6, 16, v2
	v_and_b32_e32 v2, 0xffff0000, v2
	v_fmac_f32_e32 v0, v6, v6
	v_lshlrev_b32_e32 v7, 16, v3
	v_fmac_f32_e32 v0, v2, v2
	v_and_b32_e32 v3, 0xffff0000, v3
	v_fmac_f32_e32 v0, v7, v7
	v_lshlrev_b32_e32 v8, 16, v4
	v_fmac_f32_e32 v0, v3, v3
	v_and_b32_e32 v4, 0xffff0000, v4
	v_fmac_f32_e32 v0, v8, v8
	v_lshlrev_b32_e32 v9, 16, v5
	v_fmac_f32_e32 v0, v4, v4
	v_and_b32_e32 v5, 0xffff0000, v5
	v_fmac_f32_e32 v0, v9, v9
	v_fmac_f32_e32 v0, v5, v5
	s_waitcnt vmcnt(16)
; template <int D, int ROT0, int HALF, bool GAIN, bool KEEP = true>
; DI void chunk_nr(u16* p, const float* __restrict__ gain, const float* __restrict__ tab) {
;     ...
;   if (GAIN) {
;     float ss = 0.f;
; #pragma unroll
;     for (int v = 0; v < NV; ++v) {
;       const f32x8 f = bf8_to_f32(RAWV(v));
; #pragma unroll
;       for (int e = 0; e < 8; ++e) ss += f[e] * f[e];
;       if (!KEEP && (v & 7) == 7) __builtin_amdgcn_sched_barrier(0);
;     }
	v_lshlrev_b32_e32 v18, 16, v64
	v_and_b32_e32 v64, 0xffff0000, v64
	v_fmac_f32_e32 v0, v18, v18
	v_lshlrev_b32_e32 v19, 16, v65
	v_fmac_f32_e32 v0, v64, v64
	v_and_b32_e32 v65, 0xffff0000, v65
	v_fmac_f32_e32 v0, v19, v19
	v_lshlrev_b32_e32 v20, 16, v66
	v_fmac_f32_e32 v0, v65, v65
	v_and_b32_e32 v66, 0xffff0000, v66
	v_fmac_f32_e32 v0, v20, v20
	v_lshlrev_b32_e32 v21, 16, v67
	v_fmac_f32_e32 v0, v66, v66
	v_and_b32_e32 v67, 0xffff0000, v67
	v_fmac_f32_e32 v0, v21, v21
	v_fmac_f32_e32 v0, v67, v67
	v_lshlrev_b32_e32 v64, 16, v60
	v_and_b32_e32 v60, 0xffff0000, v60
	v_fmac_f32_e32 v0, v64, v64
	v_lshlrev_b32_e32 v65, 16, v61
	v_fmac_f32_e32 v0, v60, v60
	v_and_b32_e32 v61, 0xffff0000, v61
	v_fmac_f32_e32 v0, v65, v65
	v_lshlrev_b32_e32 v66, 16, v62
	v_fmac_f32_e32 v0, v61, v61
	v_and_b32_e32 v62, 0xffff0000, v62
	v_fmac_f32_e32 v0, v66, v66
	v_lshlrev_b32_e32 v67, 16, v63
	v_fmac_f32_e32 v0, v62, v62
	v_and_b32_e32 v63, 0xffff0000, v63
	v_fmac_f32_e32 v0, v67, v67
	v_fmac_f32_e32 v0, v63, v63
	v_lshlrev_b32_e32 v60, 16, v56
	v_and_b32_e32 v56, 0xffff0000, v56
	v_fmac_f32_e32 v0, v60, v60
	v_lshlrev_b32_e32 v61, 16, v57
	v_fmac_f32_e32 v0, v56, v56
	v_and_b32_e32 v57, 0xffff0000, v57
	v_fmac_f32_e32 v0, v61, v61
	v_lshlrev_b32_e32 v62, 16, v58
	v_fmac_f32_e32 v0, v57, v57
	v_and_b32_e32 v58, 0xffff0000, v58
	v_fmac_f32_e32 v0, v62, v62
	v_lshlrev_b32_e32 v63, 16, v59
	v_fmac_f32_e32 v0, v58, v58
	v_and_b32_e32 v59, 0xffff0000, v59
	v_fmac_f32_e32 v0, v63, v63
	v_fmac_f32_e32 v0, v59, v59
	v_lshlrev_b32_e32 v56, 16, v52
	v_and_b32_e32 v52, 0xffff0000, v52
	v_fmac_f32_e32 v0, v56, v56
	v_lshlrev_b32_e32 v57, 16, v53
	v_fmac_f32_e32 v0, v52, v52
	v_and_b32_e32 v53, 0xffff0000, v53
	v_fmac_f32_e32 v0, v57, v57
	v_lshlrev_b32_e32 v58, 16, v54
	v_fmac_f32_e32 v0, v53, v53
	v_and_b32_e32 v54, 0xffff0000, v54
	v_fmac_f32_e32 v0, v58, v58
	v_lshlrev_b32_e32 v59, 16, v55
	v_fmac_f32_e32 v0, v54, v54
	v_and_b32_e32 v55, 0xffff0000, v55
	v_fmac_f32_e32 v0, v59, v59
	v_fmac_f32_e32 v0, v55, v55
	s_waitcnt vmcnt(12)
	v_lshlrev_b32_e32 v18, 16, v80
	v_and_b32_e32 v80, 0xffff0000, v80
	v_fmac_f32_e32 v0, v18, v18
	v_lshlrev_b32_e32 v19, 16, v81
	v_fmac_f32_e32 v0, v80, v80
	v_and_b32_e32 v81, 0xffff0000, v81
	v_fmac_f32_e32 v0, v19, v19
	v_lshlrev_b32_e32 v20, 16, v82
	v_fmac_f32_e32 v0, v81, v81
	v_and_b32_e32 v82, 0xffff0000, v82
	v_fmac_f32_e32 v0, v20, v20
	v_lshlrev_b32_e32 v21, 16, v83
	v_fmac_f32_e32 v0, v82, v82
	v_and_b32_e32 v83, 0xffff0000, v83
	v_fmac_f32_e32 v0, v21, v21
	v_fmac_f32_e32 v0, v83, v83
	v_lshlrev_b32_e32 v80, 16, v76
	v_and_b32_e32 v76, 0xffff0000, v76
	v_fmac_f32_e32 v0, v80, v80
	v_lshlrev_b32_e32 v81, 16, v77
	v_fmac_f32_e32 v0, v76, v76
	v_and_b32_e32 v77, 0xffff0000, v77
	v_fmac_f32_e32 v0, v81, v81
	v_lshlrev_b32_e32 v82, 16, v78
	v_fmac_f32_e32 v0, v77, v77
	v_and_b32_e32 v78, 0xffff0000, v78
	v_fmac_f32_e32 v0, v82, v82
	v_lshlrev_b32_e32 v83, 16, v79
	v_fmac_f32_e32 v0, v78, v78
	v_and_b32_e32 v79, 0xffff0000, v79
	v_fmac_f32_e32 v0, v83, v83
	v_fmac_f32_e32 v0, v79, v79
	v_lshlrev_b32_e32 v76, 16, v72
	v_and_b32_e32 v72, 0xffff0000, v72
	v_fmac_f32_e32 v0, v76, v76
	v_lshlrev_b32_e32 v77, 16, v73
	v_fmac_f32_e32 v0, v72, v72
	v_and_b32_e32 v73, 0xffff0000, v73
	v_fmac_f32_e32 v0, v77, v77
	v_lshlrev_b32_e32 v78, 16, v74
	v_fmac_f32_e32 v0, v73, v73
	v_and_b32_e32 v74, 0xffff0000, v74
	v_fmac_f32_e32 v0, v78, v78
	v_lshlrev_b32_e32 v79, 16, v75
	v_fmac_f32_e32 v0, v74, v74
	v_and_b32_e32 v75, 0xffff0000, v75
	v_fmac_f32_e32 v0, v79, v79
	v_fmac_f32_e32 v0, v75, v75
	v_lshlrev_b32_e32 v72, 16, v68
	v_and_b32_e32 v68, 0xffff0000, v68
	v_fmac_f32_e32 v0, v72, v72
	v_lshlrev_b32_e32 v73, 16, v69
	v_fmac_f32_e32 v0, v68, v68
	v_and_b32_e32 v69, 0xffff0000, v69
	v_fmac_f32_e32 v0, v73, v73
	v_lshlrev_b32_e32 v74, 16, v70
	v_fmac_f32_e32 v0, v69, v69
	v_and_b32_e32 v70, 0xffff0000, v70
	v_fmac_f32_e32 v0, v74, v74
	v_lshlrev_b32_e32 v75, 16, v71
	v_fmac_f32_e32 v0, v70, v70
	v_and_b32_e32 v71, 0xffff0000, v71
	v_fmac_f32_e32 v0, v75, v75
	v_fmac_f32_e32 v0, v71, v71
	s_waitcnt vmcnt(8)
	v_lshlrev_b32_e32 v18, 16, v122
	v_and_b32_e32 v122, 0xffff0000, v122
	v_fmac_f32_e32 v0, v18, v18
	v_lshlrev_b32_e32 v19, 16, v123
	v_fmac_f32_e32 v0, v122, v122
	v_and_b32_e32 v123, 0xffff0000, v123
	v_fmac_f32_e32 v0, v19, v19
	v_lshlrev_b32_e32 v20, 16, v124
	v_fmac_f32_e32 v0, v123, v123
	v_and_b32_e32 v124, 0xffff0000, v124
	v_fmac_f32_e32 v0, v20, v20
	v_lshlrev_b32_e32 v21, 16, v125
	v_fmac_f32_e32 v0, v124, v124
	v_and_b32_e32 v125, 0xffff0000, v125
	v_fmac_f32_e32 v0, v21, v21
	v_fmac_f32_e32 v0, v125, v125
	v_lshlrev_b32_e32 v122, 16, v118
	v_and_b32_e32 v118, 0xffff0000, v118
	v_fmac_f32_e32 v0, v122, v122
	v_lshlrev_b32_e32 v123, 16, v119
	v_fmac_f32_e32 v0, v118, v118
	v_and_b32_e32 v119, 0xffff0000, v119
	v_fmac_f32_e32 v0, v123, v123
	v_lshlrev_b32_e32 v124, 16, v120
	v_fmac_f32_e32 v0, v119, v119
	v_and_b32_e32 v120, 0xffff0000, v120
	v_fmac_f32_e32 v0, v124, v124
	v_lshlrev_b32_e32 v125, 16, v121
	v_fmac_f32_e32 v0, v120, v120
	v_and_b32_e32 v121, 0xffff0000, v121
	v_fmac_f32_e32 v0, v125, v125
	v_fmac_f32_e32 v0, v121, v121
	v_lshlrev_b32_e32 v118, 16, v114
	v_and_b32_e32 v114, 0xffff0000, v114
	v_fmac_f32_e32 v0, v118, v118
	v_lshlrev_b32_e32 v119, 16, v115
	v_fmac_f32_e32 v0, v114, v114
	v_and_b32_e32 v115, 0xffff0000, v115
	v_fmac_f32_e32 v0, v119, v119
	v_lshlrev_b32_e32 v120, 16, v116
	v_fmac_f32_e32 v0, v115, v115
	v_and_b32_e32 v116, 0xffff0000, v116
	v_fmac_f32_e32 v0, v120, v120
	v_lshlrev_b32_e32 v121, 16, v117
	v_fmac_f32_e32 v0, v116, v116
	v_and_b32_e32 v117, 0xffff0000, v117
	v_fmac_f32_e32 v0, v121, v121
	v_fmac_f32_e32 v0, v117, v117
	v_lshlrev_b32_e32 v114, 16, v110
	v_and_b32_e32 v110, 0xffff0000, v110
	v_fmac_f32_e32 v0, v114, v114
	v_lshlrev_b32_e32 v115, 16, v111
	v_fmac_f32_e32 v0, v110, v110
	v_and_b32_e32 v111, 0xffff0000, v111
	v_fmac_f32_e32 v0, v115, v115
	v_lshlrev_b32_e32 v116, 16, v112
	v_fmac_f32_e32 v0, v111, v111
	v_and_b32_e32 v112, 0xffff0000, v112
	v_fmac_f32_e32 v0, v116, v116
	v_lshlrev_b32_e32 v117, 16, v113
	v_fmac_f32_e32 v0, v112, v112
	v_and_b32_e32 v113, 0xffff0000, v113
	v_fmac_f32_e32 v0, v117, v117
	v_fmac_f32_e32 v0, v113, v113
	s_waitcnt vmcnt(4)
; template <int D, int ROT0, int HALF, bool GAIN, bool KEEP = true>
; DI void chunk_nr(u16* p, const float* __restrict__ gain, const float* __restrict__ tab) {
;     ...
; #pragma unroll
;     for (int v = 0; v < NV; ++v) {
;       const f32x8 f = bf8_to_f32(RAWV(v));
; #pragma unroll
;       for (int e = 0; e < 8; ++e) ss += f[e] * f[e];
;       if (!KEEP && (v & 7) == 7) __builtin_amdgcn_sched_barrier(0);
;     }
;     rstd = rsqrtf(ss * (1.0f / D) + EPS);
	v_lshlrev_b32_e32 v18, 16, v138
	v_and_b32_e32 v138, 0xffff0000, v138
	v_fmac_f32_e32 v0, v18, v18
	v_lshlrev_b32_e32 v19, 16, v139
	v_fmac_f32_e32 v0, v138, v138
	v_and_b32_e32 v139, 0xffff0000, v139
	v_fmac_f32_e32 v0, v19, v19
	v_lshlrev_b32_e32 v20, 16, v140
	v_fmac_f32_e32 v0, v139, v139
	v_and_b32_e32 v140, 0xffff0000, v140
	v_fmac_f32_e32 v0, v20, v20
	v_lshlrev_b32_e32 v21, 16, v141
	v_fmac_f32_e32 v0, v140, v140
	v_and_b32_e32 v141, 0xffff0000, v141
	v_fmac_f32_e32 v0, v21, v21
	v_fmac_f32_e32 v0, v141, v141
	v_lshlrev_b32_e32 v138, 16, v134
	v_and_b32_e32 v134, 0xffff0000, v134
	v_fmac_f32_e32 v0, v138, v138
	v_lshlrev_b32_e32 v139, 16, v135
	v_fmac_f32_e32 v0, v134, v134
	v_and_b32_e32 v135, 0xffff0000, v135
	v_fmac_f32_e32 v0, v139, v139
	v_lshlrev_b32_e32 v140, 16, v136
	v_fmac_f32_e32 v0, v135, v135
	v_and_b32_e32 v136, 0xffff0000, v136
	v_fmac_f32_e32 v0, v140, v140
	v_lshlrev_b32_e32 v141, 16, v137
	v_fmac_f32_e32 v0, v136, v136
	v_and_b32_e32 v137, 0xffff0000, v137
	v_fmac_f32_e32 v0, v141, v141
	v_fmac_f32_e32 v0, v137, v137
	v_lshlrev_b32_e32 v134, 16, v130
	v_and_b32_e32 v130, 0xffff0000, v130
	v_fmac_f32_e32 v0, v134, v134
	v_lshlrev_b32_e32 v135, 16, v131
	v_fmac_f32_e32 v0, v130, v130
	v_and_b32_e32 v131, 0xffff0000, v131
	v_fmac_f32_e32 v0, v135, v135
	v_lshlrev_b32_e32 v136, 16, v132
	v_fmac_f32_e32 v0, v131, v131
	v_and_b32_e32 v132, 0xffff0000, v132
	v_fmac_f32_e32 v0, v136, v136
	v_lshlrev_b32_e32 v137, 16, v133
	v_fmac_f32_e32 v0, v132, v132
	v_and_b32_e32 v133, 0xffff0000, v133
	v_fmac_f32_e32 v0, v137, v137
	v_fmac_f32_e32 v0, v133, v133
	v_lshlrev_b32_e32 v130, 16, v126
	v_and_b32_e32 v126, 0xffff0000, v126
	v_fmac_f32_e32 v0, v130, v130
	v_lshlrev_b32_e32 v131, 16, v127
	v_fmac_f32_e32 v0, v126, v126
	v_and_b32_e32 v127, 0xffff0000, v127
	v_fmac_f32_e32 v0, v131, v131
	v_lshlrev_b32_e32 v132, 16, v128
	v_fmac_f32_e32 v0, v127, v127
	v_and_b32_e32 v128, 0xffff0000, v128
	v_fmac_f32_e32 v0, v132, v132
	v_lshlrev_b32_e32 v133, 16, v129
	v_fmac_f32_e32 v0, v128, v128
	v_and_b32_e32 v129, 0xffff0000, v129
	v_fmac_f32_e32 v0, v133, v133
	v_fmac_f32_e32 v0, v129, v129
	s_waitcnt vmcnt(0)
	v_lshlrev_b32_e32 v18, 16, v154
	v_and_b32_e32 v154, 0xffff0000, v154
	v_fmac_f32_e32 v0, v18, v18
	v_lshlrev_b32_e32 v19, 16, v155
	v_fmac_f32_e32 v0, v154, v154
	v_and_b32_e32 v155, 0xffff0000, v155
	v_fmac_f32_e32 v0, v19, v19
	v_lshlrev_b32_e32 v20, 16, v156
	v_fmac_f32_e32 v0, v155, v155
	v_and_b32_e32 v156, 0xffff0000, v156
	v_fmac_f32_e32 v0, v20, v20
	v_lshlrev_b32_e32 v21, 16, v157
	v_fmac_f32_e32 v0, v156, v156
	v_and_b32_e32 v157, 0xffff0000, v157
	v_fmac_f32_e32 v0, v21, v21
	v_fmac_f32_e32 v0, v157, v157
	v_lshlrev_b32_e32 v154, 16, v150
	v_and_b32_e32 v150, 0xffff0000, v150
	v_fmac_f32_e32 v0, v154, v154
	v_lshlrev_b32_e32 v155, 16, v151
	v_fmac_f32_e32 v0, v150, v150
	v_and_b32_e32 v151, 0xffff0000, v151
	v_fmac_f32_e32 v0, v155, v155
	v_lshlrev_b32_e32 v156, 16, v152
	v_fmac_f32_e32 v0, v151, v151
	v_and_b32_e32 v152, 0xffff0000, v152
	v_fmac_f32_e32 v0, v156, v156
	v_lshlrev_b32_e32 v157, 16, v153
	v_fmac_f32_e32 v0, v152, v152
	v_and_b32_e32 v153, 0xffff0000, v153
	v_fmac_f32_e32 v0, v157, v157
	v_fmac_f32_e32 v0, v153, v153
	v_lshlrev_b32_e32 v150, 16, v146
	v_and_b32_e32 v146, 0xffff0000, v146
	v_fmac_f32_e32 v0, v150, v150
	v_lshlrev_b32_e32 v151, 16, v147
	v_fmac_f32_e32 v0, v146, v146
	v_and_b32_e32 v147, 0xffff0000, v147
	v_fmac_f32_e32 v0, v151, v151
	v_lshlrev_b32_e32 v152, 16, v148
	v_fmac_f32_e32 v0, v147, v147
	v_and_b32_e32 v148, 0xffff0000, v148
	v_fmac_f32_e32 v0, v152, v152
	v_and_b32_e32 v146, 0xffff0000, v149
	v_lshlrev_b32_e32 v147, 16, v149
	v_fmac_f32_e32 v0, v148, v148
	v_pk_mul_f32 v[146:147], v[146:147], v[146:147]
	s_nop 0
	v_add_f32_e32 v0, v147, v0
	v_add_f32_e32 v0, v146, v0
	v_and_b32_e32 v146, 0xffff0000, v142
	v_lshlrev_b32_e32 v147, 16, v142
	v_pk_mul_f32 v[146:147], v[146:147], v[146:147]
	v_and_b32_e32 v142, 0xffff0000, v143
	v_add_f32_e32 v0, v147, v0
	v_lshlrev_b32_e32 v143, 16, v143
	v_add_f32_e32 v0, v146, v0
	v_pk_mul_f32 v[142:143], v[142:143], v[142:143]
	s_nop 0
	v_add_f32_e32 v0, v143, v0
	v_add_f32_e32 v0, v142, v0
	v_and_b32_e32 v142, 0xffff0000, v144
	v_lshlrev_b32_e32 v143, 16, v144
	v_pk_mul_f32 v[142:143], v[142:143], v[142:143]
	s_nop 0
	v_add_f32_e32 v0, v143, v0
	v_add_f32_e32 v0, v142, v0
	v_and_b32_e32 v142, 0xffff0000, v145
	v_lshlrev_b32_e32 v143, 16, v145
	v_pk_mul_f32 v[142:143], v[142:143], v[142:143]
	s_nop 0
	v_add_f32_e32 v0, v143, v0
	v_add_f32_e32 v0, v142, v0
	v_fmamk_f32 v0, v0, 0x3baaaaab, v189
	v_cmp_gt_f32_e32 vcc, s55, v0
	v_mul_f32_e32 v2, 0x4b800000, v0
	s_nop 0
	v_cndmask_b32_e32 v0, v0, v2, vcc
	v_rsq_f32_e32 v0, v0
	s_nop 0
	v_mul_f32_e32 v2, 0x45800000, v0
	v_cndmask_b32_e32 v0, v0, v2, vcc
	global_load_dwordx4 v[2:5], v[32:33], off offset:48
	global_load_dwordx4 v[6:9], v[32:33], off offset:32
	global_load_dwordx4 v[14:17], v[32:33], off offset:16
	global_load_dwordx4 v[22:25], v[32:33], off
	global_load_dwordx4 v[10:13], v1, s[4:5] offset:816
	global_load_dwordx4 v[18:21], v1, s[4:5] offset:800
	global_load_dwordx4 v[34:37], v1, s[4:5] offset:784
	global_load_dwordx4 v[38:41], v1, s[4:5] offset:768
	s_waitcnt vmcnt(0)
; template <int D, int ROT0, int HALF, bool GAIN, bool KEEP = true>
; DI void chunk_nr(u16* p, const float* __restrict__ gain, const float* __restrict__ tab) {
;     ...
;     } else if (GAIN) {
;       f32x8 x1 = bf8_to_f32(RAWV(v));
;       const f32x8 g1 = *(const f32x8*)(gain + v * 8);
; #pragma unroll
;       for (int e = 0; e < 8; ++e) x1[e] = x1[e] * rstd * g1[e];
;       *(u32x4*)(p + v * 8) = f32_to_bf8(x1);
;     }
	v_lshlrev_b32_e32 v43, 16, v23
	v_lshlrev_b32_e32 v42, 16, v22
	v_and_b32_e32 v23, 0xffff0000, v23
	v_and_b32_e32 v22, 0xffff0000, v22
	v_mov_b32_e32 v44, v38
	v_mov_b32_e32 v45, v40
	v_pk_mul_f32 v[22:23], v[0:1], v[22:23] op_sel_hi:[0,1]
	v_mov_b32_e32 v40, v39
	v_lshlrev_b32_e32 v39, 16, v25
	v_lshlrev_b32_e32 v38, 16, v24
	v_and_b32_e32 v25, 0xffff0000, v25
	v_and_b32_e32 v24, 0xffff0000, v24
	v_pk_mul_f32 v[22:23], v[40:41], v[22:23]
	v_mov_b32_e32 v41, v36
	v_pk_mul_f32 v[24:25], v[0:1], v[24:25] op_sel_hi:[0,1]
	v_mov_b32_e32 v36, v35
	v_pk_mul_f32 v[42:43], v[0:1], v[42:43] op_sel_hi:[0,1]
	v_pk_mul_f32 v[38:39], v[0:1], v[38:39] op_sel_hi:[0,1]
	v_mov_b32_e32 v40, v34
	v_pk_mul_f32 v[24:25], v[36:37], v[24:25]
	v_pk_mul_f32 v[42:43], v[44:45], v[42:43]
	v_pk_mul_f32 v[38:39], v[40:41], v[38:39]
	v_bfe_u32 v34, v25, 16, 1
	v_bfe_u32 v35, v24, 16, 1
	v_bfe_u32 v36, v23, 16, 1
	v_bfe_u32 v37, v22, 16, 1
	v_add3_u32 v22, v22, v37, s54
	v_add3_u32 v23, v23, v36, s54
	v_add3_u32 v24, v24, v35, s54
	v_add3_u32 v25, v25, v34, s54
	v_bfe_u32 v34, v42, 16, 1
	v_bfe_u32 v35, v43, 16, 1
	v_bfe_u32 v36, v38, 16, 1
	v_bfe_u32 v37, v39, 16, 1
	v_add3_u32 v37, v39, v37, s54
	v_add3_u32 v36, v38, v36, s54
	v_add3_u32 v35, v43, v35, s54
	v_add3_u32 v34, v42, v34, s54
	v_lshrrev_b32_e32 v34, 16, v34
	v_lshrrev_b32_e32 v35, 16, v35
	v_lshrrev_b32_e32 v36, 16, v36
	v_lshrrev_b32_e32 v37, 16, v37
	v_and_or_b32 v25, v25, s56, v37
	v_and_or_b32 v24, v24, s56, v36
	v_and_or_b32 v23, v23, s56, v35
	v_and_or_b32 v22, v22, s56, v34
	global_store_dwordx4 v[32:33], v[22:25], off
	v_lshlrev_b32_e32 v35, 16, v7
	v_lshlrev_b32_e32 v34, 16, v6
	v_lshlrev_b32_e32 v23, 16, v15
	v_lshlrev_b32_e32 v22, 16, v14
	v_and_b32_e32 v15, 0xffff0000, v15
	v_and_b32_e32 v14, 0xffff0000, v14
	v_mov_b32_e32 v24, v18
	v_mov_b32_e32 v25, v20
	v_pk_mul_f32 v[14:15], v[0:1], v[14:15] op_sel_hi:[0,1]
	v_mov_b32_e32 v20, v19
	v_lshlrev_b32_e32 v19, 16, v17
	v_lshlrev_b32_e32 v18, 16, v16
	v_and_b32_e32 v17, 0xffff0000, v17
	v_and_b32_e32 v16, 0xffff0000, v16
	v_pk_mul_f32 v[14:15], v[20:21], v[14:15]
	v_mov_b32_e32 v21, v12
	v_pk_mul_f32 v[16:17], v[0:1], v[16:17] op_sel_hi:[0,1]
	v_mov_b32_e32 v12, v11
	v_pk_mul_f32 v[22:23], v[0:1], v[22:23] op_sel_hi:[0,1]
	v_pk_mul_f32 v[18:19], v[0:1], v[18:19] op_sel_hi:[0,1]
	v_mov_b32_e32 v20, v10
	v_pk_mul_f32 v[10:11], v[12:13], v[16:17]
	v_pk_mul_f32 v[22:23], v[24:25], v[22:23]
	v_pk_mul_f32 v[18:19], v[20:21], v[18:19]
	v_bfe_u32 v12, v11, 16, 1
	v_bfe_u32 v13, v10, 16, 1
	v_bfe_u32 v16, v15, 16, 1
	v_bfe_u32 v17, v14, 16, 1
	v_add3_u32 v14, v14, v17, s54
	v_add3_u32 v15, v15, v16, s54
	v_add3_u32 v10, v10, v13, s54
	v_add3_u32 v11, v11, v12, s54
	v_bfe_u32 v12, v22, 16, 1
	v_bfe_u32 v13, v23, 16, 1
	v_bfe_u32 v16, v18, 16, 1
	v_bfe_u32 v17, v19, 16, 1
	v_add3_u32 v17, v19, v17, s54
	v_add3_u32 v16, v18, v16, s54
	v_add3_u32 v13, v23, v13, s54
	v_add3_u32 v12, v22, v12, s54
	v_lshrrev_b32_e32 v18, 16, v12
	v_lshrrev_b32_e32 v19, 16, v13
	v_lshrrev_b32_e32 v12, 16, v16
	v_lshrrev_b32_e32 v13, 16, v17
	v_and_or_b32 v13, v11, s56, v13
	v_and_or_b32 v12, v10, s56, v12
	v_and_or_b32 v11, v15, s56, v19
	v_and_or_b32 v10, v14, s56, v18
	global_store_dwordx4 v[32:33], v[10:13], off offset:16
	global_load_dwordx4 v[10:13], v1, s[4:5] offset:880
	s_nop 0
	global_load_dwordx4 v[14:17], v1, s[4:5] offset:864
	global_load_dwordx4 v[18:21], v1, s[4:5] offset:848
	global_load_dwordx4 v[22:25], v1, s[4:5] offset:832
	v_and_b32_e32 v7, 0xffff0000, v7
	v_and_b32_e32 v6, 0xffff0000, v6
	v_pk_mul_f32 v[6:7], v[0:1], v[6:7] op_sel_hi:[0,1]
	v_pk_mul_f32 v[34:35], v[0:1], v[34:35] op_sel_hi:[0,1]
	s_waitcnt vmcnt(0)
	v_mov_b32_e32 v36, v22
	v_mov_b32_e32 v37, v24
	v_mov_b32_e32 v24, v23
	v_lshlrev_b32_e32 v23, 16, v9
	v_lshlrev_b32_e32 v22, 16, v8
	v_and_b32_e32 v9, 0xffff0000, v9
	v_and_b32_e32 v8, 0xffff0000, v8
	v_pk_mul_f32 v[6:7], v[24:25], v[6:7]
	v_mov_b32_e32 v25, v20
	v_pk_mul_f32 v[8:9], v[0:1], v[8:9] op_sel_hi:[0,1]
	v_mov_b32_e32 v20, v19
	v_pk_mul_f32 v[22:23], v[0:1], v[22:23] op_sel_hi:[0,1]
	v_mov_b32_e32 v24, v18
	v_pk_mul_f32 v[8:9], v[20:21], v[8:9]
	v_pk_mul_f32 v[34:35], v[36:37], v[34:35]
	v_pk_mul_f32 v[22:23], v[24:25], v[22:23]
	v_bfe_u32 v18, v9, 16, 1
	v_bfe_u32 v19, v8, 16, 1
	v_bfe_u32 v20, v7, 16, 1
	v_bfe_u32 v21, v6, 16, 1
	v_add3_u32 v6, v6, v21, s54
	v_add3_u32 v7, v7, v20, s54
	v_add3_u32 v8, v8, v19, s54
	v_add3_u32 v9, v9, v18, s54
	v_bfe_u32 v18, v34, 16, 1
	v_bfe_u32 v19, v35, 16, 1
	v_bfe_u32 v20, v22, 16, 1
	v_bfe_u32 v21, v23, 16, 1
	v_add3_u32 v21, v23, v21, s54
	v_add3_u32 v20, v22, v20, s54
	v_add3_u32 v19, v35, v19, s54
	v_add3_u32 v18, v34, v18, s54
	v_lshrrev_b32_e32 v18, 16, v18
	v_lshrrev_b32_e32 v19, 16, v19
	v_lshrrev_b32_e32 v20, 16, v20
	v_lshrrev_b32_e32 v21, 16, v21
	v_and_or_b32 v9, v9, s56, v21
	v_and_or_b32 v8, v8, s56, v20
	v_and_or_b32 v7, v7, s56, v19
	v_and_or_b32 v6, v6, s56, v18
	global_store_dwordx4 v[32:33], v[6:9], off offset:32
	s_nop 1
	v_lshlrev_b32_e32 v7, 16, v3
	v_lshlrev_b32_e32 v6, 16, v2
	v_and_b32_e32 v9, 0xffff0000, v3
	v_and_b32_e32 v8, 0xffff0000, v2
	v_pk_mul_f32 v[2:3], v[0:1], v[6:7] op_sel_hi:[0,1]
	v_mov_b32_e32 v6, v14
	v_mov_b32_e32 v7, v16
	v_pk_mul_f32 v[2:3], v[6:7], v[2:3]
	v_pk_mul_f32 v[6:7], v[0:1], v[8:9] op_sel_hi:[0,1]
	v_lshlrev_b32_e32 v9, 16, v5
	v_lshlrev_b32_e32 v8, 16, v4
	v_and_b32_e32 v5, 0xffff0000, v5
	v_and_b32_e32 v4, 0xffff0000, v4
	v_mov_b32_e32 v16, v15
	v_mov_b32_e32 v15, v12
	v_pk_mul_f32 v[4:5], v[0:1], v[4:5] op_sel_hi:[0,1]
	v_mov_b32_e32 v12, v11
	v_pk_mul_f32 v[6:7], v[16:17], v[6:7]
	v_pk_mul_f32 v[8:9], v[0:1], v[8:9] op_sel_hi:[0,1]
	v_mov_b32_e32 v14, v10
	v_pk_mul_f32 v[4:5], v[12:13], v[4:5]
	v_pk_mul_f32 v[8:9], v[14:15], v[8:9]
	v_bfe_u32 v10, v5, 16, 1
	v_bfe_u32 v11, v4, 16, 1
	v_bfe_u32 v12, v7, 16, 1
	v_bfe_u32 v13, v6, 16, 1
	v_add3_u32 v6, v6, v13, s54
	v_add3_u32 v7, v7, v12, s54
	v_add3_u32 v4, v4, v11, s54
	v_add3_u32 v5, v5, v10, s54
	v_bfe_u32 v10, v2, 16, 1
	v_bfe_u32 v11, v3, 16, 1
	v_bfe_u32 v12, v8, 16, 1
	v_bfe_u32 v13, v9, 16, 1
	v_add3_u32 v9, v9, v13, s54
	v_add3_u32 v8, v8, v12, s54
	v_add3_u32 v3, v3, v11, s54
	v_add3_u32 v2, v2, v10, s54
	v_lshrrev_b32_e32 v2, 16, v2
	v_lshrrev_b32_e32 v3, 16, v3
	v_lshrrev_b32_e32 v8, 16, v8
	v_lshrrev_b32_e32 v9, 16, v9
	v_and_or_b32 v5, v5, s56, v9
	v_and_or_b32 v4, v4, s56, v8
	v_and_or_b32 v3, v7, s56, v3
	v_and_or_b32 v2, v6, s56, v2
	global_store_dwordx4 v[32:33], v[2:5], off offset:48
	global_load_dwordx4 v[2:5], v[32:33], off offset:112
	s_nop 0
	global_load_dwordx4 v[6:9], v[32:33], off offset:96
	global_load_dwordx4 v[14:17], v[32:33], off offset:80
	global_load_dwordx4 v[22:25], v[32:33], off offset:64
	global_load_dwordx4 v[10:13], v1, s[4:5] offset:944
	global_load_dwordx4 v[18:21], v1, s[4:5] offset:928
	global_load_dwordx4 v[34:37], v1, s[4:5] offset:912
	global_load_dwordx4 v[38:41], v1, s[4:5] offset:896
	s_waitcnt vmcnt(0)
; template <int D, int ROT0, int HALF, bool GAIN, bool KEEP = true>
; DI void chunk_nr(u16* p, const float* __restrict__ gain, const float* __restrict__ tab) {
;     ...
;     } else if (GAIN) {
;       f32x8 x1 = bf8_to_f32(RAWV(v));
;       const f32x8 g1 = *(const f32x8*)(gain + v * 8);
; #pragma unroll
;       for (int e = 0; e < 8; ++e) x1[e] = x1[e] * rstd * g1[e];
;       *(u32x4*)(p + v * 8) = f32_to_bf8(x1);
;     }
	v_lshlrev_b32_e32 v43, 16, v23
	v_lshlrev_b32_e32 v42, 16, v22
	v_and_b32_e32 v23, 0xffff0000, v23
	v_and_b32_e32 v22, 0xffff0000, v22
	v_mov_b32_e32 v44, v38
	v_mov_b32_e32 v45, v40
	v_pk_mul_f32 v[22:23], v[0:1], v[22:23] op_sel_hi:[0,1]
	v_mov_b32_e32 v40, v39
	v_lshlrev_b32_e32 v39, 16, v25
	v_lshlrev_b32_e32 v38, 16, v24
	v_and_b32_e32 v25, 0xffff0000, v25
	v_and_b32_e32 v24, 0xffff0000, v24
	v_pk_mul_f32 v[22:23], v[40:41], v[22:23]
	v_mov_b32_e32 v41, v36
	v_pk_mul_f32 v[24:25], v[0:1], v[24:25] op_sel_hi:[0,1]
	v_mov_b32_e32 v36, v35
	v_pk_mul_f32 v[42:43], v[0:1], v[42:43] op_sel_hi:[0,1]
	v_pk_mul_f32 v[38:39], v[0:1], v[38:39] op_sel_hi:[0,1]
	v_mov_b32_e32 v40, v34
	v_pk_mul_f32 v[24:25], v[36:37], v[24:25]
	v_pk_mul_f32 v[42:43], v[44:45], v[42:43]
	v_pk_mul_f32 v[38:39], v[40:41], v[38:39]
	v_bfe_u32 v34, v25, 16, 1
	v_bfe_u32 v35, v24, 16, 1
	v_bfe_u32 v36, v23, 16, 1
	v_bfe_u32 v37, v22, 16, 1
	v_add3_u32 v22, v22, v37, s54
	v_add3_u32 v23, v23, v36, s54
	v_add3_u32 v24, v24, v35, s54
	v_add3_u32 v25, v25, v34, s54
	v_bfe_u32 v34, v42, 16, 1
	v_bfe_u32 v35, v43, 16, 1
	v_bfe_u32 v36, v38, 16, 1
	v_bfe_u32 v37, v39, 16, 1
	v_add3_u32 v37, v39, v37, s54
	v_add3_u32 v36, v38, v36, s54
	v_add3_u32 v35, v43, v35, s54
	v_add3_u32 v34, v42, v34, s54
	v_lshrrev_b32_e32 v34, 16, v34
	v_lshrrev_b32_e32 v35, 16, v35
	v_lshrrev_b32_e32 v36, 16, v36
	v_lshrrev_b32_e32 v37, 16, v37
	v_and_or_b32 v25, v25, s56, v37
	v_and_or_b32 v24, v24, s56, v36
	v_and_or_b32 v23, v23, s56, v35
	v_and_or_b32 v22, v22, s56, v34
	global_store_dwordx4 v[32:33], v[22:25], off offset:64
	v_lshlrev_b32_e32 v35, 16, v7
	v_lshlrev_b32_e32 v34, 16, v6
	v_lshlrev_b32_e32 v23, 16, v15
	v_lshlrev_b32_e32 v22, 16, v14
	v_and_b32_e32 v25, 0xffff0000, v15
	v_and_b32_e32 v24, 0xffff0000, v14
	v_pk_mul_f32 v[14:15], v[0:1], v[22:23] op_sel_hi:[0,1]
	v_mov_b32_e32 v22, v18
	v_mov_b32_e32 v23, v20
	v_pk_mul_f32 v[14:15], v[22:23], v[14:15]
	v_pk_mul_f32 v[22:23], v[0:1], v[24:25] op_sel_hi:[0,1]
	v_mov_b32_e32 v20, v19
	v_pk_mul_f32 v[18:19], v[20:21], v[22:23]
	v_lshlrev_b32_e32 v21, 16, v17
	v_lshlrev_b32_e32 v20, 16, v16
	v_and_b32_e32 v17, 0xffff0000, v17
	v_and_b32_e32 v16, 0xffff0000, v16
	v_mov_b32_e32 v23, v12
	v_pk_mul_f32 v[16:17], v[0:1], v[16:17] op_sel_hi:[0,1]
	v_mov_b32_e32 v12, v11
	v_pk_mul_f32 v[20:21], v[0:1], v[20:21] op_sel_hi:[0,1]
	v_mov_b32_e32 v22, v10
	v_pk_mul_f32 v[10:11], v[12:13], v[16:17]
	v_pk_mul_f32 v[20:21], v[22:23], v[20:21]
	v_bfe_u32 v12, v11, 16, 1
	v_bfe_u32 v13, v10, 16, 1
	v_bfe_u32 v16, v19, 16, 1
	v_bfe_u32 v17, v18, 16, 1
	v_add3_u32 v17, v18, v17, s54
	v_add3_u32 v16, v19, v16, s54
	v_add3_u32 v10, v10, v13, s54
	v_add3_u32 v11, v11, v12, s54
	v_bfe_u32 v12, v14, 16, 1
	v_bfe_u32 v13, v15, 16, 1
	v_bfe_u32 v18, v20, 16, 1
	v_bfe_u32 v19, v21, 16, 1
	v_add3_u32 v19, v21, v19, s54
	v_add3_u32 v18, v20, v18, s54
	v_add3_u32 v13, v15, v13, s54
	v_add3_u32 v12, v14, v12, s54
	v_lshrrev_b32_e32 v14, 16, v12
	v_lshrrev_b32_e32 v15, 16, v13
	v_lshrrev_b32_e32 v12, 16, v18
	v_lshrrev_b32_e32 v13, 16, v19
	v_and_or_b32 v13, v11, s56, v13
	v_and_or_b32 v12, v10, s56, v12
	v_and_or_b32 v11, v16, s56, v15
	v_and_or_b32 v10, v17, s56, v14
	global_store_dwordx4 v[32:33], v[10:13], off offset:80
	global_load_dwordx4 v[10:13], v1, s[4:5] offset:1008
	s_nop 0
	global_load_dwordx4 v[14:17], v1, s[4:5] offset:992
	global_load_dwordx4 v[18:21], v1, s[4:5] offset:976
	global_load_dwordx4 v[22:25], v1, s[4:5] offset:960
	v_and_b32_e32 v7, 0xffff0000, v7
	v_and_b32_e32 v6, 0xffff0000, v6
	v_pk_mul_f32 v[6:7], v[0:1], v[6:7] op_sel_hi:[0,1]
	v_pk_mul_f32 v[34:35], v[0:1], v[34:35] op_sel_hi:[0,1]
	s_waitcnt vmcnt(0)
	v_mov_b32_e32 v36, v22
	v_mov_b32_e32 v37, v24
	v_mov_b32_e32 v24, v23
	v_lshlrev_b32_e32 v23, 16, v9
	v_lshlrev_b32_e32 v22, 16, v8
	v_and_b32_e32 v9, 0xffff0000, v9
	v_and_b32_e32 v8, 0xffff0000, v8
	v_pk_mul_f32 v[6:7], v[24:25], v[6:7]
	v_mov_b32_e32 v25, v20
	v_pk_mul_f32 v[8:9], v[0:1], v[8:9] op_sel_hi:[0,1]
	v_mov_b32_e32 v20, v19
	v_pk_mul_f32 v[22:23], v[0:1], v[22:23] op_sel_hi:[0,1]
	v_mov_b32_e32 v24, v18
	v_pk_mul_f32 v[8:9], v[20:21], v[8:9]
	v_pk_mul_f32 v[34:35], v[36:37], v[34:35]
	v_pk_mul_f32 v[22:23], v[24:25], v[22:23]
	v_bfe_u32 v18, v9, 16, 1
	v_bfe_u32 v19, v8, 16, 1
	v_bfe_u32 v20, v7, 16, 1
	v_bfe_u32 v21, v6, 16, 1
	v_add3_u32 v6, v6, v21, s54
	v_add3_u32 v7, v7, v20, s54
	v_add3_u32 v8, v8, v19, s54
	v_add3_u32 v9, v9, v18, s54
	v_bfe_u32 v18, v34, 16, 1
	v_bfe_u32 v19, v35, 16, 1
	v_bfe_u32 v20, v22, 16, 1
	v_bfe_u32 v21, v23, 16, 1
	v_add3_u32 v21, v23, v21, s54
	v_add3_u32 v20, v22, v20, s54
	v_add3_u32 v19, v35, v19, s54
	v_add3_u32 v18, v34, v18, s54
	v_lshrrev_b32_e32 v18, 16, v18
	v_lshrrev_b32_e32 v19, 16, v19
	v_lshrrev_b32_e32 v20, 16, v20
	v_lshrrev_b32_e32 v21, 16, v21
	v_and_or_b32 v9, v9, s56, v21
	v_and_or_b32 v8, v8, s56, v20
	v_and_or_b32 v7, v7, s56, v19
	v_and_or_b32 v6, v6, s56, v18
	global_store_dwordx4 v[32:33], v[6:9], off offset:96
	s_nop 1
	v_lshlrev_b32_e32 v7, 16, v3
	v_lshlrev_b32_e32 v6, 16, v2
	v_and_b32_e32 v9, 0xffff0000, v3
	v_and_b32_e32 v8, 0xffff0000, v2
	v_pk_mul_f32 v[2:3], v[0:1], v[6:7] op_sel_hi:[0,1]
	v_mov_b32_e32 v6, v14
	v_mov_b32_e32 v7, v16
	v_pk_mul_f32 v[2:3], v[6:7], v[2:3]
	v_pk_mul_f32 v[6:7], v[0:1], v[8:9] op_sel_hi:[0,1]
	v_lshlrev_b32_e32 v9, 16, v5
	v_lshlrev_b32_e32 v8, 16, v4
	v_and_b32_e32 v5, 0xffff0000, v5
	v_and_b32_e32 v4, 0xffff0000, v4
	v_mov_b32_e32 v16, v15
	v_mov_b32_e32 v15, v12
	v_pk_mul_f32 v[4:5], v[0:1], v[4:5] op_sel_hi:[0,1]
	v_mov_b32_e32 v12, v11
	v_pk_mul_f32 v[6:7], v[16:17], v[6:7]
	v_pk_mul_f32 v[8:9], v[0:1], v[8:9] op_sel_hi:[0,1]
	v_mov_b32_e32 v14, v10
	v_pk_mul_f32 v[4:5], v[12:13], v[4:5]
	v_pk_mul_f32 v[8:9], v[14:15], v[8:9]
	v_bfe_u32 v10, v5, 16, 1
	v_bfe_u32 v11, v4, 16, 1
	v_bfe_u32 v12, v7, 16, 1
	v_bfe_u32 v13, v6, 16, 1
	v_add3_u32 v6, v6, v13, s54
	v_add3_u32 v7, v7, v12, s54
	v_add3_u32 v4, v4, v11, s54
	v_add3_u32 v5, v5, v10, s54
	v_bfe_u32 v10, v2, 16, 1
	v_bfe_u32 v11, v3, 16, 1
	v_bfe_u32 v12, v8, 16, 1
	v_bfe_u32 v13, v9, 16, 1
	v_add3_u32 v9, v9, v13, s54
	v_add3_u32 v8, v8, v12, s54
	v_add3_u32 v3, v3, v11, s54
	v_add3_u32 v2, v2, v10, s54
	v_lshrrev_b32_e32 v2, 16, v2
	v_lshrrev_b32_e32 v3, 16, v3
	v_lshrrev_b32_e32 v8, 16, v8
	v_lshrrev_b32_e32 v9, 16, v9
	v_and_or_b32 v5, v5, s56, v9
	v_and_or_b32 v4, v4, s56, v8
	v_and_or_b32 v3, v7, s56, v3
	v_and_or_b32 v2, v6, s56, v2
	global_store_dwordx4 v[32:33], v[2:5], off offset:112
	global_load_dwordx4 v[2:5], v[32:33], off offset:176
	s_nop 0
	global_load_dwordx4 v[6:9], v[32:33], off offset:160
	global_load_dwordx4 v[14:17], v[32:33], off offset:144
	global_load_dwordx4 v[22:25], v[32:33], off offset:128
	global_load_dwordx4 v[10:13], v1, s[4:5] offset:1072
	global_load_dwordx4 v[18:21], v1, s[4:5] offset:1056
	global_load_dwordx4 v[34:37], v1, s[4:5] offset:1040
	global_load_dwordx4 v[38:41], v1, s[4:5] offset:1024
	s_waitcnt vmcnt(0)
; template <int D, int ROT0, int HALF, bool GAIN, bool KEEP = true>
; DI void chunk_nr(u16* p, const float* __restrict__ gain, const float* __restrict__ tab) {
;     ...
;     } else if (GAIN) {
;       f32x8 x1 = bf8_to_f32(RAWV(v));
;       const f32x8 g1 = *(const f32x8*)(gain + v * 8);
; #pragma unroll
;       for (int e = 0; e < 8; ++e) x1[e] = x1[e] * rstd * g1[e];
;       *(u32x4*)(p + v * 8) = f32_to_bf8(x1);
;     }
	v_lshlrev_b32_e32 v43, 16, v23
	v_lshlrev_b32_e32 v42, 16, v22
	v_and_b32_e32 v23, 0xffff0000, v23
	v_and_b32_e32 v22, 0xffff0000, v22
	v_mov_b32_e32 v44, v38
	v_mov_b32_e32 v45, v40
	v_pk_mul_f32 v[22:23], v[0:1], v[22:23] op_sel_hi:[0,1]
	v_mov_b32_e32 v40, v39
	v_lshlrev_b32_e32 v39, 16, v25
	v_lshlrev_b32_e32 v38, 16, v24
	v_and_b32_e32 v25, 0xffff0000, v25
	v_and_b32_e32 v24, 0xffff0000, v24
	v_pk_mul_f32 v[22:23], v[40:41], v[22:23]
	v_mov_b32_e32 v41, v36
	v_pk_mul_f32 v[24:25], v[0:1], v[24:25] op_sel_hi:[0,1]
	v_mov_b32_e32 v36, v35
	v_pk_mul_f32 v[42:43], v[0:1], v[42:43] op_sel_hi:[0,1]
	v_pk_mul_f32 v[38:39], v[0:1], v[38:39] op_sel_hi:[0,1]
	v_mov_b32_e32 v40, v34
	v_pk_mul_f32 v[24:25], v[36:37], v[24:25]
	v_pk_mul_f32 v[42:43], v[44:45], v[42:43]
	v_pk_mul_f32 v[38:39], v[40:41], v[38:39]
	v_bfe_u32 v34, v25, 16, 1
	v_bfe_u32 v35, v24, 16, 1
	v_bfe_u32 v36, v23, 16, 1
	v_bfe_u32 v37, v22, 16, 1
	v_add3_u32 v22, v22, v37, s54
	v_add3_u32 v23, v23, v36, s54
	v_add3_u32 v24, v24, v35, s54
	v_add3_u32 v25, v25, v34, s54
	v_bfe_u32 v34, v42, 16, 1
	v_bfe_u32 v35, v43, 16, 1
	v_bfe_u32 v36, v38, 16, 1
	v_bfe_u32 v37, v39, 16, 1
	v_add3_u32 v37, v39, v37, s54
	v_add3_u32 v36, v38, v36, s54
	v_add3_u32 v35, v43, v35, s54
	v_add3_u32 v34, v42, v34, s54
	v_lshrrev_b32_e32 v34, 16, v34
	v_lshrrev_b32_e32 v35, 16, v35
	v_lshrrev_b32_e32 v36, 16, v36
	v_lshrrev_b32_e32 v37, 16, v37
	v_and_or_b32 v25, v25, s56, v37
	v_and_or_b32 v24, v24, s56, v36
	v_and_or_b32 v23, v23, s56, v35
	v_and_or_b32 v22, v22, s56, v34
	global_store_dwordx4 v[32:33], v[22:25], off offset:128
	v_lshlrev_b32_e32 v35, 16, v7
	v_lshlrev_b32_e32 v34, 16, v6
	v_lshlrev_b32_e32 v23, 16, v15
	v_lshlrev_b32_e32 v22, 16, v14
	v_and_b32_e32 v25, 0xffff0000, v15
	v_and_b32_e32 v24, 0xffff0000, v14
	v_pk_mul_f32 v[14:15], v[0:1], v[22:23] op_sel_hi:[0,1]
	v_mov_b32_e32 v22, v18
	v_mov_b32_e32 v23, v20
	v_pk_mul_f32 v[14:15], v[22:23], v[14:15]
	v_pk_mul_f32 v[22:23], v[0:1], v[24:25] op_sel_hi:[0,1]
	v_mov_b32_e32 v20, v19
	v_pk_mul_f32 v[18:19], v[20:21], v[22:23]
	v_lshlrev_b32_e32 v21, 16, v17
	v_lshlrev_b32_e32 v20, 16, v16
	v_and_b32_e32 v17, 0xffff0000, v17
	v_and_b32_e32 v16, 0xffff0000, v16
	v_mov_b32_e32 v23, v12
	v_pk_mul_f32 v[16:17], v[0:1], v[16:17] op_sel_hi:[0,1]
	v_mov_b32_e32 v12, v11
	v_pk_mul_f32 v[20:21], v[0:1], v[20:21] op_sel_hi:[0,1]
	v_mov_b32_e32 v22, v10
	v_pk_mul_f32 v[10:11], v[12:13], v[16:17]
	v_pk_mul_f32 v[20:21], v[22:23], v[20:21]
	v_bfe_u32 v12, v11, 16, 1
	v_bfe_u32 v13, v10, 16, 1
	v_bfe_u32 v16, v19, 16, 1
	v_bfe_u32 v17, v18, 16, 1
	v_add3_u32 v17, v18, v17, s54
	v_add3_u32 v16, v19, v16, s54
	v_add3_u32 v10, v10, v13, s54
	v_add3_u32 v11, v11, v12, s54
	v_bfe_u32 v12, v14, 16, 1
	v_bfe_u32 v13, v15, 16, 1
	v_bfe_u32 v18, v20, 16, 1
	v_bfe_u32 v19, v21, 16, 1
	v_add3_u32 v19, v21, v19, s54
	v_add3_u32 v18, v20, v18, s54
	v_add3_u32 v13, v15, v13, s54
	v_add3_u32 v12, v14, v12, s54
	v_lshrrev_b32_e32 v14, 16, v12
	v_lshrrev_b32_e32 v15, 16, v13
	v_lshrrev_b32_e32 v12, 16, v18
	v_lshrrev_b32_e32 v13, 16, v19
	v_and_or_b32 v13, v11, s56, v13
	v_and_or_b32 v12, v10, s56, v12
	v_and_or_b32 v11, v16, s56, v15
	v_and_or_b32 v10, v17, s56, v14
	global_store_dwordx4 v[32:33], v[10:13], off offset:144
	global_load_dwordx4 v[10:13], v1, s[4:5] offset:1136
	s_nop 0
	global_load_dwordx4 v[14:17], v1, s[4:5] offset:1120
	global_load_dwordx4 v[18:21], v1, s[4:5] offset:1104
	global_load_dwordx4 v[22:25], v1, s[4:5] offset:1088
	v_and_b32_e32 v7, 0xffff0000, v7
	v_and_b32_e32 v6, 0xffff0000, v6
	v_pk_mul_f32 v[6:7], v[0:1], v[6:7] op_sel_hi:[0,1]
	v_pk_mul_f32 v[34:35], v[0:1], v[34:35] op_sel_hi:[0,1]
	s_waitcnt vmcnt(0)
	v_mov_b32_e32 v36, v22
	v_mov_b32_e32 v37, v24
	v_mov_b32_e32 v24, v23
	v_lshlrev_b32_e32 v23, 16, v9
	v_lshlrev_b32_e32 v22, 16, v8
	v_and_b32_e32 v9, 0xffff0000, v9
	v_and_b32_e32 v8, 0xffff0000, v8
	v_pk_mul_f32 v[6:7], v[24:25], v[6:7]
	v_mov_b32_e32 v25, v20
	v_pk_mul_f32 v[8:9], v[0:1], v[8:9] op_sel_hi:[0,1]
	v_mov_b32_e32 v20, v19
	v_pk_mul_f32 v[22:23], v[0:1], v[22:23] op_sel_hi:[0,1]
	v_mov_b32_e32 v24, v18
	v_pk_mul_f32 v[8:9], v[20:21], v[8:9]
	v_pk_mul_f32 v[34:35], v[36:37], v[34:35]
	v_pk_mul_f32 v[22:23], v[24:25], v[22:23]
	v_bfe_u32 v18, v9, 16, 1
	v_bfe_u32 v19, v8, 16, 1
	v_bfe_u32 v20, v7, 16, 1
	v_bfe_u32 v21, v6, 16, 1
	v_add3_u32 v6, v6, v21, s54
	v_add3_u32 v7, v7, v20, s54
	v_add3_u32 v8, v8, v19, s54
	v_add3_u32 v9, v9, v18, s54
	v_bfe_u32 v18, v34, 16, 1
	v_bfe_u32 v19, v35, 16, 1
	v_bfe_u32 v20, v22, 16, 1
	v_bfe_u32 v21, v23, 16, 1
	v_add3_u32 v21, v23, v21, s54
	v_add3_u32 v20, v22, v20, s54
	v_add3_u32 v19, v35, v19, s54
	v_add3_u32 v18, v34, v18, s54
	v_lshrrev_b32_e32 v18, 16, v18
	v_lshrrev_b32_e32 v19, 16, v19
	v_lshrrev_b32_e32 v20, 16, v20
	v_lshrrev_b32_e32 v21, 16, v21
	v_and_or_b32 v9, v9, s56, v21
	v_and_or_b32 v8, v8, s56, v20
	v_and_or_b32 v7, v7, s56, v19
	v_and_or_b32 v6, v6, s56, v18
	global_store_dwordx4 v[32:33], v[6:9], off offset:160
	s_nop 1
	v_lshlrev_b32_e32 v7, 16, v3
	v_lshlrev_b32_e32 v6, 16, v2
	v_and_b32_e32 v9, 0xffff0000, v3
	v_and_b32_e32 v8, 0xffff0000, v2
	v_pk_mul_f32 v[2:3], v[0:1], v[6:7] op_sel_hi:[0,1]
	v_mov_b32_e32 v6, v14
	v_mov_b32_e32 v7, v16
	v_pk_mul_f32 v[2:3], v[6:7], v[2:3]
	v_pk_mul_f32 v[6:7], v[0:1], v[8:9] op_sel_hi:[0,1]
	v_lshlrev_b32_e32 v9, 16, v5
	v_lshlrev_b32_e32 v8, 16, v4
	v_and_b32_e32 v5, 0xffff0000, v5
	v_and_b32_e32 v4, 0xffff0000, v4
	v_mov_b32_e32 v16, v15
	v_mov_b32_e32 v15, v12
	v_pk_mul_f32 v[4:5], v[0:1], v[4:5] op_sel_hi:[0,1]
	v_mov_b32_e32 v12, v11
	v_pk_mul_f32 v[6:7], v[16:17], v[6:7]
	v_pk_mul_f32 v[8:9], v[0:1], v[8:9] op_sel_hi:[0,1]
	v_mov_b32_e32 v14, v10
	v_pk_mul_f32 v[4:5], v[12:13], v[4:5]
	v_pk_mul_f32 v[8:9], v[14:15], v[8:9]
	v_bfe_u32 v10, v5, 16, 1
	v_bfe_u32 v11, v4, 16, 1
	v_bfe_u32 v12, v7, 16, 1
	v_bfe_u32 v13, v6, 16, 1
	v_add3_u32 v6, v6, v13, s54
	v_add3_u32 v7, v7, v12, s54
	v_add3_u32 v4, v4, v11, s54
	v_add3_u32 v5, v5, v10, s54
	v_bfe_u32 v10, v2, 16, 1
	v_bfe_u32 v11, v3, 16, 1
	v_bfe_u32 v12, v8, 16, 1
	v_bfe_u32 v13, v9, 16, 1
	v_add3_u32 v9, v9, v13, s54
	v_add3_u32 v8, v8, v12, s54
	v_add3_u32 v3, v3, v11, s54
	v_add3_u32 v2, v2, v10, s54
	v_lshrrev_b32_e32 v2, 16, v2
	v_lshrrev_b32_e32 v3, 16, v3
	v_lshrrev_b32_e32 v8, 16, v8
	v_lshrrev_b32_e32 v9, 16, v9
	v_and_or_b32 v5, v5, s56, v9
	v_and_or_b32 v4, v4, s56, v8
	v_and_or_b32 v3, v7, s56, v3
	v_and_or_b32 v2, v6, s56, v2
	global_store_dwordx4 v[32:33], v[2:5], off offset:176
	global_load_dwordx4 v[2:5], v[32:33], off offset:240
	s_nop 0
	global_load_dwordx4 v[6:9], v[32:33], off offset:224
	global_load_dwordx4 v[14:17], v[32:33], off offset:208
	global_load_dwordx4 v[22:25], v[32:33], off offset:192
	global_load_dwordx4 v[10:13], v1, s[4:5] offset:1200
	global_load_dwordx4 v[18:21], v1, s[4:5] offset:1184
	global_load_dwordx4 v[34:37], v1, s[4:5] offset:1168
	global_load_dwordx4 v[38:41], v1, s[4:5] offset:1152
	s_waitcnt vmcnt(0)
; template <int D, int ROT0, int HALF, bool GAIN, bool KEEP = true>
; DI void chunk_nr(u16* p, const float* __restrict__ gain, const float* __restrict__ tab) {
;     ...
;     } else if (GAIN) {
;       f32x8 x1 = bf8_to_f32(RAWV(v));
;       const f32x8 g1 = *(const f32x8*)(gain + v * 8);
; #pragma unroll
;       for (int e = 0; e < 8; ++e) x1[e] = x1[e] * rstd * g1[e];
;       *(u32x4*)(p + v * 8) = f32_to_bf8(x1);
;     }
	v_lshlrev_b32_e32 v43, 16, v23
	v_lshlrev_b32_e32 v42, 16, v22
	v_and_b32_e32 v23, 0xffff0000, v23
	v_and_b32_e32 v22, 0xffff0000, v22
	v_mov_b32_e32 v44, v38
	v_mov_b32_e32 v45, v40
	v_pk_mul_f32 v[22:23], v[0:1], v[22:23] op_sel_hi:[0,1]
	v_mov_b32_e32 v40, v39
	v_lshlrev_b32_e32 v39, 16, v25
	v_lshlrev_b32_e32 v38, 16, v24
	v_and_b32_e32 v25, 0xffff0000, v25
	v_and_b32_e32 v24, 0xffff0000, v24
	v_pk_mul_f32 v[22:23], v[40:41], v[22:23]
	v_mov_b32_e32 v41, v36
	v_pk_mul_f32 v[24:25], v[0:1], v[24:25] op_sel_hi:[0,1]
	v_mov_b32_e32 v36, v35
	v_pk_mul_f32 v[42:43], v[0:1], v[42:43] op_sel_hi:[0,1]
	v_pk_mul_f32 v[38:39], v[0:1], v[38:39] op_sel_hi:[0,1]
	v_mov_b32_e32 v40, v34
	v_pk_mul_f32 v[24:25], v[36:37], v[24:25]
	v_pk_mul_f32 v[42:43], v[44:45], v[42:43]
	v_pk_mul_f32 v[38:39], v[40:41], v[38:39]
	v_bfe_u32 v34, v25, 16, 1
	v_bfe_u32 v35, v24, 16, 1
	v_bfe_u32 v36, v23, 16, 1
	v_bfe_u32 v37, v22, 16, 1
	v_add3_u32 v22, v22, v37, s54
	v_add3_u32 v23, v23, v36, s54
	v_add3_u32 v24, v24, v35, s54
	v_add3_u32 v25, v25, v34, s54
	v_bfe_u32 v34, v42, 16, 1
	v_bfe_u32 v35, v43, 16, 1
	v_bfe_u32 v36, v38, 16, 1
	v_bfe_u32 v37, v39, 16, 1
	v_add3_u32 v37, v39, v37, s54
	v_add3_u32 v36, v38, v36, s54
	v_add3_u32 v35, v43, v35, s54
	v_add3_u32 v34, v42, v34, s54
	v_lshrrev_b32_e32 v34, 16, v34
	v_lshrrev_b32_e32 v35, 16, v35
	v_lshrrev_b32_e32 v36, 16, v36
	v_lshrrev_b32_e32 v37, 16, v37
	v_and_or_b32 v25, v25, s56, v37
	v_and_or_b32 v24, v24, s56, v36
	v_and_or_b32 v23, v23, s56, v35
	v_and_or_b32 v22, v22, s56, v34
	global_store_dwordx4 v[32:33], v[22:25], off offset:192
	v_lshlrev_b32_e32 v35, 16, v7
	v_lshlrev_b32_e32 v34, 16, v6
	v_lshlrev_b32_e32 v23, 16, v15
	v_lshlrev_b32_e32 v22, 16, v14
	v_and_b32_e32 v25, 0xffff0000, v15
	v_and_b32_e32 v24, 0xffff0000, v14
	v_pk_mul_f32 v[14:15], v[0:1], v[22:23] op_sel_hi:[0,1]
	v_mov_b32_e32 v22, v18
	v_mov_b32_e32 v23, v20
	v_pk_mul_f32 v[14:15], v[22:23], v[14:15]
	v_pk_mul_f32 v[22:23], v[0:1], v[24:25] op_sel_hi:[0,1]
	v_mov_b32_e32 v20, v19
	v_pk_mul_f32 v[18:19], v[20:21], v[22:23]
	v_lshlrev_b32_e32 v21, 16, v17
	v_lshlrev_b32_e32 v20, 16, v16
	v_and_b32_e32 v17, 0xffff0000, v17
	v_and_b32_e32 v16, 0xffff0000, v16
	v_mov_b32_e32 v23, v12
	v_pk_mul_f32 v[16:17], v[0:1], v[16:17] op_sel_hi:[0,1]
	v_mov_b32_e32 v12, v11
	v_pk_mul_f32 v[20:21], v[0:1], v[20:21] op_sel_hi:[0,1]
	v_mov_b32_e32 v22, v10
	v_pk_mul_f32 v[10:11], v[12:13], v[16:17]
	v_pk_mul_f32 v[20:21], v[22:23], v[20:21]
	v_bfe_u32 v12, v11, 16, 1
	v_bfe_u32 v13, v10, 16, 1
	v_bfe_u32 v16, v19, 16, 1
	v_bfe_u32 v17, v18, 16, 1
	v_add3_u32 v17, v18, v17, s54
	v_add3_u32 v16, v19, v16, s54
	v_add3_u32 v10, v10, v13, s54
	v_add3_u32 v11, v11, v12, s54
	v_bfe_u32 v12, v14, 16, 1
	v_bfe_u32 v13, v15, 16, 1
	v_bfe_u32 v18, v20, 16, 1
	v_bfe_u32 v19, v21, 16, 1
	v_add3_u32 v19, v21, v19, s54
	v_add3_u32 v18, v20, v18, s54
	v_add3_u32 v13, v15, v13, s54
	v_add3_u32 v12, v14, v12, s54
	v_lshrrev_b32_e32 v14, 16, v12
	v_lshrrev_b32_e32 v15, 16, v13
	v_lshrrev_b32_e32 v12, 16, v18
	v_lshrrev_b32_e32 v13, 16, v19
	v_and_or_b32 v13, v11, s56, v13
	v_and_or_b32 v12, v10, s56, v12
	v_and_or_b32 v11, v16, s56, v15
	v_and_or_b32 v10, v17, s56, v14
	global_store_dwordx4 v[32:33], v[10:13], off offset:208
	global_load_dwordx4 v[10:13], v1, s[4:5] offset:1264
	s_nop 0
	global_load_dwordx4 v[14:17], v1, s[4:5] offset:1248
	global_load_dwordx4 v[18:21], v1, s[4:5] offset:1232
	global_load_dwordx4 v[22:25], v1, s[4:5] offset:1216
	v_and_b32_e32 v7, 0xffff0000, v7
	v_and_b32_e32 v6, 0xffff0000, v6
	v_pk_mul_f32 v[6:7], v[0:1], v[6:7] op_sel_hi:[0,1]
	v_pk_mul_f32 v[34:35], v[0:1], v[34:35] op_sel_hi:[0,1]
	s_waitcnt vmcnt(0)
	v_mov_b32_e32 v36, v22
	v_mov_b32_e32 v37, v24
	v_mov_b32_e32 v24, v23
	v_lshlrev_b32_e32 v23, 16, v9
	v_lshlrev_b32_e32 v22, 16, v8
	v_and_b32_e32 v9, 0xffff0000, v9
	v_and_b32_e32 v8, 0xffff0000, v8
	v_pk_mul_f32 v[6:7], v[24:25], v[6:7]
	v_mov_b32_e32 v25, v20
	v_pk_mul_f32 v[8:9], v[0:1], v[8:9] op_sel_hi:[0,1]
	v_mov_b32_e32 v20, v19
	v_pk_mul_f32 v[22:23], v[0:1], v[22:23] op_sel_hi:[0,1]
	v_mov_b32_e32 v24, v18
	v_pk_mul_f32 v[8:9], v[20:21], v[8:9]
	v_pk_mul_f32 v[34:35], v[36:37], v[34:35]
	v_pk_mul_f32 v[22:23], v[24:25], v[22:23]
	v_bfe_u32 v18, v9, 16, 1
	v_bfe_u32 v19, v8, 16, 1
	v_bfe_u32 v20, v7, 16, 1
	v_bfe_u32 v21, v6, 16, 1
	v_add3_u32 v6, v6, v21, s54
	v_add3_u32 v7, v7, v20, s54
	v_add3_u32 v8, v8, v19, s54
	v_add3_u32 v9, v9, v18, s54
	v_bfe_u32 v18, v34, 16, 1
	v_bfe_u32 v19, v35, 16, 1
	v_bfe_u32 v20, v22, 16, 1
	v_bfe_u32 v21, v23, 16, 1
	v_add3_u32 v21, v23, v21, s54
	v_add3_u32 v20, v22, v20, s54
	v_add3_u32 v19, v35, v19, s54
	v_add3_u32 v18, v34, v18, s54
	v_lshrrev_b32_e32 v18, 16, v18
	v_lshrrev_b32_e32 v19, 16, v19
	v_lshrrev_b32_e32 v20, 16, v20
	v_lshrrev_b32_e32 v21, 16, v21
	v_and_or_b32 v9, v9, s56, v21
	v_and_or_b32 v8, v8, s56, v20
	v_and_or_b32 v7, v7, s56, v19
	v_and_or_b32 v6, v6, s56, v18
	global_store_dwordx4 v[32:33], v[6:9], off offset:224
	s_nop 1
	v_lshlrev_b32_e32 v7, 16, v3
	v_lshlrev_b32_e32 v6, 16, v2
	v_and_b32_e32 v9, 0xffff0000, v3
	v_and_b32_e32 v8, 0xffff0000, v2
	v_pk_mul_f32 v[2:3], v[0:1], v[6:7] op_sel_hi:[0,1]
	v_mov_b32_e32 v6, v14
	v_mov_b32_e32 v7, v16
	v_pk_mul_f32 v[2:3], v[6:7], v[2:3]
	v_pk_mul_f32 v[6:7], v[0:1], v[8:9] op_sel_hi:[0,1]
	v_lshlrev_b32_e32 v9, 16, v5
	v_lshlrev_b32_e32 v8, 16, v4
	v_and_b32_e32 v5, 0xffff0000, v5
	v_and_b32_e32 v4, 0xffff0000, v4
	v_mov_b32_e32 v16, v15
	v_mov_b32_e32 v15, v12
	v_pk_mul_f32 v[4:5], v[0:1], v[4:5] op_sel_hi:[0,1]
	v_mov_b32_e32 v12, v11
	v_pk_mul_f32 v[6:7], v[16:17], v[6:7]
	v_pk_mul_f32 v[8:9], v[0:1], v[8:9] op_sel_hi:[0,1]
; template <int D, int ROT0, int HALF, bool GAIN, bool KEEP = true>
; DI void chunk_nr(u16* p, const float* __restrict__ gain, const float* __restrict__ tab) {
;     ...
;     if (v >= V0 && v < V0 + 2 * NRV) {
;       if (v >= V0 + NRV) continue;
;       const f32x8 x1 = bf8_to_f32(RAWV(v));
;       const f32x8 x2 = bf8_to_f32(RAWV(v + NRV));
;       f32x8 g1, g2;
;       if (GAIN) { g1 = *(const f32x8*)(gain + v * 8); g2 = *(const f32x8*)(gain + (v + NRV) * 8); }
;       const f32x8 t0 = *(const f32x8*)(tab + 2 * (v - V0) * 8);
;       const f32x8 t1 = *(const f32x8*)(tab + 2 * (v - V0) * 8 + 8);
;       f32x8 o1, o2;
; #pragma unroll
;       for (int e = 0; e < 8; ++e) {
;         float y1 = x1[e], y2 = x2[e];
;         if (GAIN) { y1 = y1 * rstd * g1[e]; y2 = y2 * rstd * g2[e]; }
;         const float c = (e < 4) ? t0[2 * e] : t1[2 * (e - 4)];
;         const float sn = (e < 4) ? t0[2 * e + 1] : t1[2 * (e - 4) + 1];
;         o1[e] = y1 * c - y2 * sn;
;         o2[e] = y2 * c + y1 * sn;
;       }
;       *(u32x4*)(p + v * 8) = f32_to_bf8(o1);
;       *(u32x4*)(p + (v + NRV) * 8) = f32_to_bf8(o2);
;     } else if (GAIN) {
;       f32x8 x1 = bf8_to_f32(RAWV(v));
;       const f32x8 g1 = *(const f32x8*)(gain + v * 8);
; #pragma unroll
;       for (int e = 0; e < 8; ++e) x1[e] = x1[e] * rstd * g1[e];
;       *(u32x4*)(p + v * 8) = f32_to_bf8(x1);
;     }
	v_mov_b32_e32 v14, v10
	v_pk_mul_f32 v[4:5], v[12:13], v[4:5]
	v_pk_mul_f32 v[8:9], v[14:15], v[8:9]
	v_bfe_u32 v10, v5, 16, 1
	v_bfe_u32 v11, v4, 16, 1
	v_bfe_u32 v12, v7, 16, 1
	v_bfe_u32 v13, v6, 16, 1
	v_add3_u32 v6, v6, v13, s54
	v_add3_u32 v7, v7, v12, s54
	v_add3_u32 v4, v4, v11, s54
	v_add3_u32 v5, v5, v10, s54
	v_bfe_u32 v10, v2, 16, 1
	v_bfe_u32 v11, v3, 16, 1
	v_bfe_u32 v12, v8, 16, 1
	v_bfe_u32 v13, v9, 16, 1
	v_add3_u32 v9, v9, v13, s54
	v_add3_u32 v8, v8, v12, s54
	v_add3_u32 v3, v3, v11, s54
	v_add3_u32 v2, v2, v10, s54
	v_lshrrev_b32_e32 v2, 16, v2
	v_lshrrev_b32_e32 v3, 16, v3
	v_lshrrev_b32_e32 v8, 16, v8
	v_lshrrev_b32_e32 v9, 16, v9
	v_and_or_b32 v5, v5, s56, v9
	v_and_or_b32 v4, v4, s56, v8
	v_and_or_b32 v3, v7, s56, v3
	v_and_or_b32 v2, v6, s56, v2
	global_store_dwordx4 v[32:33], v[2:5], off offset:240
	global_load_dwordx4 v[10:13], v[32:33], off offset:256
	global_load_dwordx4 v[14:17], v[32:33], off offset:320
	global_load_dwordx4 v[34:37], v1, s[4:5] offset:1408
	global_load_dwordx4 v[38:41], v1, s[4:5] offset:1280
	global_load_dwordx4 v[42:45], v[28:29], off offset:192
	global_load_dwordx4 v[46:49], v[28:29], off offset:208
	global_load_dwordx4 v[50:53], v1, s[4:5] offset:1424
	global_load_dwordx4 v[54:57], v1, s[4:5] offset:1296
	global_load_dwordx4 v[58:61], v[28:29], off offset:224
	global_load_dwordx4 v[62:65], v[28:29], off offset:240
	global_load_dwordx4 v[22:25], v[32:33], off offset:272
	global_load_dwordx4 v[18:21], v[32:33], off offset:336
	global_load_dwordx4 v[2:5], v1, s[4:5] offset:1328
	global_load_dwordx4 v[66:69], v1, s[4:5] offset:1312
	global_load_dwordx4 v[6:9], v1, s[4:5] offset:1456
	global_load_dwordx4 v[70:73], v1, s[4:5] offset:1440
	s_waitcnt vmcnt(0)
	v_lshlrev_b32_e32 v75, 16, v11
	v_lshlrev_b32_e32 v77, 16, v15
	v_lshlrev_b32_e32 v76, 16, v14
	v_and_b32_e32 v15, 0xffff0000, v15
	v_and_b32_e32 v14, 0xffff0000, v14
	v_mov_b32_e32 v80, v38
	v_mov_b32_e32 v81, v40
	v_mov_b32_e32 v40, v39
	v_mov_b32_e32 v38, v44
	v_mov_b32_e32 v39, v48
	v_mov_b32_e32 v48, v45
	v_lshlrev_b32_e32 v45, 16, v17
	v_lshlrev_b32_e32 v44, 16, v16
	v_and_b32_e32 v17, 0xffff0000, v17
	v_and_b32_e32 v16, 0xffff0000, v16
	v_lshlrev_b32_e32 v74, 16, v10
	v_and_b32_e32 v11, 0xffff0000, v11
	v_and_b32_e32 v10, 0xffff0000, v10
	v_mov_b32_e32 v78, v34
	v_mov_b32_e32 v79, v36
	v_mov_b32_e32 v36, v35
	v_mov_b32_e32 v34, v42
	v_mov_b32_e32 v35, v46
	v_mov_b32_e32 v46, v43
	v_lshlrev_b32_e32 v43, 16, v13
	v_lshlrev_b32_e32 v42, 16, v12
	v_and_b32_e32 v13, 0xffff0000, v13
	v_and_b32_e32 v12, 0xffff0000, v12
	v_mov_b32_e32 v83, v52
	v_mov_b32_e32 v52, v51
	v_pk_mul_f32 v[14:15], v[0:1], v[14:15] op_sel_hi:[0,1]
	v_pk_mul_f32 v[16:17], v[0:1], v[16:17] op_sel_hi:[0,1]
	v_mov_b32_e32 v82, v50
	v_mov_b32_e32 v85, v56
	v_mov_b32_e32 v56, v55
	v_mov_b32_e32 v50, v58
	v_mov_b32_e32 v51, v62
	v_mov_b32_e32 v62, v59
	v_mov_b32_e32 v55, v64
	v_mov_b32_e32 v64, v61
	v_pk_mul_f32 v[58:59], v[0:1], v[76:77] op_sel_hi:[0,1]
	v_pk_mul_f32 v[10:11], v[0:1], v[10:11] op_sel_hi:[0,1]
	v_pk_mul_f32 v[44:45], v[0:1], v[44:45] op_sel_hi:[0,1]
	v_pk_mul_f32 v[12:13], v[0:1], v[12:13] op_sel_hi:[0,1]
	v_pk_mul_f32 v[14:15], v[36:37], v[14:15]
	v_pk_mul_f32 v[16:17], v[52:53], v[16:17]
	v_mov_b32_e32 v84, v54
	v_mov_b32_e32 v54, v60
	v_pk_mul_f32 v[60:61], v[0:1], v[74:75] op_sel_hi:[0,1]
	v_pk_mul_f32 v[42:43], v[0:1], v[42:43] op_sel_hi:[0,1]
	v_pk_mul_f32 v[58:59], v[78:79], v[58:59]
	v_pk_mul_f32 v[36:37], v[40:41], v[10:11]
	v_pk_mul_f32 v[40:41], v[82:83], v[44:45]
	v_pk_mul_f32 v[44:45], v[56:57], v[12:13]
	v_pk_mul_f32 v[12:13], v[48:49], v[14:15]
	v_pk_mul_f32 v[56:57], v[64:65], v[16:17]
	v_pk_mul_f32 v[60:61], v[80:81], v[60:61]
	v_pk_mul_f32 v[42:43], v[84:85], v[42:43]
	v_pk_mul_f32 v[10:11], v[46:47], v[58:59]
	v_pk_mul_f32 v[52:53], v[62:63], v[40:41]
	v_pk_fma_f32 v[12:13], v[38:39], v[36:37], v[12:13] neg_lo:[0,0,1] neg_hi:[0,0,1]
	v_pk_fma_f32 v[56:57], v[54:55], v[44:45], v[56:57] neg_lo:[0,0,1] neg_hi:[0,0,1]
	v_pk_fma_f32 v[10:11], v[34:35], v[60:61], v[10:11] neg_lo:[0,0,1] neg_hi:[0,0,1]
	v_pk_fma_f32 v[52:53], v[50:51], v[42:43], v[52:53] neg_lo:[0,0,1] neg_hi:[0,0,1]
	v_bfe_u32 v74, v57, 16, 1
	v_bfe_u32 v75, v56, 16, 1
	v_bfe_u32 v76, v13, 16, 1
	v_bfe_u32 v77, v12, 16, 1
	v_add3_u32 v77, v12, v77, s54
	v_add3_u32 v76, v13, v76, s54
	v_add3_u32 v12, v56, v75, s54
	v_add3_u32 v13, v57, v74, s54
	v_bfe_u32 v56, v10, 16, 1
	v_bfe_u32 v57, v11, 16, 1
	v_bfe_u32 v74, v52, 16, 1
	v_bfe_u32 v75, v53, 16, 1
	v_add3_u32 v53, v53, v75, s54
	v_add3_u32 v52, v52, v74, s54
	v_add3_u32 v11, v11, v57, s54
	v_add3_u32 v10, v10, v56, s54
	v_lshrrev_b32_e32 v10, 16, v10
	v_lshrrev_b32_e32 v11, 16, v11
	v_lshrrev_b32_e32 v52, 16, v52
	v_lshrrev_b32_e32 v53, 16, v53
	v_and_or_b32 v13, v13, s56, v53
	v_and_or_b32 v12, v12, s56, v52
	v_and_or_b32 v11, v76, s56, v11
	v_and_or_b32 v10, v77, s56, v10
	global_store_dwordx4 v[32:33], v[10:13], off offset:256
	v_lshlrev_b32_e32 v53, 16, v19
	v_lshlrev_b32_e32 v52, 16, v18
	v_pk_mul_f32 v[10:11], v[46:47], v[60:61]
	v_pk_mul_f32 v[12:13], v[48:49], v[36:37]
	v_pk_fma_f32 v[10:11], v[34:35], v[58:59], v[10:11]
	v_pk_mul_f32 v[34:35], v[64:65], v[44:45]
	v_pk_fma_f32 v[12:13], v[38:39], v[14:15], v[12:13]
	v_pk_mul_f32 v[14:15], v[62:63], v[42:43]
	v_pk_fma_f32 v[16:17], v[54:55], v[16:17], v[34:35]
	v_pk_fma_f32 v[14:15], v[50:51], v[40:41], v[14:15]
	v_bfe_u32 v34, v17, 16, 1
	v_bfe_u32 v35, v16, 16, 1
	v_bfe_u32 v36, v13, 16, 1
	v_bfe_u32 v37, v12, 16, 1
	v_add3_u32 v37, v12, v37, s54
	v_add3_u32 v36, v13, v36, s54
	v_add3_u32 v12, v16, v35, s54
	v_add3_u32 v13, v17, v34, s54
	v_bfe_u32 v16, v10, 16, 1
; template <int D, int ROT0, int HALF, bool GAIN, bool KEEP = true>
; DI void chunk_nr(u16* p, const float* __restrict__ gain, const float* __restrict__ tab) {
;     ...
;     if (v >= V0 && v < V0 + 2 * NRV) {
;       if (v >= V0 + NRV) continue;
;       const f32x8 x1 = bf8_to_f32(RAWV(v));
;       const f32x8 x2 = bf8_to_f32(RAWV(v + NRV));
;       f32x8 g1, g2;
;       if (GAIN) { g1 = *(const f32x8*)(gain + v * 8); g2 = *(const f32x8*)(gain + (v + NRV) * 8); }
;       const f32x8 t0 = *(const f32x8*)(tab + 2 * (v - V0) * 8);
;       const f32x8 t1 = *(const f32x8*)(tab + 2 * (v - V0) * 8 + 8);
;       f32x8 o1, o2;
; #pragma unroll
;       for (int e = 0; e < 8; ++e) {
;         float y1 = x1[e], y2 = x2[e];
;         if (GAIN) { y1 = y1 * rstd * g1[e]; y2 = y2 * rstd * g2[e]; }
;         const float c = (e < 4) ? t0[2 * e] : t1[2 * (e - 4)];
;         const float sn = (e < 4) ? t0[2 * e + 1] : t1[2 * (e - 4) + 1];
;         o1[e] = y1 * c - y2 * sn;
;         o2[e] = y2 * c + y1 * sn;
;       }
;       *(u32x4*)(p + v * 8) = f32_to_bf8(o1);
;       *(u32x4*)(p + (v + NRV) * 8) = f32_to_bf8(o2);
	v_bfe_u32 v17, v11, 16, 1
	v_bfe_u32 v34, v14, 16, 1
	v_bfe_u32 v35, v15, 16, 1
	v_add3_u32 v15, v15, v35, s54
	v_add3_u32 v14, v14, v34, s54
	v_add3_u32 v11, v11, v17, s54
	v_add3_u32 v10, v10, v16, s54
	v_lshrrev_b32_e32 v10, 16, v10
	v_lshrrev_b32_e32 v11, 16, v11
	v_lshrrev_b32_e32 v14, 16, v14
	v_lshrrev_b32_e32 v15, 16, v15
	v_and_or_b32 v13, v13, s56, v15
	v_and_or_b32 v12, v12, s56, v14
	v_and_or_b32 v11, v36, s56, v11
	v_and_or_b32 v10, v37, s56, v10
	global_store_dwordx4 v[32:33], v[10:13], off offset:320
	global_load_dwordx4 v[34:37], v[28:29], off offset:256
	global_load_dwordx4 v[38:41], v[28:29], off offset:272
	global_load_dwordx4 v[42:45], v[28:29], off offset:288
	global_load_dwordx4 v[46:49], v[28:29], off offset:304
	global_load_dwordx4 v[14:17], v[32:33], off offset:288
	global_load_dwordx4 v[10:13], v[32:33], off offset:352
	v_and_b32_e32 v19, 0xffff0000, v19
	v_and_b32_e32 v18, 0xffff0000, v18
	v_lshlrev_b32_e32 v61, 16, v21
	v_lshlrev_b32_e32 v60, 16, v20
	v_and_b32_e32 v21, 0xffff0000, v21
	v_and_b32_e32 v20, 0xffff0000, v20
	v_lshlrev_b32_e32 v51, 16, v23
	v_lshlrev_b32_e32 v50, 16, v22
	v_and_b32_e32 v23, 0xffff0000, v23
	v_and_b32_e32 v22, 0xffff0000, v22
	v_mov_b32_e32 v54, v70
	v_mov_b32_e32 v55, v72
	v_mov_b32_e32 v72, v71
	v_pk_mul_f32 v[52:53], v[0:1], v[52:53] op_sel_hi:[0,1]
	v_pk_mul_f32 v[18:19], v[0:1], v[18:19] op_sel_hi:[0,1]
	v_lshlrev_b32_e32 v59, 16, v25
	v_lshlrev_b32_e32 v58, 16, v24
	v_and_b32_e32 v25, 0xffff0000, v25
	v_and_b32_e32 v24, 0xffff0000, v24
	v_pk_mul_f32 v[60:61], v[0:1], v[60:61] op_sel_hi:[0,1]
	v_mov_b32_e32 v62, v6
	v_mov_b32_e32 v63, v8
	v_pk_mul_f32 v[20:21], v[0:1], v[20:21] op_sel_hi:[0,1]
	v_mov_b32_e32 v8, v7
	v_mov_b32_e32 v57, v68
	v_mov_b32_e32 v68, v67
	v_pk_mul_f32 v[22:23], v[0:1], v[22:23] op_sel_hi:[0,1]
	v_pk_mul_f32 v[52:53], v[54:55], v[52:53]
	v_pk_mul_f32 v[18:19], v[72:73], v[18:19]
	v_pk_mul_f32 v[60:61], v[62:63], v[60:61]
	v_mov_b32_e32 v63, v4
	v_pk_mul_f32 v[6:7], v[8:9], v[20:21]
	v_pk_mul_f32 v[8:9], v[0:1], v[24:25] op_sel_hi:[0,1]
	v_mov_b32_e32 v4, v3
	v_mov_b32_e32 v56, v66
	v_pk_mul_f32 v[50:51], v[0:1], v[50:51] op_sel_hi:[0,1]
	v_pk_mul_f32 v[22:23], v[68:69], v[22:23]
	v_pk_mul_f32 v[58:59], v[0:1], v[58:59] op_sel_hi:[0,1]
	v_mov_b32_e32 v62, v2
	v_pk_mul_f32 v[8:9], v[4:5], v[8:9]
	v_pk_mul_f32 v[50:51], v[56:57], v[50:51]
	v_pk_mul_f32 v[58:59], v[62:63], v[58:59]
	s_waitcnt vmcnt(0)
	v_mov_b32_e32 v54, v34
	v_mov_b32_e32 v55, v38
	v_mov_b32_e32 v38, v35
	v_mov_b32_e32 v35, v40
	v_mov_b32_e32 v40, v37
	v_mov_b32_e32 v25, v48
	v_mov_b32_e32 v48, v45
	v_mov_b32_e32 v34, v36
	v_pk_mul_f32 v[36:37], v[40:41], v[18:19]
	v_mov_b32_e32 v21, v46
	v_mov_b32_e32 v46, v43
	v_mov_b32_e32 v24, v44
	v_pk_mul_f32 v[4:5], v[48:49], v[6:7]
	v_pk_mul_f32 v[56:57], v[38:39], v[52:53]
	v_pk_fma_f32 v[36:37], v[34:35], v[22:23], v[36:37] neg_lo:[0,0,1] neg_hi:[0,0,1]
	v_mov_b32_e32 v20, v42
	v_pk_mul_f32 v[2:3], v[46:47], v[60:61]
	v_pk_fma_f32 v[4:5], v[24:25], v[8:9], v[4:5] neg_lo:[0,0,1] neg_hi:[0,0,1]
	v_pk_fma_f32 v[56:57], v[54:55], v[50:51], v[56:57] neg_lo:[0,0,1] neg_hi:[0,0,1]
	v_pk_fma_f32 v[2:3], v[20:21], v[58:59], v[2:3] neg_lo:[0,0,1] neg_hi:[0,0,1]
	v_bfe_u32 v42, v5, 16, 1
	v_bfe_u32 v43, v4, 16, 1
	v_bfe_u32 v44, v37, 16, 1
	v_bfe_u32 v45, v36, 16, 1
	v_add3_u32 v36, v36, v45, s54
	v_add3_u32 v37, v37, v44, s54
	v_add3_u32 v4, v4, v43, s54
	v_add3_u32 v5, v5, v42, s54
	v_bfe_u32 v42, v56, 16, 1
	v_bfe_u32 v43, v57, 16, 1
	v_bfe_u32 v44, v2, 16, 1
	v_bfe_u32 v45, v3, 16, 1
	v_add3_u32 v3, v3, v45, s54
	v_add3_u32 v2, v2, v44, s54
	v_add3_u32 v43, v57, v43, s54
	v_add3_u32 v42, v56, v42, s54
	v_lshrrev_b32_e32 v42, 16, v42
	v_lshrrev_b32_e32 v43, 16, v43
	v_lshrrev_b32_e32 v2, 16, v2
	v_lshrrev_b32_e32 v3, 16, v3
	v_and_or_b32 v5, v5, s56, v3
	v_and_or_b32 v4, v4, s56, v2
	v_and_or_b32 v3, v37, s56, v43
	v_and_or_b32 v2, v36, s56, v42
	global_store_dwordx4 v[32:33], v[2:5], off offset:272
	v_pk_mul_f32 v[8:9], v[48:49], v[8:9]
	v_lshlrev_b32_e32 v77, 16, v11
	v_pk_mul_f32 v[4:5], v[40:41], v[22:23]
	v_pk_mul_f32 v[2:3], v[38:39], v[50:51]
	v_pk_fma_f32 v[4:5], v[34:35], v[18:19], v[4:5]
	v_pk_mul_f32 v[18:19], v[46:47], v[58:59]
	v_pk_fma_f32 v[6:7], v[24:25], v[6:7], v[8:9]
	v_pk_fma_f32 v[2:3], v[54:55], v[52:53], v[2:3]
	v_pk_fma_f32 v[18:19], v[20:21], v[60:61], v[18:19]
	v_bfe_u32 v8, v7, 16, 1
	v_bfe_u32 v9, v6, 16, 1
	v_bfe_u32 v20, v5, 16, 1
	v_bfe_u32 v21, v4, 16, 1
	v_add3_u32 v21, v4, v21, s54
	v_add3_u32 v20, v5, v20, s54
	v_add3_u32 v4, v6, v9, s54
	v_add3_u32 v5, v7, v8, s54
	v_bfe_u32 v6, v2, 16, 1
	v_bfe_u32 v7, v3, 16, 1
	v_bfe_u32 v8, v18, 16, 1
	v_bfe_u32 v9, v19, 16, 1
	v_add3_u32 v9, v19, v9, s54
	v_add3_u32 v8, v18, v8, s54
	v_add3_u32 v3, v3, v7, s54
	v_add3_u32 v2, v2, v6, s54
	v_lshrrev_b32_e32 v2, 16, v2
	v_lshrrev_b32_e32 v3, 16, v3
	v_lshrrev_b32_e32 v6, 16, v8
	v_lshrrev_b32_e32 v7, 16, v9
	v_and_or_b32 v5, v5, s56, v7
	v_and_or_b32 v4, v4, s56, v6
	v_and_or_b32 v3, v20, s56, v3
	v_and_or_b32 v2, v21, s56, v2
	global_store_dwordx4 v[32:33], v[2:5], off offset:336
	global_load_dwordx4 v[6:9], v1, s[4:5] offset:1472
	global_load_dwordx4 v[18:21], v1, s[4:5] offset:1344
	global_load_dwordx4 v[22:25], v[28:29], off offset:320
	global_load_dwordx4 v[34:37], v[28:29], off offset:336
	global_load_dwordx4 v[38:41], v1, s[4:5] offset:1488
	global_load_dwordx4 v[42:45], v1, s[4:5] offset:1360
	global_load_dwordx4 v[46:49], v[28:29], off offset:352
	global_load_dwordx4 v[50:53], v[28:29], off offset:368
	global_load_dwordx4 v[54:57], v[32:33], off offset:304
	global_load_dwordx4 v[58:61], v[32:33], off offset:368
	global_load_dwordx4 v[2:5], v1, s[4:5] offset:1392
	global_load_dwordx4 v[62:65], v1, s[4:5] offset:1376
	global_load_dwordx4 v[66:69], v1, s[4:5] offset:1520
	global_load_dwordx4 v[70:73], v1, s[4:5] offset:1504
	v_lshlrev_b32_e32 v76, 16, v10
	v_lshlrev_b32_e32 v75, 16, v15
	v_lshlrev_b32_e32 v74, 16, v14
	v_and_b32_e32 v15, 0xffff0000, v15
	v_and_b32_e32 v14, 0xffff0000, v14
	v_pk_mul_f32 v[76:77], v[0:1], v[76:77] op_sel_hi:[0,1]
	v_and_b32_e32 v11, 0xffff0000, v11
	v_and_b32_e32 v10, 0xffff0000, v10
	v_pk_mul_f32 v[74:75], v[0:1], v[74:75] op_sel_hi:[0,1]
	v_pk_mul_f32 v[10:11], v[0:1], v[10:11] op_sel_hi:[0,1]
	s_waitcnt vmcnt(0)
; template <int D, int ROT0, int HALF, bool GAIN, bool KEEP = true>
; DI void chunk_nr(u16* p, const float* __restrict__ gain, const float* __restrict__ tab) {
;     ...
;     if (v >= V0 && v < V0 + 2 * NRV) {
;       if (v >= V0 + NRV) continue;
;       const f32x8 x1 = bf8_to_f32(RAWV(v));
;       const f32x8 x2 = bf8_to_f32(RAWV(v + NRV));
;       f32x8 g1, g2;
;       if (GAIN) { g1 = *(const f32x8*)(gain + v * 8); g2 = *(const f32x8*)(gain + (v + NRV) * 8); }
;       const f32x8 t0 = *(const f32x8*)(tab + 2 * (v - V0) * 8);
;       const f32x8 t1 = *(const f32x8*)(tab + 2 * (v - V0) * 8 + 8);
;       f32x8 o1, o2;
; #pragma unroll
;       for (int e = 0; e < 8; ++e) {
;         float y1 = x1[e], y2 = x2[e];
;         if (GAIN) { y1 = y1 * rstd * g1[e]; y2 = y2 * rstd * g2[e]; }
;         const float c = (e < 4) ? t0[2 * e] : t1[2 * (e - 4)];
;         const float sn = (e < 4) ? t0[2 * e + 1] : t1[2 * (e - 4) + 1];
;         o1[e] = y1 * c - y2 * sn;
;         o2[e] = y2 * c + y1 * sn;
;       }
;       *(u32x4*)(p + v * 8) = f32_to_bf8(o1);
;       *(u32x4*)(p + (v + NRV) * 8) = f32_to_bf8(o2);
	v_mov_b32_e32 v78, v6
	v_mov_b32_e32 v79, v8
	v_pk_mul_f32 v[76:77], v[78:79], v[76:77]
	v_mov_b32_e32 v79, v20
	v_mov_b32_e32 v8, v7
	v_pk_mul_f32 v[6:7], v[0:1], v[14:15] op_sel_hi:[0,1]
	v_mov_b32_e32 v20, v19
	v_mov_b32_e32 v78, v18
	v_pk_mul_f32 v[14:15], v[20:21], v[6:7]
	v_mov_b32_e32 v20, v24
	v_mov_b32_e32 v21, v36
	v_mov_b32_e32 v36, v25
	v_lshlrev_b32_e32 v25, 16, v13
	v_lshlrev_b32_e32 v24, 16, v12
	v_and_b32_e32 v13, 0xffff0000, v13
	v_and_b32_e32 v12, 0xffff0000, v12
	v_pk_mul_f32 v[74:75], v[78:79], v[74:75]
	v_mov_b32_e32 v18, v22
	v_mov_b32_e32 v19, v34
	v_mov_b32_e32 v34, v23
	v_lshlrev_b32_e32 v23, 16, v17
	v_lshlrev_b32_e32 v22, 16, v16
	v_and_b32_e32 v17, 0xffff0000, v17
	v_and_b32_e32 v16, 0xffff0000, v16
	v_pk_mul_f32 v[24:25], v[0:1], v[24:25] op_sel_hi:[0,1]
	v_mov_b32_e32 v78, v38
	v_mov_b32_e32 v79, v40
	v_pk_mul_f32 v[12:13], v[0:1], v[12:13] op_sel_hi:[0,1]
	v_mov_b32_e32 v40, v39
	v_pk_mul_f32 v[10:11], v[8:9], v[10:11]
	v_pk_mul_f32 v[24:25], v[78:79], v[24:25]
	v_mov_b32_e32 v79, v44
	v_pk_mul_f32 v[12:13], v[40:41], v[12:13]
	v_pk_mul_f32 v[16:17], v[0:1], v[16:17] op_sel_hi:[0,1]
	v_mov_b32_e32 v44, v43
	v_mov_b32_e32 v43, v52
	v_mov_b32_e32 v52, v49
	v_pk_mul_f32 v[8:9], v[36:37], v[10:11]
	v_pk_mul_f32 v[22:23], v[0:1], v[22:23] op_sel_hi:[0,1]
	v_mov_b32_e32 v78, v42
	v_pk_mul_f32 v[16:17], v[44:45], v[16:17]
	v_mov_b32_e32 v39, v50
	v_mov_b32_e32 v50, v47
	v_mov_b32_e32 v42, v48
	v_pk_mul_f32 v[44:45], v[52:53], v[12:13]
	v_pk_mul_f32 v[6:7], v[34:35], v[76:77]
	v_pk_fma_f32 v[8:9], v[20:21], v[14:15], v[8:9] neg_lo:[0,0,1] neg_hi:[0,0,1]
	v_pk_mul_f32 v[22:23], v[78:79], v[22:23]
	v_mov_b32_e32 v38, v46
	v_pk_mul_f32 v[40:41], v[50:51], v[24:25]
	v_pk_fma_f32 v[44:45], v[42:43], v[16:17], v[44:45] neg_lo:[0,0,1] neg_hi:[0,0,1]
	v_pk_fma_f32 v[6:7], v[18:19], v[74:75], v[6:7] neg_lo:[0,0,1] neg_hi:[0,0,1]
	v_pk_fma_f32 v[40:41], v[38:39], v[22:23], v[40:41] neg_lo:[0,0,1] neg_hi:[0,0,1]
	v_bfe_u32 v46, v45, 16, 1
	v_bfe_u32 v47, v44, 16, 1
	v_bfe_u32 v48, v9, 16, 1
	v_bfe_u32 v49, v8, 16, 1
	v_add3_u32 v49, v8, v49, s54
	v_add3_u32 v48, v9, v48, s54
	v_add3_u32 v8, v44, v47, s54
	v_add3_u32 v9, v45, v46, s54
	v_bfe_u32 v44, v6, 16, 1
	v_bfe_u32 v45, v7, 16, 1
	v_bfe_u32 v46, v40, 16, 1
	v_bfe_u32 v47, v41, 16, 1
	v_add3_u32 v41, v41, v47, s54
	v_add3_u32 v40, v40, v46, s54
	v_add3_u32 v7, v7, v45, s54
	v_add3_u32 v6, v6, v44, s54
	v_lshrrev_b32_e32 v6, 16, v6
	v_lshrrev_b32_e32 v7, 16, v7
	v_lshrrev_b32_e32 v40, 16, v40
	v_lshrrev_b32_e32 v41, 16, v41
	v_and_or_b32 v9, v9, s56, v41
	v_and_or_b32 v8, v8, s56, v40
	v_and_or_b32 v7, v48, s56, v7
	v_and_or_b32 v6, v49, s56, v6
	global_store_dwordx4 v[32:33], v[6:9], off offset:288
	v_lshlrev_b32_e32 v47, 16, v61
	v_lshlrev_b32_e32 v46, 16, v60
	v_pk_mul_f32 v[8:9], v[36:37], v[14:15]
	v_pk_mul_f32 v[14:15], v[52:53], v[16:17]
	v_pk_mul_f32 v[6:7], v[34:35], v[74:75]
	v_pk_fma_f32 v[8:9], v[20:21], v[10:11], v[8:9]
	v_pk_mul_f32 v[10:11], v[50:51], v[22:23]
	v_pk_fma_f32 v[12:13], v[42:43], v[12:13], v[14:15]
	v_pk_fma_f32 v[6:7], v[18:19], v[76:77], v[6:7]
	v_pk_fma_f32 v[10:11], v[38:39], v[24:25], v[10:11]
	v_bfe_u32 v14, v13, 16, 1
	v_bfe_u32 v15, v12, 16, 1
	v_bfe_u32 v16, v9, 16, 1
	v_bfe_u32 v17, v8, 16, 1
	v_add3_u32 v17, v8, v17, s54
	v_add3_u32 v16, v9, v16, s54
	v_add3_u32 v8, v12, v15, s54
	v_add3_u32 v9, v13, v14, s54
	v_bfe_u32 v12, v6, 16, 1
	v_bfe_u32 v13, v7, 16, 1
	v_bfe_u32 v14, v10, 16, 1
	v_bfe_u32 v15, v11, 16, 1
	v_add3_u32 v11, v11, v15, s54
	v_add3_u32 v10, v10, v14, s54
	v_add3_u32 v7, v7, v13, s54
	v_add3_u32 v6, v6, v12, s54
	v_lshrrev_b32_e32 v6, 16, v6
	v_lshrrev_b32_e32 v7, 16, v7
	v_lshrrev_b32_e32 v10, 16, v10
	v_lshrrev_b32_e32 v11, 16, v11
	v_and_or_b32 v9, v9, s56, v11
	v_and_or_b32 v8, v8, s56, v10
	v_and_or_b32 v7, v16, s56, v7
	v_and_or_b32 v6, v17, s56, v6
	global_store_dwordx4 v[32:33], v[6:9], off offset:352
	global_load_dwordx4 v[6:9], v[28:29], off offset:384
	s_nop 0
	global_load_dwordx4 v[10:13], v[28:29], off offset:400
	global_load_dwordx4 v[14:17], v[28:29], off offset:416
	global_load_dwordx4 v[18:21], v[28:29], off offset:432
	v_lshlrev_b32_e32 v35, 16, v59
	v_lshlrev_b32_e32 v34, 16, v58
	v_and_b32_e32 v37, 0xffff0000, v59
	v_and_b32_e32 v36, 0xffff0000, v58
	v_lshlrev_b32_e32 v43, 16, v57
	v_lshlrev_b32_e32 v42, 16, v56
	v_and_b32_e32 v49, 0xffff0000, v61
	v_and_b32_e32 v48, 0xffff0000, v60
	v_pk_mul_f32 v[46:47], v[0:1], v[46:47] op_sel_hi:[0,1]
	v_mov_b32_e32 v50, v66
	v_mov_b32_e32 v51, v68
	v_lshlrev_b32_e32 v23, 16, v55
	v_lshlrev_b32_e32 v22, 16, v54
	v_and_b32_e32 v25, 0xffff0000, v55
	v_and_b32_e32 v24, 0xffff0000, v54
	v_pk_mul_f32 v[34:35], v[0:1], v[34:35] op_sel_hi:[0,1]
	v_mov_b32_e32 v38, v70
	v_mov_b32_e32 v39, v72
	v_pk_mul_f32 v[36:37], v[0:1], v[36:37] op_sel_hi:[0,1]
	v_mov_b32_e32 v72, v71
	v_and_b32_e32 v45, 0xffff0000, v57
	v_and_b32_e32 v44, 0xffff0000, v56
	v_pk_mul_f32 v[46:47], v[50:51], v[46:47]
	v_pk_mul_f32 v[42:43], v[0:1], v[42:43] op_sel_hi:[0,1]
	v_mov_b32_e32 v50, v2
	v_mov_b32_e32 v51, v4
	v_pk_mul_f32 v[48:49], v[0:1], v[48:49] op_sel_hi:[0,1]
	v_mov_b32_e32 v68, v67
	v_pk_mul_f32 v[34:35], v[38:39], v[34:35]
	v_pk_mul_f32 v[22:23], v[0:1], v[22:23] op_sel_hi:[0,1]
	v_mov_b32_e32 v38, v62
	v_mov_b32_e32 v39, v64
	v_pk_mul_f32 v[36:37], v[72:73], v[36:37]
	v_pk_mul_f32 v[24:25], v[0:1], v[24:25] op_sel_hi:[0,1]
	v_mov_b32_e32 v64, v63
	v_pk_mul_f32 v[42:43], v[50:51], v[42:43]
	v_pk_mul_f32 v[48:49], v[68:69], v[48:49]
	v_pk_mul_f32 v[44:45], v[0:1], v[44:45] op_sel_hi:[0,1]
	v_mov_b32_e32 v4, v3
	v_pk_mul_f32 v[22:23], v[38:39], v[22:23]
	v_pk_mul_f32 v[24:25], v[64:65], v[24:25]
	v_pk_mul_f32 v[44:45], v[4:5], v[44:45]
	s_waitcnt vmcnt(0)
; template <int D, int ROT0, int HALF, bool GAIN, bool KEEP = true>
; DI void chunk_nr(u16* p, const float* __restrict__ gain, const float* __restrict__ tab) {
;     ...
;   float rstd = 1.f;
;   if (GAIN) {
;     float ss = 0.f;
; #pragma unroll
;     for (int v = 0; v < NV; ++v) {
;       const f32x8 f = bf8_to_f32(RAWV(v));
; #pragma unroll
;       for (int e = 0; e < 8; ++e) ss += f[e] * f[e];
;       if (!KEEP && (v & 7) == 7) __builtin_amdgcn_sched_barrier(0);
;     }
;     rstd = rsqrtf(ss * (1.0f / D) + EPS);
;   }
; #pragma unroll
;   for (int v = 0; v < NV; ++v) {
;     if (v >= V0 && v < V0 + 2 * NRV) {
;       if (v >= V0 + NRV) continue;
;       const f32x8 x1 = bf8_to_f32(RAWV(v));
;       const f32x8 x2 = bf8_to_f32(RAWV(v + NRV));
;       f32x8 g1, g2;
;       if (GAIN) { g1 = *(const f32x8*)(gain + v * 8); g2 = *(const f32x8*)(gain + (v + NRV) * 8); }
;       const f32x8 t0 = *(const f32x8*)(tab + 2 * (v - V0) * 8);
;       const f32x8 t1 = *(const f32x8*)(tab + 2 * (v - V0) * 8 + 8);
;       f32x8 o1, o2;
; #pragma unroll
;       for (int e = 0; e < 8; ++e) {
;         float y1 = x1[e], y2 = x2[e];
;         if (GAIN) { y1 = y1 * rstd * g1[e]; y2 = y2 * rstd * g2[e]; }
;         const float c = (e < 4) ? t0[2 * e] : t1[2 * (e - 4)];
;         const float sn = (e < 4) ? t0[2 * e + 1] : t1[2 * (e - 4) + 1];
;         o1[e] = y1 * c - y2 * sn;
;         o2[e] = y2 * c + y1 * sn;
;       }
;       *(u32x4*)(p + v * 8) = f32_to_bf8(o1);
;       *(u32x4*)(p + (v + NRV) * 8) = f32_to_bf8(o2);
	v_mov_b32_e32 v40, v8
	v_mov_b32_e32 v41, v12
	v_mov_b32_e32 v12, v9
	v_mov_b32_e32 v51, v18
	v_mov_b32_e32 v18, v15
	v_mov_b32_e32 v15, v20
	v_mov_b32_e32 v20, v17
	v_mov_b32_e32 v39, v10
	v_mov_b32_e32 v10, v7
	v_pk_mul_f32 v[8:9], v[12:13], v[36:37]
	v_mov_b32_e32 v50, v14
	v_mov_b32_e32 v14, v16
	v_pk_mul_f32 v[4:5], v[20:21], v[48:49]
	v_mov_b32_e32 v38, v6
	v_pk_mul_f32 v[6:7], v[10:11], v[34:35]
	v_pk_fma_f32 v[8:9], v[40:41], v[24:25], v[8:9] neg_lo:[0,0,1] neg_hi:[0,0,1]
	v_pk_mul_f32 v[2:3], v[18:19], v[46:47]
	v_pk_fma_f32 v[4:5], v[14:15], v[44:45], v[4:5] neg_lo:[0,0,1] neg_hi:[0,0,1]
	v_pk_fma_f32 v[6:7], v[38:39], v[22:23], v[6:7] neg_lo:[0,0,1] neg_hi:[0,0,1]
	v_pk_fma_f32 v[2:3], v[50:51], v[42:43], v[2:3] neg_lo:[0,0,1] neg_hi:[0,0,1]
	v_bfe_u32 v0, v5, 16, 1
	v_bfe_u32 v16, v4, 16, 1
	v_bfe_u32 v17, v9, 16, 1
	v_bfe_u32 v52, v8, 16, 1
	v_add3_u32 v8, v8, v52, s54
	v_add3_u32 v9, v9, v17, s54
	v_add3_u32 v4, v4, v16, s54
	v_add3_u32 v0, v5, v0, s54
	v_bfe_u32 v5, v6, 16, 1
	v_bfe_u32 v16, v7, 16, 1
	v_bfe_u32 v17, v2, 16, 1
	v_bfe_u32 v52, v3, 16, 1
	v_add3_u32 v3, v3, v52, s54
	v_add3_u32 v2, v2, v17, s54
	v_add3_u32 v7, v7, v16, s54
	v_add3_u32 v5, v6, v5, s54
	v_lshrrev_b32_e32 v6, 16, v5
	v_lshrrev_b32_e32 v7, 16, v7
	v_lshrrev_b32_e32 v2, 16, v2
	v_lshrrev_b32_e32 v3, 16, v3
	v_and_or_b32 v5, v0, s56, v3
	v_and_or_b32 v4, v4, s56, v2
	v_and_or_b32 v3, v9, s56, v7
	v_and_or_b32 v2, v8, s56, v6
	global_store_dwordx4 v[32:33], v[2:5], off offset:304
	v_pk_mul_f32 v[8:9], v[20:21], v[44:45]
	v_pk_mul_f32 v[6:7], v[18:19], v[42:43]
	v_pk_mul_f32 v[4:5], v[12:13], v[24:25]
	v_pk_mul_f32 v[2:3], v[10:11], v[22:23]
	v_pk_fma_f32 v[4:5], v[40:41], v[36:37], v[4:5]
	v_pk_fma_f32 v[8:9], v[14:15], v[48:49], v[8:9]
	v_pk_fma_f32 v[2:3], v[38:39], v[34:35], v[2:3]
	v_pk_fma_f32 v[6:7], v[50:51], v[46:47], v[6:7]
	v_bfe_u32 v0, v9, 16, 1
	v_bfe_u32 v10, v8, 16, 1
	v_bfe_u32 v11, v5, 16, 1
	v_bfe_u32 v12, v4, 16, 1
	v_add3_u32 v12, v4, v12, s54
	v_add3_u32 v11, v5, v11, s54
	v_add3_u32 v4, v8, v10, s54
	v_add3_u32 v0, v9, v0, s54
	v_bfe_u32 v5, v2, 16, 1
	v_bfe_u32 v8, v3, 16, 1
	v_bfe_u32 v9, v6, 16, 1
	v_bfe_u32 v10, v7, 16, 1
	v_add3_u32 v7, v7, v10, s54
	v_add3_u32 v6, v6, v9, s54
	v_add3_u32 v3, v3, v8, s54
	v_add3_u32 v2, v2, v5, s54
	v_lshrrev_b32_e32 v2, 16, v2
	v_lshrrev_b32_e32 v3, 16, v3
	v_lshrrev_b32_e32 v6, 16, v6
	v_lshrrev_b32_e32 v5, 16, v7
	v_and_or_b32 v5, v0, s56, v5
	v_and_or_b32 v4, v4, s56, v6
	v_and_or_b32 v3, v11, s56, v3
	v_and_or_b32 v2, v12, s56, v2
	global_store_dwordx4 v[32:33], v[2:5], off offset:368
	s_mov_b64 s[10:11], 0
.LBB0_193:
	s_andn2_b64 vcc, exec, s[10:11]
	s_cbranch_vccnz .LBB0_190
	v_readlane_b32 s10, v249, 29
	v_readlane_b32 s12, v249, 6
	v_readlane_b32 s11, v249, 30
	v_readlane_b32 s16, v249, 10
	v_readlane_b32 s17, v249, 11
	s_mov_b32 s8, s11
	s_ashr_i64 s[8:9], s[8:9], 31
	v_lshl_add_u64 v[2:3], s[16:17], 0, v[30:31]
	v_lshl_add_u64 v[30:31], v[2:3], 0, s[8:9]
	global_load_dwordx4 v[2:5], v[30:31], off offset:48
	global_load_dwordx4 v[6:9], v[30:31], off offset:32
	global_load_dwordx4 v[10:13], v[30:31], off offset:16
	global_load_dwordx4 v[14:17], v[30:31], off
	v_readlane_b32 s13, v249, 7
	v_readlane_b32 s14, v249, 8
	v_readlane_b32 s15, v249, 9
	v_readlane_b32 s18, v249, 12
	v_readlane_b32 s19, v249, 13
	s_waitcnt vmcnt(0)
	v_and_b32_e32 v0, 0xffff0000, v14
	v_lshlrev_b32_e32 v18, 16, v14
	v_mul_f32_e32 v0, v0, v0
	v_lshlrev_b32_e32 v14, 16, v15
	v_fmac_f32_e32 v0, v18, v18
	v_and_b32_e32 v15, 0xffff0000, v15
	v_fmac_f32_e32 v0, v14, v14
	v_lshlrev_b32_e32 v19, 16, v16
	v_fmac_f32_e32 v0, v15, v15
	v_and_b32_e32 v16, 0xffff0000, v16
	v_fmac_f32_e32 v0, v19, v19
	v_lshlrev_b32_e32 v20, 16, v17
	v_fmac_f32_e32 v0, v16, v16
	v_and_b32_e32 v17, 0xffff0000, v17
	v_fmac_f32_e32 v0, v20, v20
	v_fmac_f32_e32 v0, v17, v17
	v_lshlrev_b32_e32 v14, 16, v10
	v_and_b32_e32 v10, 0xffff0000, v10
	v_fmac_f32_e32 v0, v14, v14
	v_lshlrev_b32_e32 v15, 16, v11
	v_fmac_f32_e32 v0, v10, v10
	v_and_b32_e32 v11, 0xffff0000, v11
	v_fmac_f32_e32 v0, v15, v15
	v_lshlrev_b32_e32 v16, 16, v12
	v_fmac_f32_e32 v0, v11, v11
	v_and_b32_e32 v12, 0xffff0000, v12
	v_fmac_f32_e32 v0, v16, v16
	v_lshlrev_b32_e32 v17, 16, v13
	v_fmac_f32_e32 v0, v12, v12
	v_and_b32_e32 v13, 0xffff0000, v13
	v_fmac_f32_e32 v0, v17, v17
	v_fmac_f32_e32 v0, v13, v13
	v_lshlrev_b32_e32 v10, 16, v6
	v_and_b32_e32 v6, 0xffff0000, v6
	v_fmac_f32_e32 v0, v10, v10
	v_lshlrev_b32_e32 v11, 16, v7
	v_fmac_f32_e32 v0, v6, v6
	v_and_b32_e32 v7, 0xffff0000, v7
	v_fmac_f32_e32 v0, v11, v11
	v_lshlrev_b32_e32 v12, 16, v8
	v_fmac_f32_e32 v0, v7, v7
	v_and_b32_e32 v8, 0xffff0000, v8
	v_fmac_f32_e32 v0, v12, v12
	v_lshlrev_b32_e32 v13, 16, v9
	v_fmac_f32_e32 v0, v8, v8
	v_and_b32_e32 v9, 0xffff0000, v9
	v_fmac_f32_e32 v0, v13, v13
	v_fmac_f32_e32 v0, v9, v9
	v_lshlrev_b32_e32 v6, 16, v2
	v_and_b32_e32 v2, 0xffff0000, v2
	v_fmac_f32_e32 v0, v6, v6
	v_lshlrev_b32_e32 v7, 16, v3
	v_fmac_f32_e32 v0, v2, v2
	v_and_b32_e32 v3, 0xffff0000, v3
	v_fmac_f32_e32 v0, v7, v7
	v_lshlrev_b32_e32 v8, 16, v4
	v_fmac_f32_e32 v0, v3, v3
	v_and_b32_e32 v4, 0xffff0000, v4
	v_fmac_f32_e32 v0, v8, v8
	v_lshlrev_b32_e32 v9, 16, v5
	v_fmac_f32_e32 v0, v4, v4
	v_and_b32_e32 v5, 0xffff0000, v5
	v_fmac_f32_e32 v0, v9, v9
	v_fmac_f32_e32 v0, v5, v5
	global_load_dwordx4 v[2:5], v[30:31], off offset:112
	global_load_dwordx4 v[6:9], v[30:31], off offset:96
	global_load_dwordx4 v[10:13], v[30:31], off offset:80
	global_load_dwordx4 v[14:17], v[30:31], off offset:64
	global_load_dwordx4 v[32:35], v[30:31], off offset:176
	global_load_dwordx4 v[36:39], v[30:31], off offset:160
	global_load_dwordx4 v[40:43], v[30:31], off offset:144
	global_load_dwordx4 v[44:47], v[30:31], off offset:128
	global_load_dwordx4 v[48:51], v[30:31], off offset:240
	global_load_dwordx4 v[52:55], v[30:31], off offset:224
	global_load_dwordx4 v[56:59], v[30:31], off offset:208
	global_load_dwordx4 v[60:63], v[30:31], off offset:192
	global_load_dwordx4 v[64:67], v[30:31], off offset:304
	global_load_dwordx4 v[68:71], v[30:31], off offset:288
	global_load_dwordx4 v[72:75], v[30:31], off offset:272
	global_load_dwordx4 v[76:79], v[30:31], off offset:256
	global_load_dwordx4 v[110:113], v[30:31], off offset:368
	global_load_dwordx4 v[114:117], v[30:31], off offset:352
	global_load_dwordx4 v[118:121], v[30:31], off offset:336
	global_load_dwordx4 v[122:125], v[30:31], off offset:320
	s_waitcnt vmcnt(16)
; template <int D, int ROT0, int HALF, bool GAIN, bool KEEP = true>
; DI void chunk_nr(u16* p, const float* __restrict__ gain, const float* __restrict__ tab) {
;     ...
;     for (int v = 0; v < NV; ++v) {
;       const f32x8 f = bf8_to_f32(RAWV(v));
; #pragma unroll
;       for (int e = 0; e < 8; ++e) ss += f[e] * f[e];
;       if (!KEEP && (v & 7) == 7) __builtin_amdgcn_sched_barrier(0);
;     }
	v_lshlrev_b32_e32 v18, 16, v14
	v_and_b32_e32 v14, 0xffff0000, v14
	v_fmac_f32_e32 v0, v18, v18
	v_lshlrev_b32_e32 v19, 16, v15
	v_fmac_f32_e32 v0, v14, v14
	v_and_b32_e32 v15, 0xffff0000, v15
	v_fmac_f32_e32 v0, v19, v19
	v_lshlrev_b32_e32 v20, 16, v16
	v_fmac_f32_e32 v0, v15, v15
	v_and_b32_e32 v16, 0xffff0000, v16
	v_fmac_f32_e32 v0, v20, v20
	v_lshlrev_b32_e32 v21, 16, v17
	v_fmac_f32_e32 v0, v16, v16
	v_and_b32_e32 v17, 0xffff0000, v17
	v_fmac_f32_e32 v0, v21, v21
	v_fmac_f32_e32 v0, v17, v17
	v_lshlrev_b32_e32 v14, 16, v10
	v_and_b32_e32 v10, 0xffff0000, v10
	v_fmac_f32_e32 v0, v14, v14
	v_lshlrev_b32_e32 v15, 16, v11
	v_fmac_f32_e32 v0, v10, v10
	v_and_b32_e32 v11, 0xffff0000, v11
	v_fmac_f32_e32 v0, v15, v15
	v_lshlrev_b32_e32 v16, 16, v12
	v_fmac_f32_e32 v0, v11, v11
	v_and_b32_e32 v12, 0xffff0000, v12
	v_fmac_f32_e32 v0, v16, v16
	v_lshlrev_b32_e32 v17, 16, v13
	v_fmac_f32_e32 v0, v12, v12
	v_and_b32_e32 v13, 0xffff0000, v13
	v_fmac_f32_e32 v0, v17, v17
	v_fmac_f32_e32 v0, v13, v13
	v_lshlrev_b32_e32 v10, 16, v6
	v_and_b32_e32 v6, 0xffff0000, v6
	v_fmac_f32_e32 v0, v10, v10
	v_lshlrev_b32_e32 v11, 16, v7
	v_fmac_f32_e32 v0, v6, v6
	v_and_b32_e32 v7, 0xffff0000, v7
	v_fmac_f32_e32 v0, v11, v11
	v_lshlrev_b32_e32 v12, 16, v8
	v_fmac_f32_e32 v0, v7, v7
	v_and_b32_e32 v8, 0xffff0000, v8
	v_fmac_f32_e32 v0, v12, v12
	v_lshlrev_b32_e32 v13, 16, v9
	v_fmac_f32_e32 v0, v8, v8
	v_and_b32_e32 v9, 0xffff0000, v9
	v_fmac_f32_e32 v0, v13, v13
	v_fmac_f32_e32 v0, v9, v9
	v_lshlrev_b32_e32 v6, 16, v2
	v_and_b32_e32 v2, 0xffff0000, v2
	v_fmac_f32_e32 v0, v6, v6
	v_lshlrev_b32_e32 v7, 16, v3
	v_fmac_f32_e32 v0, v2, v2
	v_and_b32_e32 v3, 0xffff0000, v3
	v_fmac_f32_e32 v0, v7, v7
	v_lshlrev_b32_e32 v8, 16, v4
	v_fmac_f32_e32 v0, v3, v3
	v_and_b32_e32 v4, 0xffff0000, v4
	v_fmac_f32_e32 v0, v8, v8
	v_lshlrev_b32_e32 v9, 16, v5
	v_fmac_f32_e32 v0, v4, v4
	v_and_b32_e32 v5, 0xffff0000, v5
	v_fmac_f32_e32 v0, v9, v9
	v_fmac_f32_e32 v0, v5, v5
	s_waitcnt vmcnt(12)
	v_lshlrev_b32_e32 v18, 16, v44
	v_and_b32_e32 v44, 0xffff0000, v44
	v_fmac_f32_e32 v0, v18, v18
	v_lshlrev_b32_e32 v19, 16, v45
	v_fmac_f32_e32 v0, v44, v44
	v_and_b32_e32 v45, 0xffff0000, v45
	v_fmac_f32_e32 v0, v19, v19
	v_lshlrev_b32_e32 v20, 16, v46
	v_fmac_f32_e32 v0, v45, v45
	v_and_b32_e32 v46, 0xffff0000, v46
	v_fmac_f32_e32 v0, v20, v20
	v_lshlrev_b32_e32 v21, 16, v47
	v_fmac_f32_e32 v0, v46, v46
	v_and_b32_e32 v47, 0xffff0000, v47
	v_fmac_f32_e32 v0, v21, v21
	v_fmac_f32_e32 v0, v47, v47
	v_lshlrev_b32_e32 v44, 16, v40
	v_and_b32_e32 v40, 0xffff0000, v40
	v_fmac_f32_e32 v0, v44, v44
	v_lshlrev_b32_e32 v45, 16, v41
	v_fmac_f32_e32 v0, v40, v40
	v_and_b32_e32 v41, 0xffff0000, v41
	v_fmac_f32_e32 v0, v45, v45
	v_lshlrev_b32_e32 v46, 16, v42
	v_fmac_f32_e32 v0, v41, v41
	v_and_b32_e32 v42, 0xffff0000, v42
	v_fmac_f32_e32 v0, v46, v46
	v_lshlrev_b32_e32 v47, 16, v43
	v_fmac_f32_e32 v0, v42, v42
	v_and_b32_e32 v43, 0xffff0000, v43
	v_fmac_f32_e32 v0, v47, v47
	v_fmac_f32_e32 v0, v43, v43
	v_lshlrev_b32_e32 v40, 16, v36
	v_and_b32_e32 v36, 0xffff0000, v36
	v_fmac_f32_e32 v0, v40, v40
	v_lshlrev_b32_e32 v41, 16, v37
	v_fmac_f32_e32 v0, v36, v36
	v_and_b32_e32 v37, 0xffff0000, v37
	v_fmac_f32_e32 v0, v41, v41
	v_lshlrev_b32_e32 v42, 16, v38
	v_fmac_f32_e32 v0, v37, v37
	v_and_b32_e32 v38, 0xffff0000, v38
	v_fmac_f32_e32 v0, v42, v42
	v_lshlrev_b32_e32 v43, 16, v39
	v_fmac_f32_e32 v0, v38, v38
	v_and_b32_e32 v39, 0xffff0000, v39
	v_fmac_f32_e32 v0, v43, v43
	v_fmac_f32_e32 v0, v39, v39
	v_lshlrev_b32_e32 v36, 16, v32
	v_and_b32_e32 v32, 0xffff0000, v32
	v_fmac_f32_e32 v0, v36, v36
	v_lshlrev_b32_e32 v37, 16, v33
	v_fmac_f32_e32 v0, v32, v32
	v_and_b32_e32 v33, 0xffff0000, v33
	v_fmac_f32_e32 v0, v37, v37
	v_lshlrev_b32_e32 v38, 16, v34
	v_fmac_f32_e32 v0, v33, v33
	v_and_b32_e32 v34, 0xffff0000, v34
	v_fmac_f32_e32 v0, v38, v38
	v_lshlrev_b32_e32 v39, 16, v35
	v_fmac_f32_e32 v0, v34, v34
	v_and_b32_e32 v35, 0xffff0000, v35
	v_fmac_f32_e32 v0, v39, v39
	v_fmac_f32_e32 v0, v35, v35
	s_waitcnt vmcnt(8)
	v_lshlrev_b32_e32 v18, 16, v60
	v_and_b32_e32 v60, 0xffff0000, v60
	v_fmac_f32_e32 v0, v18, v18
	v_lshlrev_b32_e32 v19, 16, v61
	v_fmac_f32_e32 v0, v60, v60
	v_and_b32_e32 v61, 0xffff0000, v61
	v_fmac_f32_e32 v0, v19, v19
	v_lshlrev_b32_e32 v20, 16, v62
	v_fmac_f32_e32 v0, v61, v61
	v_and_b32_e32 v62, 0xffff0000, v62
	v_fmac_f32_e32 v0, v20, v20
	v_lshlrev_b32_e32 v21, 16, v63
	v_fmac_f32_e32 v0, v62, v62
	v_and_b32_e32 v63, 0xffff0000, v63
	v_fmac_f32_e32 v0, v21, v21
	v_fmac_f32_e32 v0, v63, v63
	v_lshlrev_b32_e32 v60, 16, v56
	v_and_b32_e32 v56, 0xffff0000, v56
	v_fmac_f32_e32 v0, v60, v60
	v_lshlrev_b32_e32 v61, 16, v57
	v_fmac_f32_e32 v0, v56, v56
	v_and_b32_e32 v57, 0xffff0000, v57
	v_fmac_f32_e32 v0, v61, v61
	v_lshlrev_b32_e32 v62, 16, v58
	v_fmac_f32_e32 v0, v57, v57
	v_and_b32_e32 v58, 0xffff0000, v58
	v_fmac_f32_e32 v0, v62, v62
	v_lshlrev_b32_e32 v63, 16, v59
	v_fmac_f32_e32 v0, v58, v58
	v_and_b32_e32 v59, 0xffff0000, v59
	v_fmac_f32_e32 v0, v63, v63
	v_fmac_f32_e32 v0, v59, v59
	v_lshlrev_b32_e32 v56, 16, v52
	v_and_b32_e32 v52, 0xffff0000, v52
	v_fmac_f32_e32 v0, v56, v56
	v_lshlrev_b32_e32 v57, 16, v53
	v_fmac_f32_e32 v0, v52, v52
	v_and_b32_e32 v53, 0xffff0000, v53
	v_fmac_f32_e32 v0, v57, v57
	v_lshlrev_b32_e32 v58, 16, v54
	v_fmac_f32_e32 v0, v53, v53
	v_and_b32_e32 v54, 0xffff0000, v54
	v_fmac_f32_e32 v0, v58, v58
	v_lshlrev_b32_e32 v59, 16, v55
	v_fmac_f32_e32 v0, v54, v54
	v_and_b32_e32 v55, 0xffff0000, v55
	v_fmac_f32_e32 v0, v59, v59
	v_fmac_f32_e32 v0, v55, v55
	v_lshlrev_b32_e32 v52, 16, v48
	v_and_b32_e32 v48, 0xffff0000, v48
	v_fmac_f32_e32 v0, v52, v52
	v_lshlrev_b32_e32 v53, 16, v49
	v_fmac_f32_e32 v0, v48, v48
	v_and_b32_e32 v49, 0xffff0000, v49
	v_fmac_f32_e32 v0, v53, v53
	v_lshlrev_b32_e32 v54, 16, v50
	v_fmac_f32_e32 v0, v49, v49
	v_and_b32_e32 v50, 0xffff0000, v50
	v_fmac_f32_e32 v0, v54, v54
	v_lshlrev_b32_e32 v55, 16, v51
	v_fmac_f32_e32 v0, v50, v50
	v_and_b32_e32 v51, 0xffff0000, v51
	v_fmac_f32_e32 v0, v55, v55
	v_fmac_f32_e32 v0, v51, v51
	s_waitcnt vmcnt(4)
; template <int D, int ROT0, int HALF, bool GAIN, bool KEEP = true>
; DI void chunk_nr(u16* p, const float* __restrict__ gain, const float* __restrict__ tab) {
;     ...
;     for (int v = 0; v < NV; ++v) {
;       const f32x8 f = bf8_to_f32(RAWV(v));
; #pragma unroll
;       for (int e = 0; e < 8; ++e) ss += f[e] * f[e];
;       if (!KEEP && (v & 7) == 7) __builtin_amdgcn_sched_barrier(0);
;     }
;     rstd = rsqrtf(ss * (1.0f / D) + EPS);
;     ...
;     } else if (GAIN) {
;       f32x8 x1 = bf8_to_f32(RAWV(v));
;       const f32x8 g1 = *(const f32x8*)(gain + v * 8);
; #pragma unroll
;       for (int e = 0; e < 8; ++e) x1[e] = x1[e] * rstd * g1[e];
;       *(u32x4*)(p + v * 8) = f32_to_bf8(x1);
	v_lshlrev_b32_e32 v18, 16, v76
	v_and_b32_e32 v76, 0xffff0000, v76
	v_fmac_f32_e32 v0, v18, v18
	v_lshlrev_b32_e32 v19, 16, v77
	v_fmac_f32_e32 v0, v76, v76
	v_and_b32_e32 v77, 0xffff0000, v77
	v_fmac_f32_e32 v0, v19, v19
	v_lshlrev_b32_e32 v20, 16, v78
	v_fmac_f32_e32 v0, v77, v77
	v_and_b32_e32 v78, 0xffff0000, v78
	v_fmac_f32_e32 v0, v20, v20
	v_lshlrev_b32_e32 v21, 16, v79
	v_fmac_f32_e32 v0, v78, v78
	v_and_b32_e32 v79, 0xffff0000, v79
	v_fmac_f32_e32 v0, v21, v21
	v_fmac_f32_e32 v0, v79, v79
	v_lshlrev_b32_e32 v76, 16, v72
	v_and_b32_e32 v72, 0xffff0000, v72
	v_fmac_f32_e32 v0, v76, v76
	v_lshlrev_b32_e32 v77, 16, v73
	v_fmac_f32_e32 v0, v72, v72
	v_and_b32_e32 v73, 0xffff0000, v73
	v_fmac_f32_e32 v0, v77, v77
	v_lshlrev_b32_e32 v78, 16, v74
	v_fmac_f32_e32 v0, v73, v73
	v_and_b32_e32 v74, 0xffff0000, v74
	v_fmac_f32_e32 v0, v78, v78
	v_lshlrev_b32_e32 v79, 16, v75
	v_fmac_f32_e32 v0, v74, v74
	v_and_b32_e32 v75, 0xffff0000, v75
	v_fmac_f32_e32 v0, v79, v79
	v_fmac_f32_e32 v0, v75, v75
	v_lshlrev_b32_e32 v72, 16, v68
	v_and_b32_e32 v68, 0xffff0000, v68
	v_fmac_f32_e32 v0, v72, v72
	v_lshlrev_b32_e32 v73, 16, v69
	v_fmac_f32_e32 v0, v68, v68
	v_and_b32_e32 v69, 0xffff0000, v69
	v_fmac_f32_e32 v0, v73, v73
	v_lshlrev_b32_e32 v74, 16, v70
	v_fmac_f32_e32 v0, v69, v69
	v_and_b32_e32 v70, 0xffff0000, v70
	v_fmac_f32_e32 v0, v74, v74
	v_lshlrev_b32_e32 v75, 16, v71
	v_fmac_f32_e32 v0, v70, v70
	v_and_b32_e32 v71, 0xffff0000, v71
	v_fmac_f32_e32 v0, v75, v75
	v_fmac_f32_e32 v0, v71, v71
	v_lshlrev_b32_e32 v68, 16, v64
	v_and_b32_e32 v64, 0xffff0000, v64
	v_fmac_f32_e32 v0, v68, v68
	v_lshlrev_b32_e32 v69, 16, v65
	v_fmac_f32_e32 v0, v64, v64
	v_and_b32_e32 v65, 0xffff0000, v65
	v_fmac_f32_e32 v0, v69, v69
	v_lshlrev_b32_e32 v70, 16, v66
	v_fmac_f32_e32 v0, v65, v65
	v_and_b32_e32 v66, 0xffff0000, v66
	v_fmac_f32_e32 v0, v70, v70
	v_lshlrev_b32_e32 v71, 16, v67
	v_fmac_f32_e32 v0, v66, v66
	v_and_b32_e32 v67, 0xffff0000, v67
	v_fmac_f32_e32 v0, v71, v71
	v_fmac_f32_e32 v0, v67, v67
	s_waitcnt vmcnt(0)
	v_lshlrev_b32_e32 v18, 16, v122
	v_and_b32_e32 v122, 0xffff0000, v122
	v_fmac_f32_e32 v0, v18, v18
	v_lshlrev_b32_e32 v19, 16, v123
	v_fmac_f32_e32 v0, v122, v122
	v_and_b32_e32 v123, 0xffff0000, v123
	v_fmac_f32_e32 v0, v19, v19
	v_lshlrev_b32_e32 v20, 16, v124
	v_fmac_f32_e32 v0, v123, v123
	v_and_b32_e32 v124, 0xffff0000, v124
	v_fmac_f32_e32 v0, v20, v20
	v_lshlrev_b32_e32 v21, 16, v125
	v_fmac_f32_e32 v0, v124, v124
	v_and_b32_e32 v125, 0xffff0000, v125
	v_fmac_f32_e32 v0, v21, v21
	v_fmac_f32_e32 v0, v125, v125
	v_lshlrev_b32_e32 v122, 16, v118
	v_and_b32_e32 v118, 0xffff0000, v118
	v_fmac_f32_e32 v0, v122, v122
	v_lshlrev_b32_e32 v123, 16, v119
	v_fmac_f32_e32 v0, v118, v118
	v_and_b32_e32 v119, 0xffff0000, v119
	v_fmac_f32_e32 v0, v123, v123
	v_lshlrev_b32_e32 v124, 16, v120
	v_fmac_f32_e32 v0, v119, v119
	v_and_b32_e32 v120, 0xffff0000, v120
	v_fmac_f32_e32 v0, v124, v124
	v_lshlrev_b32_e32 v125, 16, v121
	v_fmac_f32_e32 v0, v120, v120
	v_and_b32_e32 v121, 0xffff0000, v121
	v_fmac_f32_e32 v0, v125, v125
	v_fmac_f32_e32 v0, v121, v121
	v_lshlrev_b32_e32 v118, 16, v114
	v_and_b32_e32 v114, 0xffff0000, v114
	v_fmac_f32_e32 v0, v118, v118
	v_lshlrev_b32_e32 v119, 16, v115
	v_fmac_f32_e32 v0, v114, v114
	v_and_b32_e32 v115, 0xffff0000, v115
	v_fmac_f32_e32 v0, v119, v119
	v_lshlrev_b32_e32 v120, 16, v116
	v_fmac_f32_e32 v0, v115, v115
	v_and_b32_e32 v116, 0xffff0000, v116
	v_fmac_f32_e32 v0, v120, v120
	v_and_b32_e32 v114, 0xffff0000, v117
	v_lshlrev_b32_e32 v115, 16, v117
	v_fmac_f32_e32 v0, v116, v116
	v_pk_mul_f32 v[114:115], v[114:115], v[114:115]
	s_nop 0
	v_add_f32_e32 v0, v115, v0
	v_add_f32_e32 v0, v114, v0
	v_and_b32_e32 v114, 0xffff0000, v110
	v_lshlrev_b32_e32 v115, 16, v110
	v_pk_mul_f32 v[114:115], v[114:115], v[114:115]
	v_and_b32_e32 v110, 0xffff0000, v111
	v_add_f32_e32 v0, v115, v0
	v_lshlrev_b32_e32 v111, 16, v111
	v_add_f32_e32 v0, v114, v0
	v_pk_mul_f32 v[110:111], v[110:111], v[110:111]
	s_nop 0
	v_add_f32_e32 v0, v111, v0
	v_add_f32_e32 v0, v110, v0
	v_and_b32_e32 v110, 0xffff0000, v112
	v_lshlrev_b32_e32 v111, 16, v112
	v_pk_mul_f32 v[110:111], v[110:111], v[110:111]
	s_nop 0
	v_add_f32_e32 v0, v111, v0
	v_add_f32_e32 v0, v110, v0
	v_and_b32_e32 v110, 0xffff0000, v113
	v_lshlrev_b32_e32 v111, 16, v113
	v_pk_mul_f32 v[110:111], v[110:111], v[110:111]
	s_nop 0
	v_add_f32_e32 v0, v111, v0
	v_add_f32_e32 v0, v110, v0
	v_fmamk_f32 v0, v0, 0x3baaaaab, v189
	v_cmp_gt_f32_e32 vcc, s55, v0
	v_mul_f32_e32 v2, 0x4b800000, v0
	s_nop 0
	v_cndmask_b32_e32 v0, v0, v2, vcc
	v_rsq_f32_e32 v0, v0
	s_nop 0
	v_mul_f32_e32 v2, 0x45800000, v0
	v_cndmask_b32_e32 v0, v0, v2, vcc
	global_load_dwordx4 v[2:5], v[30:31], off offset:48
	global_load_dwordx4 v[6:9], v[30:31], off offset:32
	global_load_dwordx4 v[14:17], v[30:31], off offset:16
	global_load_dwordx4 v[22:25], v[30:31], off
	global_load_dwordx4 v[10:13], v1, s[4:5] offset:48
	global_load_dwordx4 v[18:21], v1, s[4:5] offset:32
	global_load_dwordx4 v[32:35], v1, s[4:5] offset:16
	global_load_dwordx4 v[36:39], v1, s[4:5]
	s_waitcnt vmcnt(0)
; template <int D, int ROT0, int HALF, bool GAIN, bool KEEP = true>
; DI void chunk_nr(u16* p, const float* __restrict__ gain, const float* __restrict__ tab) {
;     ...
;     } else if (GAIN) {
;       f32x8 x1 = bf8_to_f32(RAWV(v));
;       const f32x8 g1 = *(const f32x8*)(gain + v * 8);
; #pragma unroll
;       for (int e = 0; e < 8; ++e) x1[e] = x1[e] * rstd * g1[e];
;       *(u32x4*)(p + v * 8) = f32_to_bf8(x1);
;     }
	v_lshlrev_b32_e32 v41, 16, v23
	v_lshlrev_b32_e32 v40, 16, v22
	v_and_b32_e32 v23, 0xffff0000, v23
	v_and_b32_e32 v22, 0xffff0000, v22
	v_mov_b32_e32 v42, v36
	v_mov_b32_e32 v43, v38
	v_pk_mul_f32 v[22:23], v[0:1], v[22:23] op_sel_hi:[0,1]
	v_mov_b32_e32 v38, v37
	v_lshlrev_b32_e32 v37, 16, v25
	v_lshlrev_b32_e32 v36, 16, v24
	v_and_b32_e32 v25, 0xffff0000, v25
	v_and_b32_e32 v24, 0xffff0000, v24
	v_pk_mul_f32 v[22:23], v[38:39], v[22:23]
	v_mov_b32_e32 v39, v34
	v_pk_mul_f32 v[24:25], v[0:1], v[24:25] op_sel_hi:[0,1]
	v_mov_b32_e32 v34, v33
	v_pk_mul_f32 v[40:41], v[0:1], v[40:41] op_sel_hi:[0,1]
	v_pk_mul_f32 v[36:37], v[0:1], v[36:37] op_sel_hi:[0,1]
	v_mov_b32_e32 v38, v32
	v_pk_mul_f32 v[24:25], v[34:35], v[24:25]
	v_pk_mul_f32 v[40:41], v[42:43], v[40:41]
	v_pk_mul_f32 v[36:37], v[38:39], v[36:37]
	v_bfe_u32 v32, v25, 16, 1
	v_bfe_u32 v33, v24, 16, 1
	v_bfe_u32 v34, v23, 16, 1
	v_bfe_u32 v35, v22, 16, 1
	v_add3_u32 v22, v22, v35, s54
	v_add3_u32 v23, v23, v34, s54
	v_add3_u32 v24, v24, v33, s54
	v_add3_u32 v25, v25, v32, s54
	v_bfe_u32 v32, v40, 16, 1
	v_bfe_u32 v33, v41, 16, 1
	v_bfe_u32 v34, v36, 16, 1
	v_bfe_u32 v35, v37, 16, 1
	v_add3_u32 v35, v37, v35, s54
	v_add3_u32 v34, v36, v34, s54
	v_add3_u32 v33, v41, v33, s54
	v_add3_u32 v32, v40, v32, s54
	v_lshrrev_b32_e32 v32, 16, v32
	v_lshrrev_b32_e32 v33, 16, v33
	v_lshrrev_b32_e32 v34, 16, v34
	v_lshrrev_b32_e32 v35, 16, v35
	v_and_or_b32 v25, v25, s56, v35
	v_and_or_b32 v24, v24, s56, v34
	v_and_or_b32 v23, v23, s56, v33
	v_and_or_b32 v22, v22, s56, v32
	global_store_dwordx4 v[30:31], v[22:25], off
	v_lshlrev_b32_e32 v33, 16, v7
	v_lshlrev_b32_e32 v32, 16, v6
	v_lshlrev_b32_e32 v23, 16, v15
	v_lshlrev_b32_e32 v22, 16, v14
	v_and_b32_e32 v15, 0xffff0000, v15
	v_and_b32_e32 v14, 0xffff0000, v14
	v_mov_b32_e32 v24, v18
	v_mov_b32_e32 v25, v20
	v_pk_mul_f32 v[14:15], v[0:1], v[14:15] op_sel_hi:[0,1]
	v_mov_b32_e32 v20, v19
	v_lshlrev_b32_e32 v19, 16, v17
	v_lshlrev_b32_e32 v18, 16, v16
	v_and_b32_e32 v17, 0xffff0000, v17
	v_and_b32_e32 v16, 0xffff0000, v16
	v_pk_mul_f32 v[14:15], v[20:21], v[14:15]
	v_mov_b32_e32 v21, v12
	v_pk_mul_f32 v[16:17], v[0:1], v[16:17] op_sel_hi:[0,1]
	v_mov_b32_e32 v12, v11
	v_pk_mul_f32 v[22:23], v[0:1], v[22:23] op_sel_hi:[0,1]
	v_pk_mul_f32 v[18:19], v[0:1], v[18:19] op_sel_hi:[0,1]
	v_mov_b32_e32 v20, v10
	v_pk_mul_f32 v[10:11], v[12:13], v[16:17]
	v_pk_mul_f32 v[22:23], v[24:25], v[22:23]
	v_pk_mul_f32 v[18:19], v[20:21], v[18:19]
	v_bfe_u32 v12, v11, 16, 1
	v_bfe_u32 v13, v10, 16, 1
	v_bfe_u32 v16, v15, 16, 1
	v_bfe_u32 v17, v14, 16, 1
	v_add3_u32 v14, v14, v17, s54
	v_add3_u32 v15, v15, v16, s54
	v_add3_u32 v10, v10, v13, s54
	v_add3_u32 v11, v11, v12, s54
	v_bfe_u32 v12, v22, 16, 1
	v_bfe_u32 v13, v23, 16, 1
	v_bfe_u32 v16, v18, 16, 1
	v_bfe_u32 v17, v19, 16, 1
	v_add3_u32 v17, v19, v17, s54
	v_add3_u32 v16, v18, v16, s54
	v_add3_u32 v13, v23, v13, s54
	v_add3_u32 v12, v22, v12, s54
	v_lshrrev_b32_e32 v18, 16, v12
	v_lshrrev_b32_e32 v19, 16, v13
	v_lshrrev_b32_e32 v12, 16, v16
	v_lshrrev_b32_e32 v13, 16, v17
	v_and_or_b32 v13, v11, s56, v13
	v_and_or_b32 v12, v10, s56, v12
	v_and_or_b32 v11, v15, s56, v19
	v_and_or_b32 v10, v14, s56, v18
	global_store_dwordx4 v[30:31], v[10:13], off offset:16
	global_load_dwordx4 v[10:13], v1, s[4:5] offset:112
	s_nop 0
	global_load_dwordx4 v[14:17], v1, s[4:5] offset:96
	global_load_dwordx4 v[18:21], v1, s[4:5] offset:80
	global_load_dwordx4 v[22:25], v1, s[4:5] offset:64
	v_and_b32_e32 v7, 0xffff0000, v7
	v_and_b32_e32 v6, 0xffff0000, v6
	v_pk_mul_f32 v[6:7], v[0:1], v[6:7] op_sel_hi:[0,1]
	v_pk_mul_f32 v[32:33], v[0:1], v[32:33] op_sel_hi:[0,1]
	s_waitcnt vmcnt(0)
	v_mov_b32_e32 v34, v22
	v_mov_b32_e32 v35, v24
	v_mov_b32_e32 v24, v23
	v_lshlrev_b32_e32 v23, 16, v9
	v_lshlrev_b32_e32 v22, 16, v8
	v_and_b32_e32 v9, 0xffff0000, v9
	v_and_b32_e32 v8, 0xffff0000, v8
	v_pk_mul_f32 v[6:7], v[24:25], v[6:7]
	v_mov_b32_e32 v25, v20
	v_pk_mul_f32 v[8:9], v[0:1], v[8:9] op_sel_hi:[0,1]
	v_mov_b32_e32 v20, v19
	v_pk_mul_f32 v[22:23], v[0:1], v[22:23] op_sel_hi:[0,1]
	v_mov_b32_e32 v24, v18
	v_pk_mul_f32 v[8:9], v[20:21], v[8:9]
	v_pk_mul_f32 v[32:33], v[34:35], v[32:33]
	v_pk_mul_f32 v[22:23], v[24:25], v[22:23]
	v_bfe_u32 v18, v9, 16, 1
	v_bfe_u32 v19, v8, 16, 1
	v_bfe_u32 v20, v7, 16, 1
	v_bfe_u32 v21, v6, 16, 1
	v_add3_u32 v6, v6, v21, s54
	v_add3_u32 v7, v7, v20, s54
	v_add3_u32 v8, v8, v19, s54
	v_add3_u32 v9, v9, v18, s54
	v_bfe_u32 v18, v32, 16, 1
	v_bfe_u32 v19, v33, 16, 1
	v_bfe_u32 v20, v22, 16, 1
	v_bfe_u32 v21, v23, 16, 1
	v_add3_u32 v21, v23, v21, s54
	v_add3_u32 v20, v22, v20, s54
	v_add3_u32 v19, v33, v19, s54
	v_add3_u32 v18, v32, v18, s54
	v_lshrrev_b32_e32 v18, 16, v18
	v_lshrrev_b32_e32 v19, 16, v19
	v_lshrrev_b32_e32 v20, 16, v20
	v_lshrrev_b32_e32 v21, 16, v21
	v_and_or_b32 v9, v9, s56, v21
	v_and_or_b32 v8, v8, s56, v20
	v_and_or_b32 v7, v7, s56, v19
	v_and_or_b32 v6, v6, s56, v18
	global_store_dwordx4 v[30:31], v[6:9], off offset:32
	s_nop 1
	v_lshlrev_b32_e32 v7, 16, v3
	v_lshlrev_b32_e32 v6, 16, v2
	v_and_b32_e32 v9, 0xffff0000, v3
	v_and_b32_e32 v8, 0xffff0000, v2
	v_pk_mul_f32 v[2:3], v[0:1], v[6:7] op_sel_hi:[0,1]
	v_mov_b32_e32 v6, v14
	v_mov_b32_e32 v7, v16
	v_pk_mul_f32 v[2:3], v[6:7], v[2:3]
	v_pk_mul_f32 v[6:7], v[0:1], v[8:9] op_sel_hi:[0,1]
	v_lshlrev_b32_e32 v9, 16, v5
	v_lshlrev_b32_e32 v8, 16, v4
	v_and_b32_e32 v5, 0xffff0000, v5
	v_and_b32_e32 v4, 0xffff0000, v4
	v_mov_b32_e32 v16, v15
	v_mov_b32_e32 v15, v12
	v_pk_mul_f32 v[4:5], v[0:1], v[4:5] op_sel_hi:[0,1]
	v_mov_b32_e32 v12, v11
	v_pk_mul_f32 v[6:7], v[16:17], v[6:7]
	v_pk_mul_f32 v[8:9], v[0:1], v[8:9] op_sel_hi:[0,1]
	v_mov_b32_e32 v14, v10
	v_pk_mul_f32 v[4:5], v[12:13], v[4:5]
	v_pk_mul_f32 v[8:9], v[14:15], v[8:9]
	v_bfe_u32 v10, v5, 16, 1
	v_bfe_u32 v11, v4, 16, 1
	v_bfe_u32 v12, v7, 16, 1
	v_bfe_u32 v13, v6, 16, 1
	v_add3_u32 v6, v6, v13, s54
	v_add3_u32 v7, v7, v12, s54
	v_add3_u32 v4, v4, v11, s54
	v_add3_u32 v5, v5, v10, s54
	v_bfe_u32 v10, v2, 16, 1
	v_bfe_u32 v11, v3, 16, 1
	v_bfe_u32 v12, v8, 16, 1
	v_bfe_u32 v13, v9, 16, 1
	v_add3_u32 v9, v9, v13, s54
	v_add3_u32 v8, v8, v12, s54
	v_add3_u32 v3, v3, v11, s54
	v_add3_u32 v2, v2, v10, s54
	v_lshrrev_b32_e32 v2, 16, v2
	v_lshrrev_b32_e32 v3, 16, v3
	v_lshrrev_b32_e32 v8, 16, v8
	v_lshrrev_b32_e32 v9, 16, v9
	v_and_or_b32 v5, v5, s56, v9
	v_and_or_b32 v4, v4, s56, v8
	v_and_or_b32 v3, v7, s56, v3
	v_and_or_b32 v2, v6, s56, v2
	global_store_dwordx4 v[30:31], v[2:5], off offset:48
	global_load_dwordx4 v[2:5], v[30:31], off offset:112
	s_nop 0
	global_load_dwordx4 v[6:9], v[30:31], off offset:96
	global_load_dwordx4 v[14:17], v[30:31], off offset:80
	global_load_dwordx4 v[22:25], v[30:31], off offset:64
	global_load_dwordx4 v[10:13], v1, s[4:5] offset:176
	global_load_dwordx4 v[18:21], v1, s[4:5] offset:160
	global_load_dwordx4 v[32:35], v1, s[4:5] offset:144
	global_load_dwordx4 v[36:39], v1, s[4:5] offset:128
	s_waitcnt vmcnt(0)
; template <int D, int ROT0, int HALF, bool GAIN, bool KEEP = true>
; DI void chunk_nr(u16* p, const float* __restrict__ gain, const float* __restrict__ tab) {
;     ...
;     } else if (GAIN) {
;       f32x8 x1 = bf8_to_f32(RAWV(v));
;       const f32x8 g1 = *(const f32x8*)(gain + v * 8);
; #pragma unroll
;       for (int e = 0; e < 8; ++e) x1[e] = x1[e] * rstd * g1[e];
;       *(u32x4*)(p + v * 8) = f32_to_bf8(x1);
;     }
	v_lshlrev_b32_e32 v41, 16, v23
	v_lshlrev_b32_e32 v40, 16, v22
	v_and_b32_e32 v23, 0xffff0000, v23
	v_and_b32_e32 v22, 0xffff0000, v22
	v_mov_b32_e32 v42, v36
	v_mov_b32_e32 v43, v38
	v_pk_mul_f32 v[22:23], v[0:1], v[22:23] op_sel_hi:[0,1]
	v_mov_b32_e32 v38, v37
	v_lshlrev_b32_e32 v37, 16, v25
	v_lshlrev_b32_e32 v36, 16, v24
	v_and_b32_e32 v25, 0xffff0000, v25
	v_and_b32_e32 v24, 0xffff0000, v24
	v_pk_mul_f32 v[22:23], v[38:39], v[22:23]
	v_mov_b32_e32 v39, v34
	v_pk_mul_f32 v[24:25], v[0:1], v[24:25] op_sel_hi:[0,1]
	v_mov_b32_e32 v34, v33
	v_pk_mul_f32 v[40:41], v[0:1], v[40:41] op_sel_hi:[0,1]
	v_pk_mul_f32 v[36:37], v[0:1], v[36:37] op_sel_hi:[0,1]
	v_mov_b32_e32 v38, v32
	v_pk_mul_f32 v[24:25], v[34:35], v[24:25]
	v_pk_mul_f32 v[40:41], v[42:43], v[40:41]
	v_pk_mul_f32 v[36:37], v[38:39], v[36:37]
	v_bfe_u32 v32, v25, 16, 1
	v_bfe_u32 v33, v24, 16, 1
	v_bfe_u32 v34, v23, 16, 1
	v_bfe_u32 v35, v22, 16, 1
	v_add3_u32 v22, v22, v35, s54
	v_add3_u32 v23, v23, v34, s54
	v_add3_u32 v24, v24, v33, s54
	v_add3_u32 v25, v25, v32, s54
	v_bfe_u32 v32, v40, 16, 1
	v_bfe_u32 v33, v41, 16, 1
	v_bfe_u32 v34, v36, 16, 1
	v_bfe_u32 v35, v37, 16, 1
	v_add3_u32 v35, v37, v35, s54
	v_add3_u32 v34, v36, v34, s54
	v_add3_u32 v33, v41, v33, s54
	v_add3_u32 v32, v40, v32, s54
	v_lshrrev_b32_e32 v32, 16, v32
	v_lshrrev_b32_e32 v33, 16, v33
	v_lshrrev_b32_e32 v34, 16, v34
	v_lshrrev_b32_e32 v35, 16, v35
	v_and_or_b32 v25, v25, s56, v35
	v_and_or_b32 v24, v24, s56, v34
	v_and_or_b32 v23, v23, s56, v33
	v_and_or_b32 v22, v22, s56, v32
	global_store_dwordx4 v[30:31], v[22:25], off offset:64
	v_lshlrev_b32_e32 v33, 16, v7
	v_lshlrev_b32_e32 v32, 16, v6
	v_lshlrev_b32_e32 v23, 16, v15
	v_lshlrev_b32_e32 v22, 16, v14
	v_and_b32_e32 v25, 0xffff0000, v15
	v_and_b32_e32 v24, 0xffff0000, v14
	v_pk_mul_f32 v[14:15], v[0:1], v[22:23] op_sel_hi:[0,1]
	v_mov_b32_e32 v22, v18
	v_mov_b32_e32 v23, v20
	v_pk_mul_f32 v[14:15], v[22:23], v[14:15]
	v_pk_mul_f32 v[22:23], v[0:1], v[24:25] op_sel_hi:[0,1]
	v_mov_b32_e32 v20, v19
	v_pk_mul_f32 v[18:19], v[20:21], v[22:23]
	v_lshlrev_b32_e32 v21, 16, v17
	v_lshlrev_b32_e32 v20, 16, v16
	v_and_b32_e32 v17, 0xffff0000, v17
	v_and_b32_e32 v16, 0xffff0000, v16
	v_mov_b32_e32 v23, v12
	v_pk_mul_f32 v[16:17], v[0:1], v[16:17] op_sel_hi:[0,1]
	v_mov_b32_e32 v12, v11
	v_pk_mul_f32 v[20:21], v[0:1], v[20:21] op_sel_hi:[0,1]
	v_mov_b32_e32 v22, v10
	v_pk_mul_f32 v[10:11], v[12:13], v[16:17]
	v_pk_mul_f32 v[20:21], v[22:23], v[20:21]
	v_bfe_u32 v12, v11, 16, 1
	v_bfe_u32 v13, v10, 16, 1
	v_bfe_u32 v16, v19, 16, 1
	v_bfe_u32 v17, v18, 16, 1
	v_add3_u32 v17, v18, v17, s54
	v_add3_u32 v16, v19, v16, s54
	v_add3_u32 v10, v10, v13, s54
	v_add3_u32 v11, v11, v12, s54
	v_bfe_u32 v12, v14, 16, 1
	v_bfe_u32 v13, v15, 16, 1
	v_bfe_u32 v18, v20, 16, 1
	v_bfe_u32 v19, v21, 16, 1
	v_add3_u32 v19, v21, v19, s54
	v_add3_u32 v18, v20, v18, s54
	v_add3_u32 v13, v15, v13, s54
	v_add3_u32 v12, v14, v12, s54
	v_lshrrev_b32_e32 v14, 16, v12
	v_lshrrev_b32_e32 v15, 16, v13
	v_lshrrev_b32_e32 v12, 16, v18
	v_lshrrev_b32_e32 v13, 16, v19
	v_and_or_b32 v13, v11, s56, v13
	v_and_or_b32 v12, v10, s56, v12
	v_and_or_b32 v11, v16, s56, v15
	v_and_or_b32 v10, v17, s56, v14
	global_store_dwordx4 v[30:31], v[10:13], off offset:80
	global_load_dwordx4 v[10:13], v1, s[4:5] offset:240
	s_nop 0
	global_load_dwordx4 v[14:17], v1, s[4:5] offset:224
	global_load_dwordx4 v[18:21], v1, s[4:5] offset:208
	global_load_dwordx4 v[22:25], v1, s[4:5] offset:192
	v_and_b32_e32 v7, 0xffff0000, v7
	v_and_b32_e32 v6, 0xffff0000, v6
	v_pk_mul_f32 v[6:7], v[0:1], v[6:7] op_sel_hi:[0,1]
	v_pk_mul_f32 v[32:33], v[0:1], v[32:33] op_sel_hi:[0,1]
	s_waitcnt vmcnt(0)
	v_mov_b32_e32 v34, v22
	v_mov_b32_e32 v35, v24
	v_mov_b32_e32 v24, v23
	v_lshlrev_b32_e32 v23, 16, v9
	v_lshlrev_b32_e32 v22, 16, v8
	v_and_b32_e32 v9, 0xffff0000, v9
	v_and_b32_e32 v8, 0xffff0000, v8
	v_pk_mul_f32 v[6:7], v[24:25], v[6:7]
	v_mov_b32_e32 v25, v20
	v_pk_mul_f32 v[8:9], v[0:1], v[8:9] op_sel_hi:[0,1]
	v_mov_b32_e32 v20, v19
	v_pk_mul_f32 v[22:23], v[0:1], v[22:23] op_sel_hi:[0,1]
	v_mov_b32_e32 v24, v18
	v_pk_mul_f32 v[8:9], v[20:21], v[8:9]
	v_pk_mul_f32 v[32:33], v[34:35], v[32:33]
	v_pk_mul_f32 v[22:23], v[24:25], v[22:23]
	v_bfe_u32 v18, v9, 16, 1
	v_bfe_u32 v19, v8, 16, 1
	v_bfe_u32 v20, v7, 16, 1
	v_bfe_u32 v21, v6, 16, 1
	v_add3_u32 v6, v6, v21, s54
	v_add3_u32 v7, v7, v20, s54
	v_add3_u32 v8, v8, v19, s54
	v_add3_u32 v9, v9, v18, s54
	v_bfe_u32 v18, v32, 16, 1
	v_bfe_u32 v19, v33, 16, 1
	v_bfe_u32 v20, v22, 16, 1
	v_bfe_u32 v21, v23, 16, 1
	v_add3_u32 v21, v23, v21, s54
	v_add3_u32 v20, v22, v20, s54
	v_add3_u32 v19, v33, v19, s54
	v_add3_u32 v18, v32, v18, s54
	v_lshrrev_b32_e32 v18, 16, v18
	v_lshrrev_b32_e32 v19, 16, v19
	v_lshrrev_b32_e32 v20, 16, v20
	v_lshrrev_b32_e32 v21, 16, v21
	v_and_or_b32 v9, v9, s56, v21
	v_and_or_b32 v8, v8, s56, v20
	v_and_or_b32 v7, v7, s56, v19
	v_and_or_b32 v6, v6, s56, v18
	global_store_dwordx4 v[30:31], v[6:9], off offset:96
	s_nop 1
	v_lshlrev_b32_e32 v7, 16, v3
	v_lshlrev_b32_e32 v6, 16, v2
	v_and_b32_e32 v9, 0xffff0000, v3
	v_and_b32_e32 v8, 0xffff0000, v2
	v_pk_mul_f32 v[2:3], v[0:1], v[6:7] op_sel_hi:[0,1]
	v_mov_b32_e32 v6, v14
	v_mov_b32_e32 v7, v16
	v_pk_mul_f32 v[2:3], v[6:7], v[2:3]
	v_pk_mul_f32 v[6:7], v[0:1], v[8:9] op_sel_hi:[0,1]
	v_lshlrev_b32_e32 v9, 16, v5
	v_lshlrev_b32_e32 v8, 16, v4
	v_and_b32_e32 v5, 0xffff0000, v5
	v_and_b32_e32 v4, 0xffff0000, v4
	v_mov_b32_e32 v16, v15
	v_mov_b32_e32 v15, v12
	v_pk_mul_f32 v[4:5], v[0:1], v[4:5] op_sel_hi:[0,1]
	v_mov_b32_e32 v12, v11
	v_pk_mul_f32 v[6:7], v[16:17], v[6:7]
	v_pk_mul_f32 v[8:9], v[0:1], v[8:9] op_sel_hi:[0,1]
	v_mov_b32_e32 v14, v10
	v_pk_mul_f32 v[4:5], v[12:13], v[4:5]
	v_pk_mul_f32 v[8:9], v[14:15], v[8:9]
	v_bfe_u32 v10, v5, 16, 1
	v_bfe_u32 v11, v4, 16, 1
	v_bfe_u32 v12, v7, 16, 1
	v_bfe_u32 v13, v6, 16, 1
	v_add3_u32 v6, v6, v13, s54
	v_add3_u32 v7, v7, v12, s54
	v_add3_u32 v4, v4, v11, s54
	v_add3_u32 v5, v5, v10, s54
	v_bfe_u32 v10, v2, 16, 1
	v_bfe_u32 v11, v3, 16, 1
	v_bfe_u32 v12, v8, 16, 1
	v_bfe_u32 v13, v9, 16, 1
	v_add3_u32 v9, v9, v13, s54
	v_add3_u32 v8, v8, v12, s54
	v_add3_u32 v3, v3, v11, s54
	v_add3_u32 v2, v2, v10, s54
	v_lshrrev_b32_e32 v2, 16, v2
	v_lshrrev_b32_e32 v3, 16, v3
	v_lshrrev_b32_e32 v8, 16, v8
	v_lshrrev_b32_e32 v9, 16, v9
	v_and_or_b32 v5, v5, s56, v9
	v_and_or_b32 v4, v4, s56, v8
	v_and_or_b32 v3, v7, s56, v3
	v_and_or_b32 v2, v6, s56, v2
	global_store_dwordx4 v[30:31], v[2:5], off offset:112
	global_load_dwordx4 v[2:5], v[30:31], off offset:176
	s_nop 0
	global_load_dwordx4 v[6:9], v[30:31], off offset:160
	global_load_dwordx4 v[14:17], v[30:31], off offset:144
	global_load_dwordx4 v[22:25], v[30:31], off offset:128
	global_load_dwordx4 v[10:13], v1, s[4:5] offset:304
	global_load_dwordx4 v[18:21], v1, s[4:5] offset:288
	global_load_dwordx4 v[32:35], v1, s[4:5] offset:272
	global_load_dwordx4 v[36:39], v1, s[4:5] offset:256
	s_waitcnt vmcnt(0)
; template <int D, int ROT0, int HALF, bool GAIN, bool KEEP = true>
; DI void chunk_nr(u16* p, const float* __restrict__ gain, const float* __restrict__ tab) {
;     ...
;     } else if (GAIN) {
;       f32x8 x1 = bf8_to_f32(RAWV(v));
;       const f32x8 g1 = *(const f32x8*)(gain + v * 8);
; #pragma unroll
;       for (int e = 0; e < 8; ++e) x1[e] = x1[e] * rstd * g1[e];
;       *(u32x4*)(p + v * 8) = f32_to_bf8(x1);
;     }
	v_lshlrev_b32_e32 v41, 16, v23
	v_lshlrev_b32_e32 v40, 16, v22
	v_and_b32_e32 v23, 0xffff0000, v23
	v_and_b32_e32 v22, 0xffff0000, v22
	v_mov_b32_e32 v42, v36
	v_mov_b32_e32 v43, v38
	v_pk_mul_f32 v[22:23], v[0:1], v[22:23] op_sel_hi:[0,1]
	v_mov_b32_e32 v38, v37
	v_lshlrev_b32_e32 v37, 16, v25
	v_lshlrev_b32_e32 v36, 16, v24
	v_and_b32_e32 v25, 0xffff0000, v25
	v_and_b32_e32 v24, 0xffff0000, v24
	v_pk_mul_f32 v[22:23], v[38:39], v[22:23]
	v_mov_b32_e32 v39, v34
	v_pk_mul_f32 v[24:25], v[0:1], v[24:25] op_sel_hi:[0,1]
	v_mov_b32_e32 v34, v33
	v_pk_mul_f32 v[40:41], v[0:1], v[40:41] op_sel_hi:[0,1]
	v_pk_mul_f32 v[36:37], v[0:1], v[36:37] op_sel_hi:[0,1]
	v_mov_b32_e32 v38, v32
	v_pk_mul_f32 v[24:25], v[34:35], v[24:25]
	v_pk_mul_f32 v[40:41], v[42:43], v[40:41]
	v_pk_mul_f32 v[36:37], v[38:39], v[36:37]
	v_bfe_u32 v32, v25, 16, 1
	v_bfe_u32 v33, v24, 16, 1
	v_bfe_u32 v34, v23, 16, 1
	v_bfe_u32 v35, v22, 16, 1
	v_add3_u32 v22, v22, v35, s54
	v_add3_u32 v23, v23, v34, s54
	v_add3_u32 v24, v24, v33, s54
	v_add3_u32 v25, v25, v32, s54
	v_bfe_u32 v32, v40, 16, 1
	v_bfe_u32 v33, v41, 16, 1
	v_bfe_u32 v34, v36, 16, 1
	v_bfe_u32 v35, v37, 16, 1
	v_add3_u32 v35, v37, v35, s54
	v_add3_u32 v34, v36, v34, s54
	v_add3_u32 v33, v41, v33, s54
	v_add3_u32 v32, v40, v32, s54
	v_lshrrev_b32_e32 v32, 16, v32
	v_lshrrev_b32_e32 v33, 16, v33
	v_lshrrev_b32_e32 v34, 16, v34
	v_lshrrev_b32_e32 v35, 16, v35
	v_and_or_b32 v25, v25, s56, v35
	v_and_or_b32 v24, v24, s56, v34
	v_and_or_b32 v23, v23, s56, v33
	v_and_or_b32 v22, v22, s56, v32
	global_store_dwordx4 v[30:31], v[22:25], off offset:128
	v_lshlrev_b32_e32 v33, 16, v7
	v_lshlrev_b32_e32 v32, 16, v6
	v_lshlrev_b32_e32 v23, 16, v15
	v_lshlrev_b32_e32 v22, 16, v14
	v_and_b32_e32 v25, 0xffff0000, v15
	v_and_b32_e32 v24, 0xffff0000, v14
	v_pk_mul_f32 v[14:15], v[0:1], v[22:23] op_sel_hi:[0,1]
	v_mov_b32_e32 v22, v18
	v_mov_b32_e32 v23, v20
	v_pk_mul_f32 v[14:15], v[22:23], v[14:15]
	v_pk_mul_f32 v[22:23], v[0:1], v[24:25] op_sel_hi:[0,1]
	v_mov_b32_e32 v20, v19
	v_pk_mul_f32 v[18:19], v[20:21], v[22:23]
	v_lshlrev_b32_e32 v21, 16, v17
	v_lshlrev_b32_e32 v20, 16, v16
	v_and_b32_e32 v17, 0xffff0000, v17
	v_and_b32_e32 v16, 0xffff0000, v16
	v_mov_b32_e32 v23, v12
	v_pk_mul_f32 v[16:17], v[0:1], v[16:17] op_sel_hi:[0,1]
	v_mov_b32_e32 v12, v11
	v_pk_mul_f32 v[20:21], v[0:1], v[20:21] op_sel_hi:[0,1]
	v_mov_b32_e32 v22, v10
	v_pk_mul_f32 v[10:11], v[12:13], v[16:17]
	v_pk_mul_f32 v[20:21], v[22:23], v[20:21]
	v_bfe_u32 v12, v11, 16, 1
	v_bfe_u32 v13, v10, 16, 1
	v_bfe_u32 v16, v19, 16, 1
	v_bfe_u32 v17, v18, 16, 1
	v_add3_u32 v17, v18, v17, s54
	v_add3_u32 v16, v19, v16, s54
	v_add3_u32 v10, v10, v13, s54
	v_add3_u32 v11, v11, v12, s54
	v_bfe_u32 v12, v14, 16, 1
	v_bfe_u32 v13, v15, 16, 1
	v_bfe_u32 v18, v20, 16, 1
	v_bfe_u32 v19, v21, 16, 1
	v_add3_u32 v19, v21, v19, s54
	v_add3_u32 v18, v20, v18, s54
	v_add3_u32 v13, v15, v13, s54
	v_add3_u32 v12, v14, v12, s54
	v_lshrrev_b32_e32 v14, 16, v12
	v_lshrrev_b32_e32 v15, 16, v13
	v_lshrrev_b32_e32 v12, 16, v18
	v_lshrrev_b32_e32 v13, 16, v19
	v_and_or_b32 v13, v11, s56, v13
	v_and_or_b32 v12, v10, s56, v12
	v_and_or_b32 v11, v16, s56, v15
	v_and_or_b32 v10, v17, s56, v14
	global_store_dwordx4 v[30:31], v[10:13], off offset:144
	global_load_dwordx4 v[10:13], v1, s[4:5] offset:368
	s_nop 0
	global_load_dwordx4 v[14:17], v1, s[4:5] offset:352
	global_load_dwordx4 v[18:21], v1, s[4:5] offset:336
	global_load_dwordx4 v[22:25], v1, s[4:5] offset:320
	v_and_b32_e32 v7, 0xffff0000, v7
	v_and_b32_e32 v6, 0xffff0000, v6
	v_pk_mul_f32 v[6:7], v[0:1], v[6:7] op_sel_hi:[0,1]
	v_pk_mul_f32 v[32:33], v[0:1], v[32:33] op_sel_hi:[0,1]
	s_waitcnt vmcnt(0)
	v_mov_b32_e32 v34, v22
	v_mov_b32_e32 v35, v24
	v_mov_b32_e32 v24, v23
	v_lshlrev_b32_e32 v23, 16, v9
	v_lshlrev_b32_e32 v22, 16, v8
	v_and_b32_e32 v9, 0xffff0000, v9
	v_and_b32_e32 v8, 0xffff0000, v8
	v_pk_mul_f32 v[6:7], v[24:25], v[6:7]
	v_mov_b32_e32 v25, v20
	v_pk_mul_f32 v[8:9], v[0:1], v[8:9] op_sel_hi:[0,1]
	v_mov_b32_e32 v20, v19
	v_pk_mul_f32 v[22:23], v[0:1], v[22:23] op_sel_hi:[0,1]
	v_mov_b32_e32 v24, v18
	v_pk_mul_f32 v[8:9], v[20:21], v[8:9]
	v_pk_mul_f32 v[32:33], v[34:35], v[32:33]
	v_pk_mul_f32 v[22:23], v[24:25], v[22:23]
	v_bfe_u32 v18, v9, 16, 1
	v_bfe_u32 v19, v8, 16, 1
	v_bfe_u32 v20, v7, 16, 1
	v_bfe_u32 v21, v6, 16, 1
	v_add3_u32 v6, v6, v21, s54
	v_add3_u32 v7, v7, v20, s54
	v_add3_u32 v8, v8, v19, s54
	v_add3_u32 v9, v9, v18, s54
	v_bfe_u32 v18, v32, 16, 1
	v_bfe_u32 v19, v33, 16, 1
	v_bfe_u32 v20, v22, 16, 1
	v_bfe_u32 v21, v23, 16, 1
	v_add3_u32 v21, v23, v21, s54
	v_add3_u32 v20, v22, v20, s54
	v_add3_u32 v19, v33, v19, s54
	v_add3_u32 v18, v32, v18, s54
	v_lshrrev_b32_e32 v18, 16, v18
	v_lshrrev_b32_e32 v19, 16, v19
	v_lshrrev_b32_e32 v20, 16, v20
	v_lshrrev_b32_e32 v21, 16, v21
	v_and_or_b32 v9, v9, s56, v21
	v_and_or_b32 v8, v8, s56, v20
	v_and_or_b32 v7, v7, s56, v19
	v_and_or_b32 v6, v6, s56, v18
	global_store_dwordx4 v[30:31], v[6:9], off offset:160
	s_nop 1
	v_lshlrev_b32_e32 v7, 16, v3
	v_lshlrev_b32_e32 v6, 16, v2
	v_and_b32_e32 v9, 0xffff0000, v3
	v_and_b32_e32 v8, 0xffff0000, v2
	v_pk_mul_f32 v[2:3], v[0:1], v[6:7] op_sel_hi:[0,1]
	v_mov_b32_e32 v6, v14
	v_mov_b32_e32 v7, v16
	v_pk_mul_f32 v[2:3], v[6:7], v[2:3]
	v_pk_mul_f32 v[6:7], v[0:1], v[8:9] op_sel_hi:[0,1]
	v_lshlrev_b32_e32 v9, 16, v5
	v_lshlrev_b32_e32 v8, 16, v4
	v_and_b32_e32 v5, 0xffff0000, v5
	v_and_b32_e32 v4, 0xffff0000, v4
	v_mov_b32_e32 v16, v15
	v_mov_b32_e32 v15, v12
	v_pk_mul_f32 v[4:5], v[0:1], v[4:5] op_sel_hi:[0,1]
	v_mov_b32_e32 v12, v11
	v_pk_mul_f32 v[6:7], v[16:17], v[6:7]
	v_pk_mul_f32 v[8:9], v[0:1], v[8:9] op_sel_hi:[0,1]
	v_mov_b32_e32 v14, v10
	v_pk_mul_f32 v[4:5], v[12:13], v[4:5]
	v_pk_mul_f32 v[8:9], v[14:15], v[8:9]
	v_bfe_u32 v10, v5, 16, 1
	v_bfe_u32 v11, v4, 16, 1
	v_bfe_u32 v12, v7, 16, 1
	v_bfe_u32 v13, v6, 16, 1
	v_add3_u32 v6, v6, v13, s54
	v_add3_u32 v7, v7, v12, s54
	v_add3_u32 v4, v4, v11, s54
	v_add3_u32 v5, v5, v10, s54
	v_bfe_u32 v10, v2, 16, 1
	v_bfe_u32 v11, v3, 16, 1
	v_bfe_u32 v12, v8, 16, 1
	v_bfe_u32 v13, v9, 16, 1
	v_add3_u32 v9, v9, v13, s54
	v_add3_u32 v8, v8, v12, s54
	v_add3_u32 v3, v3, v11, s54
	v_add3_u32 v2, v2, v10, s54
	v_lshrrev_b32_e32 v2, 16, v2
	v_lshrrev_b32_e32 v3, 16, v3
	v_lshrrev_b32_e32 v8, 16, v8
	v_lshrrev_b32_e32 v9, 16, v9
	v_and_or_b32 v5, v5, s56, v9
	v_and_or_b32 v4, v4, s56, v8
	v_and_or_b32 v3, v7, s56, v3
	v_and_or_b32 v2, v6, s56, v2
	global_store_dwordx4 v[30:31], v[2:5], off offset:176
	global_load_dwordx4 v[2:5], v[30:31], off offset:240
	s_nop 0
	global_load_dwordx4 v[6:9], v[30:31], off offset:224
	global_load_dwordx4 v[14:17], v[30:31], off offset:208
	global_load_dwordx4 v[22:25], v[30:31], off offset:192
	global_load_dwordx4 v[10:13], v1, s[4:5] offset:432
	global_load_dwordx4 v[18:21], v1, s[4:5] offset:416
	global_load_dwordx4 v[32:35], v1, s[4:5] offset:400
	global_load_dwordx4 v[36:39], v1, s[4:5] offset:384
	s_waitcnt vmcnt(0)
; template <int D, int ROT0, int HALF, bool GAIN, bool KEEP = true>
; DI void chunk_nr(u16* p, const float* __restrict__ gain, const float* __restrict__ tab) {
;     ...
;     } else if (GAIN) {
;       f32x8 x1 = bf8_to_f32(RAWV(v));
;       const f32x8 g1 = *(const f32x8*)(gain + v * 8);
; #pragma unroll
;       for (int e = 0; e < 8; ++e) x1[e] = x1[e] * rstd * g1[e];
;       *(u32x4*)(p + v * 8) = f32_to_bf8(x1);
;     }
	v_lshlrev_b32_e32 v41, 16, v23
	v_lshlrev_b32_e32 v40, 16, v22
	v_and_b32_e32 v23, 0xffff0000, v23
	v_and_b32_e32 v22, 0xffff0000, v22
	v_mov_b32_e32 v42, v36
	v_mov_b32_e32 v43, v38
	v_pk_mul_f32 v[22:23], v[0:1], v[22:23] op_sel_hi:[0,1]
	v_mov_b32_e32 v38, v37
	v_lshlrev_b32_e32 v37, 16, v25
	v_lshlrev_b32_e32 v36, 16, v24
	v_and_b32_e32 v25, 0xffff0000, v25
	v_and_b32_e32 v24, 0xffff0000, v24
	v_pk_mul_f32 v[22:23], v[38:39], v[22:23]
	v_mov_b32_e32 v39, v34
	v_pk_mul_f32 v[24:25], v[0:1], v[24:25] op_sel_hi:[0,1]
	v_mov_b32_e32 v34, v33
	v_pk_mul_f32 v[40:41], v[0:1], v[40:41] op_sel_hi:[0,1]
	v_pk_mul_f32 v[36:37], v[0:1], v[36:37] op_sel_hi:[0,1]
	v_mov_b32_e32 v38, v32
	v_pk_mul_f32 v[24:25], v[34:35], v[24:25]
	v_pk_mul_f32 v[40:41], v[42:43], v[40:41]
	v_pk_mul_f32 v[36:37], v[38:39], v[36:37]
	v_bfe_u32 v32, v25, 16, 1
	v_bfe_u32 v33, v24, 16, 1
	v_bfe_u32 v34, v23, 16, 1
	v_bfe_u32 v35, v22, 16, 1
	v_add3_u32 v22, v22, v35, s54
	v_add3_u32 v23, v23, v34, s54
	v_add3_u32 v24, v24, v33, s54
	v_add3_u32 v25, v25, v32, s54
	v_bfe_u32 v32, v40, 16, 1
	v_bfe_u32 v33, v41, 16, 1
	v_bfe_u32 v34, v36, 16, 1
	v_bfe_u32 v35, v37, 16, 1
	v_add3_u32 v35, v37, v35, s54
	v_add3_u32 v34, v36, v34, s54
	v_add3_u32 v33, v41, v33, s54
	v_add3_u32 v32, v40, v32, s54
	v_lshrrev_b32_e32 v32, 16, v32
	v_lshrrev_b32_e32 v33, 16, v33
	v_lshrrev_b32_e32 v34, 16, v34
	v_lshrrev_b32_e32 v35, 16, v35
	v_and_or_b32 v25, v25, s56, v35
	v_and_or_b32 v24, v24, s56, v34
	v_and_or_b32 v23, v23, s56, v33
	v_and_or_b32 v22, v22, s56, v32
	global_store_dwordx4 v[30:31], v[22:25], off offset:192
	v_lshlrev_b32_e32 v33, 16, v7
	v_lshlrev_b32_e32 v32, 16, v6
	v_lshlrev_b32_e32 v23, 16, v15
	v_lshlrev_b32_e32 v22, 16, v14
	v_and_b32_e32 v25, 0xffff0000, v15
	v_and_b32_e32 v24, 0xffff0000, v14
	v_pk_mul_f32 v[14:15], v[0:1], v[22:23] op_sel_hi:[0,1]
	v_mov_b32_e32 v22, v18
	v_mov_b32_e32 v23, v20
	v_pk_mul_f32 v[14:15], v[22:23], v[14:15]
	v_pk_mul_f32 v[22:23], v[0:1], v[24:25] op_sel_hi:[0,1]
	v_mov_b32_e32 v20, v19
	v_pk_mul_f32 v[18:19], v[20:21], v[22:23]
	v_lshlrev_b32_e32 v21, 16, v17
	v_lshlrev_b32_e32 v20, 16, v16
	v_and_b32_e32 v17, 0xffff0000, v17
	v_and_b32_e32 v16, 0xffff0000, v16
	v_mov_b32_e32 v23, v12
	v_pk_mul_f32 v[16:17], v[0:1], v[16:17] op_sel_hi:[0,1]
	v_mov_b32_e32 v12, v11
	v_pk_mul_f32 v[20:21], v[0:1], v[20:21] op_sel_hi:[0,1]
	v_mov_b32_e32 v22, v10
	v_pk_mul_f32 v[10:11], v[12:13], v[16:17]
	v_pk_mul_f32 v[20:21], v[22:23], v[20:21]
	v_bfe_u32 v12, v11, 16, 1
	v_bfe_u32 v13, v10, 16, 1
	v_bfe_u32 v16, v19, 16, 1
	v_bfe_u32 v17, v18, 16, 1
	v_add3_u32 v17, v18, v17, s54
	v_add3_u32 v16, v19, v16, s54
	v_add3_u32 v10, v10, v13, s54
	v_add3_u32 v11, v11, v12, s54
	v_bfe_u32 v12, v14, 16, 1
	v_bfe_u32 v13, v15, 16, 1
	v_bfe_u32 v18, v20, 16, 1
	v_bfe_u32 v19, v21, 16, 1
	v_add3_u32 v19, v21, v19, s54
	v_add3_u32 v18, v20, v18, s54
	v_add3_u32 v13, v15, v13, s54
	v_add3_u32 v12, v14, v12, s54
	v_lshrrev_b32_e32 v14, 16, v12
	v_lshrrev_b32_e32 v15, 16, v13
	v_lshrrev_b32_e32 v12, 16, v18
	v_lshrrev_b32_e32 v13, 16, v19
	v_and_or_b32 v13, v11, s56, v13
	v_and_or_b32 v12, v10, s56, v12
	v_and_or_b32 v11, v16, s56, v15
	v_and_or_b32 v10, v17, s56, v14
	global_store_dwordx4 v[30:31], v[10:13], off offset:208
	global_load_dwordx4 v[10:13], v1, s[4:5] offset:496
	s_nop 0
	global_load_dwordx4 v[14:17], v1, s[4:5] offset:480
	global_load_dwordx4 v[18:21], v1, s[4:5] offset:464
	global_load_dwordx4 v[22:25], v1, s[4:5] offset:448
	v_and_b32_e32 v7, 0xffff0000, v7
	v_and_b32_e32 v6, 0xffff0000, v6
	v_pk_mul_f32 v[6:7], v[0:1], v[6:7] op_sel_hi:[0,1]
	v_pk_mul_f32 v[32:33], v[0:1], v[32:33] op_sel_hi:[0,1]
	s_waitcnt vmcnt(0)
	v_mov_b32_e32 v34, v22
	v_mov_b32_e32 v35, v24
	v_mov_b32_e32 v24, v23
	v_lshlrev_b32_e32 v23, 16, v9
	v_lshlrev_b32_e32 v22, 16, v8
	v_and_b32_e32 v9, 0xffff0000, v9
	v_and_b32_e32 v8, 0xffff0000, v8
	v_pk_mul_f32 v[6:7], v[24:25], v[6:7]
	v_mov_b32_e32 v25, v20
	v_pk_mul_f32 v[8:9], v[0:1], v[8:9] op_sel_hi:[0,1]
	v_mov_b32_e32 v20, v19
	v_pk_mul_f32 v[22:23], v[0:1], v[22:23] op_sel_hi:[0,1]
	v_mov_b32_e32 v24, v18
	v_pk_mul_f32 v[8:9], v[20:21], v[8:9]
	v_pk_mul_f32 v[32:33], v[34:35], v[32:33]
	v_pk_mul_f32 v[22:23], v[24:25], v[22:23]
	v_bfe_u32 v18, v9, 16, 1
	v_bfe_u32 v19, v8, 16, 1
	v_bfe_u32 v20, v7, 16, 1
	v_bfe_u32 v21, v6, 16, 1
	v_add3_u32 v6, v6, v21, s54
	v_add3_u32 v7, v7, v20, s54
	v_add3_u32 v8, v8, v19, s54
	v_add3_u32 v9, v9, v18, s54
	v_bfe_u32 v18, v32, 16, 1
	v_bfe_u32 v19, v33, 16, 1
	v_bfe_u32 v20, v22, 16, 1
	v_bfe_u32 v21, v23, 16, 1
	v_add3_u32 v21, v23, v21, s54
	v_add3_u32 v20, v22, v20, s54
	v_add3_u32 v19, v33, v19, s54
	v_add3_u32 v18, v32, v18, s54
	v_lshrrev_b32_e32 v18, 16, v18
	v_lshrrev_b32_e32 v19, 16, v19
	v_lshrrev_b32_e32 v20, 16, v20
	v_lshrrev_b32_e32 v21, 16, v21
	v_and_or_b32 v9, v9, s56, v21
	v_and_or_b32 v8, v8, s56, v20
	v_and_or_b32 v7, v7, s56, v19
	v_and_or_b32 v6, v6, s56, v18
	global_store_dwordx4 v[30:31], v[6:9], off offset:224
	s_nop 1
	v_lshlrev_b32_e32 v7, 16, v3
	v_lshlrev_b32_e32 v6, 16, v2
	v_and_b32_e32 v9, 0xffff0000, v3
	v_and_b32_e32 v8, 0xffff0000, v2
	v_pk_mul_f32 v[2:3], v[0:1], v[6:7] op_sel_hi:[0,1]
	v_mov_b32_e32 v6, v14
	v_mov_b32_e32 v7, v16
	v_pk_mul_f32 v[2:3], v[6:7], v[2:3]
	v_pk_mul_f32 v[6:7], v[0:1], v[8:9] op_sel_hi:[0,1]
	v_lshlrev_b32_e32 v9, 16, v5
	v_lshlrev_b32_e32 v8, 16, v4
	v_and_b32_e32 v5, 0xffff0000, v5
	v_and_b32_e32 v4, 0xffff0000, v4
	v_mov_b32_e32 v16, v15
	v_mov_b32_e32 v15, v12
	v_pk_mul_f32 v[4:5], v[0:1], v[4:5] op_sel_hi:[0,1]
	v_mov_b32_e32 v12, v11
	v_pk_mul_f32 v[6:7], v[16:17], v[6:7]
	v_pk_mul_f32 v[8:9], v[0:1], v[8:9] op_sel_hi:[0,1]
; template <int D, int ROT0, int HALF, bool GAIN, bool KEEP = true>
; DI void chunk_nr(u16* p, const float* __restrict__ gain, const float* __restrict__ tab) {
;     ...
;     if (v >= V0 && v < V0 + 2 * NRV) {
;       if (v >= V0 + NRV) continue;
;       const f32x8 x1 = bf8_to_f32(RAWV(v));
;       const f32x8 x2 = bf8_to_f32(RAWV(v + NRV));
;       f32x8 g1, g2;
;       if (GAIN) { g1 = *(const f32x8*)(gain + v * 8); g2 = *(const f32x8*)(gain + (v + NRV) * 8); }
;       const f32x8 t0 = *(const f32x8*)(tab + 2 * (v - V0) * 8);
;       const f32x8 t1 = *(const f32x8*)(tab + 2 * (v - V0) * 8 + 8);
;       f32x8 o1, o2;
; #pragma unroll
;       for (int e = 0; e < 8; ++e) {
;         float y1 = x1[e], y2 = x2[e];
;         if (GAIN) { y1 = y1 * rstd * g1[e]; y2 = y2 * rstd * g2[e]; }
;         const float c = (e < 4) ? t0[2 * e] : t1[2 * (e - 4)];
;         const float sn = (e < 4) ? t0[2 * e + 1] : t1[2 * (e - 4) + 1];
;         o1[e] = y1 * c - y2 * sn;
;         o2[e] = y2 * c + y1 * sn;
;       }
;       *(u32x4*)(p + v * 8) = f32_to_bf8(o1);
;       *(u32x4*)(p + (v + NRV) * 8) = f32_to_bf8(o2);
;     } else if (GAIN) {
;       f32x8 x1 = bf8_to_f32(RAWV(v));
;       const f32x8 g1 = *(const f32x8*)(gain + v * 8);
; #pragma unroll
;       for (int e = 0; e < 8; ++e) x1[e] = x1[e] * rstd * g1[e];
;       *(u32x4*)(p + v * 8) = f32_to_bf8(x1);
;     }
	v_mov_b32_e32 v14, v10
	v_pk_mul_f32 v[4:5], v[12:13], v[4:5]
	v_pk_mul_f32 v[8:9], v[14:15], v[8:9]
	v_bfe_u32 v10, v5, 16, 1
	v_bfe_u32 v11, v4, 16, 1
	v_bfe_u32 v12, v7, 16, 1
	v_bfe_u32 v13, v6, 16, 1
	v_add3_u32 v6, v6, v13, s54
	v_add3_u32 v7, v7, v12, s54
	v_add3_u32 v4, v4, v11, s54
	v_add3_u32 v5, v5, v10, s54
	v_bfe_u32 v10, v2, 16, 1
	v_bfe_u32 v11, v3, 16, 1
	v_bfe_u32 v12, v8, 16, 1
	v_bfe_u32 v13, v9, 16, 1
	v_add3_u32 v9, v9, v13, s54
	v_add3_u32 v8, v8, v12, s54
	v_add3_u32 v3, v3, v11, s54
	v_add3_u32 v2, v2, v10, s54
	v_lshrrev_b32_e32 v2, 16, v2
	v_lshrrev_b32_e32 v3, 16, v3
	v_lshrrev_b32_e32 v8, 16, v8
	v_lshrrev_b32_e32 v9, 16, v9
	v_and_or_b32 v5, v5, s56, v9
	v_and_or_b32 v4, v4, s56, v8
	v_and_or_b32 v3, v7, s56, v3
	v_and_or_b32 v2, v6, s56, v2
	global_store_dwordx4 v[30:31], v[2:5], off offset:240
	global_load_dwordx4 v[10:13], v[30:31], off offset:256
	global_load_dwordx4 v[14:17], v[30:31], off offset:320
	global_load_dwordx4 v[32:35], v1, s[4:5] offset:640
	global_load_dwordx4 v[36:39], v1, s[4:5] offset:512
	global_load_dwordx4 v[40:43], v[28:29], off offset:192
	global_load_dwordx4 v[44:47], v[28:29], off offset:208
	global_load_dwordx4 v[48:51], v1, s[4:5] offset:656
	global_load_dwordx4 v[52:55], v1, s[4:5] offset:528
	global_load_dwordx4 v[56:59], v[28:29], off offset:224
	global_load_dwordx4 v[60:63], v[28:29], off offset:240
	global_load_dwordx4 v[22:25], v[30:31], off offset:272
	global_load_dwordx4 v[18:21], v[30:31], off offset:336
	global_load_dwordx4 v[2:5], v1, s[4:5] offset:560
	global_load_dwordx4 v[64:67], v1, s[4:5] offset:544
	global_load_dwordx4 v[6:9], v1, s[4:5] offset:688
	global_load_dwordx4 v[68:71], v1, s[4:5] offset:672
	s_waitcnt vmcnt(0)
	v_lshlrev_b32_e32 v73, 16, v11
	v_lshlrev_b32_e32 v75, 16, v15
	v_lshlrev_b32_e32 v74, 16, v14
	v_and_b32_e32 v15, 0xffff0000, v15
	v_and_b32_e32 v14, 0xffff0000, v14
	v_mov_b32_e32 v78, v36
	v_mov_b32_e32 v79, v38
	v_mov_b32_e32 v38, v37
	v_mov_b32_e32 v36, v42
	v_mov_b32_e32 v37, v46
	v_mov_b32_e32 v46, v43
	v_lshlrev_b32_e32 v43, 16, v17
	v_lshlrev_b32_e32 v42, 16, v16
	v_and_b32_e32 v17, 0xffff0000, v17
	v_and_b32_e32 v16, 0xffff0000, v16
	v_lshlrev_b32_e32 v72, 16, v10
	v_and_b32_e32 v11, 0xffff0000, v11
	v_and_b32_e32 v10, 0xffff0000, v10
	v_mov_b32_e32 v76, v32
	v_mov_b32_e32 v77, v34
	v_mov_b32_e32 v34, v33
	v_mov_b32_e32 v32, v40
	v_mov_b32_e32 v33, v44
	v_mov_b32_e32 v44, v41
	v_lshlrev_b32_e32 v41, 16, v13
	v_lshlrev_b32_e32 v40, 16, v12
	v_and_b32_e32 v13, 0xffff0000, v13
	v_and_b32_e32 v12, 0xffff0000, v12
	v_mov_b32_e32 v81, v50
	v_mov_b32_e32 v50, v49
	v_pk_mul_f32 v[14:15], v[0:1], v[14:15] op_sel_hi:[0,1]
	v_pk_mul_f32 v[16:17], v[0:1], v[16:17] op_sel_hi:[0,1]
	v_mov_b32_e32 v80, v48
	v_mov_b32_e32 v83, v54
	v_mov_b32_e32 v54, v53
	v_mov_b32_e32 v48, v56
	v_mov_b32_e32 v49, v60
	v_mov_b32_e32 v60, v57
	v_mov_b32_e32 v53, v62
	v_mov_b32_e32 v62, v59
	v_pk_mul_f32 v[56:57], v[0:1], v[74:75] op_sel_hi:[0,1]
	v_pk_mul_f32 v[10:11], v[0:1], v[10:11] op_sel_hi:[0,1]
	v_pk_mul_f32 v[42:43], v[0:1], v[42:43] op_sel_hi:[0,1]
	v_pk_mul_f32 v[12:13], v[0:1], v[12:13] op_sel_hi:[0,1]
	v_pk_mul_f32 v[14:15], v[34:35], v[14:15]
	v_pk_mul_f32 v[16:17], v[50:51], v[16:17]
	v_mov_b32_e32 v82, v52
	v_mov_b32_e32 v52, v58
	v_pk_mul_f32 v[58:59], v[0:1], v[72:73] op_sel_hi:[0,1]
	v_pk_mul_f32 v[40:41], v[0:1], v[40:41] op_sel_hi:[0,1]
	v_pk_mul_f32 v[56:57], v[76:77], v[56:57]
	v_pk_mul_f32 v[34:35], v[38:39], v[10:11]
	v_pk_mul_f32 v[38:39], v[80:81], v[42:43]
	v_pk_mul_f32 v[42:43], v[54:55], v[12:13]
	v_pk_mul_f32 v[12:13], v[46:47], v[14:15]
	v_pk_mul_f32 v[54:55], v[62:63], v[16:17]
	v_pk_mul_f32 v[58:59], v[78:79], v[58:59]
	v_pk_mul_f32 v[40:41], v[82:83], v[40:41]
	v_pk_mul_f32 v[10:11], v[44:45], v[56:57]
	v_pk_mul_f32 v[50:51], v[60:61], v[38:39]
	v_pk_fma_f32 v[12:13], v[36:37], v[34:35], v[12:13] neg_lo:[0,0,1] neg_hi:[0,0,1]
	v_pk_fma_f32 v[54:55], v[52:53], v[42:43], v[54:55] neg_lo:[0,0,1] neg_hi:[0,0,1]
	v_pk_fma_f32 v[10:11], v[32:33], v[58:59], v[10:11] neg_lo:[0,0,1] neg_hi:[0,0,1]
	v_pk_fma_f32 v[50:51], v[48:49], v[40:41], v[50:51] neg_lo:[0,0,1] neg_hi:[0,0,1]
	v_bfe_u32 v72, v55, 16, 1
	v_bfe_u32 v73, v54, 16, 1
	v_bfe_u32 v74, v13, 16, 1
	v_bfe_u32 v75, v12, 16, 1
	v_add3_u32 v75, v12, v75, s54
	v_add3_u32 v74, v13, v74, s54
	v_add3_u32 v12, v54, v73, s54
	v_add3_u32 v13, v55, v72, s54
	v_bfe_u32 v54, v10, 16, 1
	v_bfe_u32 v55, v11, 16, 1
	v_bfe_u32 v72, v50, 16, 1
	v_bfe_u32 v73, v51, 16, 1
	v_add3_u32 v51, v51, v73, s54
	v_add3_u32 v50, v50, v72, s54
	v_add3_u32 v11, v11, v55, s54
	v_add3_u32 v10, v10, v54, s54
	v_lshrrev_b32_e32 v10, 16, v10
	v_lshrrev_b32_e32 v11, 16, v11
	v_lshrrev_b32_e32 v50, 16, v50
	v_lshrrev_b32_e32 v51, 16, v51
	v_and_or_b32 v13, v13, s56, v51
	v_and_or_b32 v12, v12, s56, v50
	v_and_or_b32 v11, v74, s56, v11
	v_and_or_b32 v10, v75, s56, v10
	global_store_dwordx4 v[30:31], v[10:13], off offset:256
	v_lshlrev_b32_e32 v51, 16, v19
	v_lshlrev_b32_e32 v50, 16, v18
	v_pk_mul_f32 v[10:11], v[44:45], v[58:59]
	v_pk_mul_f32 v[12:13], v[46:47], v[34:35]
	v_pk_fma_f32 v[10:11], v[32:33], v[56:57], v[10:11]
	v_pk_mul_f32 v[32:33], v[62:63], v[42:43]
	v_pk_fma_f32 v[12:13], v[36:37], v[14:15], v[12:13]
	v_pk_mul_f32 v[14:15], v[60:61], v[40:41]
	v_pk_fma_f32 v[16:17], v[52:53], v[16:17], v[32:33]
	v_pk_fma_f32 v[14:15], v[48:49], v[38:39], v[14:15]
	v_bfe_u32 v32, v17, 16, 1
	v_bfe_u32 v33, v16, 16, 1
	v_bfe_u32 v34, v13, 16, 1
	v_bfe_u32 v35, v12, 16, 1
	v_add3_u32 v35, v12, v35, s54
	v_add3_u32 v34, v13, v34, s54
	v_add3_u32 v12, v16, v33, s54
	v_add3_u32 v13, v17, v32, s54
	v_bfe_u32 v16, v10, 16, 1
; template <int D, int ROT0, int HALF, bool GAIN, bool KEEP = true>
; DI void chunk_nr(u16* p, const float* __restrict__ gain, const float* __restrict__ tab) {
;     ...
;     if (v >= V0 && v < V0 + 2 * NRV) {
;       if (v >= V0 + NRV) continue;
;       const f32x8 x1 = bf8_to_f32(RAWV(v));
;       const f32x8 x2 = bf8_to_f32(RAWV(v + NRV));
;       f32x8 g1, g2;
;       if (GAIN) { g1 = *(const f32x8*)(gain + v * 8); g2 = *(const f32x8*)(gain + (v + NRV) * 8); }
;       const f32x8 t0 = *(const f32x8*)(tab + 2 * (v - V0) * 8);
;       const f32x8 t1 = *(const f32x8*)(tab + 2 * (v - V0) * 8 + 8);
;       f32x8 o1, o2;
; #pragma unroll
;       for (int e = 0; e < 8; ++e) {
;         float y1 = x1[e], y2 = x2[e];
;         if (GAIN) { y1 = y1 * rstd * g1[e]; y2 = y2 * rstd * g2[e]; }
;         const float c = (e < 4) ? t0[2 * e] : t1[2 * (e - 4)];
;         const float sn = (e < 4) ? t0[2 * e + 1] : t1[2 * (e - 4) + 1];
;         o1[e] = y1 * c - y2 * sn;
;         o2[e] = y2 * c + y1 * sn;
;       }
;       *(u32x4*)(p + v * 8) = f32_to_bf8(o1);
;       *(u32x4*)(p + (v + NRV) * 8) = f32_to_bf8(o2);
	v_bfe_u32 v17, v11, 16, 1
	v_bfe_u32 v32, v14, 16, 1
	v_bfe_u32 v33, v15, 16, 1
	v_add3_u32 v15, v15, v33, s54
	v_add3_u32 v14, v14, v32, s54
	v_add3_u32 v11, v11, v17, s54
	v_add3_u32 v10, v10, v16, s54
	v_lshrrev_b32_e32 v10, 16, v10
	v_lshrrev_b32_e32 v11, 16, v11
	v_lshrrev_b32_e32 v14, 16, v14
	v_lshrrev_b32_e32 v15, 16, v15
	v_and_or_b32 v13, v13, s56, v15
	v_and_or_b32 v12, v12, s56, v14
	v_and_or_b32 v11, v34, s56, v11
	v_and_or_b32 v10, v35, s56, v10
	global_store_dwordx4 v[30:31], v[10:13], off offset:320
	global_load_dwordx4 v[32:35], v[28:29], off offset:256
	global_load_dwordx4 v[36:39], v[28:29], off offset:272
	global_load_dwordx4 v[40:43], v[28:29], off offset:288
	global_load_dwordx4 v[44:47], v[28:29], off offset:304
	global_load_dwordx4 v[14:17], v[30:31], off offset:288
	global_load_dwordx4 v[10:13], v[30:31], off offset:352
	v_and_b32_e32 v19, 0xffff0000, v19
	v_and_b32_e32 v18, 0xffff0000, v18
	v_lshlrev_b32_e32 v59, 16, v21
	v_lshlrev_b32_e32 v58, 16, v20
	v_and_b32_e32 v21, 0xffff0000, v21
	v_and_b32_e32 v20, 0xffff0000, v20
	v_lshlrev_b32_e32 v49, 16, v23
	v_lshlrev_b32_e32 v48, 16, v22
	v_and_b32_e32 v23, 0xffff0000, v23
	v_and_b32_e32 v22, 0xffff0000, v22
	v_mov_b32_e32 v52, v68
	v_mov_b32_e32 v53, v70
	v_mov_b32_e32 v70, v69
	v_pk_mul_f32 v[50:51], v[0:1], v[50:51] op_sel_hi:[0,1]
	v_pk_mul_f32 v[18:19], v[0:1], v[18:19] op_sel_hi:[0,1]
	v_lshlrev_b32_e32 v57, 16, v25
	v_lshlrev_b32_e32 v56, 16, v24
	v_and_b32_e32 v25, 0xffff0000, v25
	v_and_b32_e32 v24, 0xffff0000, v24
	v_pk_mul_f32 v[58:59], v[0:1], v[58:59] op_sel_hi:[0,1]
	v_mov_b32_e32 v60, v6
	v_mov_b32_e32 v61, v8
	v_pk_mul_f32 v[20:21], v[0:1], v[20:21] op_sel_hi:[0,1]
	v_mov_b32_e32 v8, v7
	v_mov_b32_e32 v55, v66
	v_mov_b32_e32 v66, v65
	v_pk_mul_f32 v[22:23], v[0:1], v[22:23] op_sel_hi:[0,1]
	v_pk_mul_f32 v[50:51], v[52:53], v[50:51]
	v_pk_mul_f32 v[18:19], v[70:71], v[18:19]
	v_pk_mul_f32 v[58:59], v[60:61], v[58:59]
	v_mov_b32_e32 v61, v4
	v_pk_mul_f32 v[6:7], v[8:9], v[20:21]
	v_pk_mul_f32 v[8:9], v[0:1], v[24:25] op_sel_hi:[0,1]
	v_mov_b32_e32 v4, v3
	v_mov_b32_e32 v54, v64
	v_pk_mul_f32 v[48:49], v[0:1], v[48:49] op_sel_hi:[0,1]
	v_pk_mul_f32 v[22:23], v[66:67], v[22:23]
	v_pk_mul_f32 v[56:57], v[0:1], v[56:57] op_sel_hi:[0,1]
	v_mov_b32_e32 v60, v2
	v_pk_mul_f32 v[8:9], v[4:5], v[8:9]
	v_pk_mul_f32 v[48:49], v[54:55], v[48:49]
	v_pk_mul_f32 v[56:57], v[60:61], v[56:57]
	s_waitcnt vmcnt(0)
	v_mov_b32_e32 v52, v32
	v_mov_b32_e32 v53, v36
	v_mov_b32_e32 v36, v33
	v_mov_b32_e32 v33, v38
	v_mov_b32_e32 v38, v35
	v_mov_b32_e32 v25, v46
	v_mov_b32_e32 v46, v43
	v_mov_b32_e32 v32, v34
	v_pk_mul_f32 v[34:35], v[38:39], v[18:19]
	v_mov_b32_e32 v21, v44
	v_mov_b32_e32 v44, v41
	v_mov_b32_e32 v24, v42
	v_pk_mul_f32 v[4:5], v[46:47], v[6:7]
	v_pk_mul_f32 v[54:55], v[36:37], v[50:51]
	v_pk_fma_f32 v[34:35], v[32:33], v[22:23], v[34:35] neg_lo:[0,0,1] neg_hi:[0,0,1]
	v_mov_b32_e32 v20, v40
	v_pk_mul_f32 v[2:3], v[44:45], v[58:59]
	v_pk_fma_f32 v[4:5], v[24:25], v[8:9], v[4:5] neg_lo:[0,0,1] neg_hi:[0,0,1]
	v_pk_fma_f32 v[54:55], v[52:53], v[48:49], v[54:55] neg_lo:[0,0,1] neg_hi:[0,0,1]
	v_pk_fma_f32 v[2:3], v[20:21], v[56:57], v[2:3] neg_lo:[0,0,1] neg_hi:[0,0,1]
	v_bfe_u32 v40, v5, 16, 1
	v_bfe_u32 v41, v4, 16, 1
	v_bfe_u32 v42, v35, 16, 1
	v_bfe_u32 v43, v34, 16, 1
	v_add3_u32 v34, v34, v43, s54
	v_add3_u32 v35, v35, v42, s54
	v_add3_u32 v4, v4, v41, s54
	v_add3_u32 v5, v5, v40, s54
	v_bfe_u32 v40, v54, 16, 1
	v_bfe_u32 v41, v55, 16, 1
	v_bfe_u32 v42, v2, 16, 1
	v_bfe_u32 v43, v3, 16, 1
	v_add3_u32 v3, v3, v43, s54
	v_add3_u32 v2, v2, v42, s54
	v_add3_u32 v41, v55, v41, s54
	v_add3_u32 v40, v54, v40, s54
	v_lshrrev_b32_e32 v40, 16, v40
	v_lshrrev_b32_e32 v41, 16, v41
	v_lshrrev_b32_e32 v2, 16, v2
	v_lshrrev_b32_e32 v3, 16, v3
	v_and_or_b32 v5, v5, s56, v3
	v_and_or_b32 v4, v4, s56, v2
	v_and_or_b32 v3, v35, s56, v41
	v_and_or_b32 v2, v34, s56, v40
	global_store_dwordx4 v[30:31], v[2:5], off offset:272
	v_pk_mul_f32 v[8:9], v[46:47], v[8:9]
	v_lshlrev_b32_e32 v75, 16, v11
	v_pk_mul_f32 v[4:5], v[38:39], v[22:23]
	v_pk_mul_f32 v[2:3], v[36:37], v[48:49]
	v_pk_fma_f32 v[4:5], v[32:33], v[18:19], v[4:5]
	v_pk_mul_f32 v[18:19], v[44:45], v[56:57]
	v_pk_fma_f32 v[6:7], v[24:25], v[6:7], v[8:9]
	v_pk_fma_f32 v[2:3], v[52:53], v[50:51], v[2:3]
	v_pk_fma_f32 v[18:19], v[20:21], v[58:59], v[18:19]
	v_bfe_u32 v8, v7, 16, 1
	v_bfe_u32 v9, v6, 16, 1
	v_bfe_u32 v20, v5, 16, 1
	v_bfe_u32 v21, v4, 16, 1
	v_add3_u32 v21, v4, v21, s54
	v_add3_u32 v20, v5, v20, s54
	v_add3_u32 v4, v6, v9, s54
	v_add3_u32 v5, v7, v8, s54
	v_bfe_u32 v6, v2, 16, 1
	v_bfe_u32 v7, v3, 16, 1
	v_bfe_u32 v8, v18, 16, 1
	v_bfe_u32 v9, v19, 16, 1
	v_add3_u32 v9, v19, v9, s54
	v_add3_u32 v8, v18, v8, s54
	v_add3_u32 v3, v3, v7, s54
	v_add3_u32 v2, v2, v6, s54
	v_lshrrev_b32_e32 v2, 16, v2
	v_lshrrev_b32_e32 v3, 16, v3
	v_lshrrev_b32_e32 v6, 16, v8
	v_lshrrev_b32_e32 v7, 16, v9
	v_and_or_b32 v5, v5, s56, v7
	v_and_or_b32 v4, v4, s56, v6
	v_and_or_b32 v3, v20, s56, v3
	v_and_or_b32 v2, v21, s56, v2
	global_store_dwordx4 v[30:31], v[2:5], off offset:336
	global_load_dwordx4 v[6:9], v1, s[4:5] offset:704
	global_load_dwordx4 v[18:21], v1, s[4:5] offset:576
	global_load_dwordx4 v[22:25], v[28:29], off offset:320
	global_load_dwordx4 v[32:35], v[28:29], off offset:336
	global_load_dwordx4 v[36:39], v1, s[4:5] offset:720
	global_load_dwordx4 v[40:43], v1, s[4:5] offset:592
	global_load_dwordx4 v[44:47], v[28:29], off offset:352
	global_load_dwordx4 v[48:51], v[28:29], off offset:368
	global_load_dwordx4 v[52:55], v[30:31], off offset:304
	global_load_dwordx4 v[56:59], v[30:31], off offset:368
	global_load_dwordx4 v[2:5], v1, s[4:5] offset:624
	global_load_dwordx4 v[60:63], v1, s[4:5] offset:608
	global_load_dwordx4 v[64:67], v1, s[4:5] offset:752
	global_load_dwordx4 v[68:71], v1, s[4:5] offset:736
	v_lshlrev_b32_e32 v74, 16, v10
	v_lshlrev_b32_e32 v73, 16, v15
	v_lshlrev_b32_e32 v72, 16, v14
	v_and_b32_e32 v15, 0xffff0000, v15
	v_and_b32_e32 v14, 0xffff0000, v14
	v_pk_mul_f32 v[74:75], v[0:1], v[74:75] op_sel_hi:[0,1]
	v_and_b32_e32 v11, 0xffff0000, v11
	v_and_b32_e32 v10, 0xffff0000, v10
	v_pk_mul_f32 v[72:73], v[0:1], v[72:73] op_sel_hi:[0,1]
	v_pk_mul_f32 v[10:11], v[0:1], v[10:11] op_sel_hi:[0,1]
	s_waitcnt vmcnt(0)
; template <int D, int ROT0, int HALF, bool GAIN, bool KEEP = true>
; DI void chunk_nr(u16* p, const float* __restrict__ gain, const float* __restrict__ tab) {
;     ...
;     if (v >= V0 && v < V0 + 2 * NRV) {
;       if (v >= V0 + NRV) continue;
;       const f32x8 x1 = bf8_to_f32(RAWV(v));
;       const f32x8 x2 = bf8_to_f32(RAWV(v + NRV));
;       f32x8 g1, g2;
;       if (GAIN) { g1 = *(const f32x8*)(gain + v * 8); g2 = *(const f32x8*)(gain + (v + NRV) * 8); }
;       const f32x8 t0 = *(const f32x8*)(tab + 2 * (v - V0) * 8);
;       const f32x8 t1 = *(const f32x8*)(tab + 2 * (v - V0) * 8 + 8);
;       f32x8 o1, o2;
; #pragma unroll
;       for (int e = 0; e < 8; ++e) {
;         float y1 = x1[e], y2 = x2[e];
;         if (GAIN) { y1 = y1 * rstd * g1[e]; y2 = y2 * rstd * g2[e]; }
;         const float c = (e < 4) ? t0[2 * e] : t1[2 * (e - 4)];
;         const float sn = (e < 4) ? t0[2 * e + 1] : t1[2 * (e - 4) + 1];
;         o1[e] = y1 * c - y2 * sn;
;         o2[e] = y2 * c + y1 * sn;
;       }
;       *(u32x4*)(p + v * 8) = f32_to_bf8(o1);
;       *(u32x4*)(p + (v + NRV) * 8) = f32_to_bf8(o2);
	v_mov_b32_e32 v76, v6
	v_mov_b32_e32 v77, v8
	v_pk_mul_f32 v[74:75], v[76:77], v[74:75]
	v_mov_b32_e32 v77, v20
	v_mov_b32_e32 v8, v7
	v_pk_mul_f32 v[6:7], v[0:1], v[14:15] op_sel_hi:[0,1]
	v_mov_b32_e32 v20, v19
	v_mov_b32_e32 v76, v18
	v_pk_mul_f32 v[14:15], v[20:21], v[6:7]
	v_mov_b32_e32 v20, v24
	v_mov_b32_e32 v21, v34
	v_mov_b32_e32 v34, v25
	v_lshlrev_b32_e32 v25, 16, v13
	v_lshlrev_b32_e32 v24, 16, v12
	v_and_b32_e32 v13, 0xffff0000, v13
	v_and_b32_e32 v12, 0xffff0000, v12
	v_pk_mul_f32 v[72:73], v[76:77], v[72:73]
	v_mov_b32_e32 v18, v22
	v_mov_b32_e32 v19, v32
	v_mov_b32_e32 v32, v23
	v_lshlrev_b32_e32 v23, 16, v17
	v_lshlrev_b32_e32 v22, 16, v16
	v_and_b32_e32 v17, 0xffff0000, v17
	v_and_b32_e32 v16, 0xffff0000, v16
	v_pk_mul_f32 v[24:25], v[0:1], v[24:25] op_sel_hi:[0,1]
	v_mov_b32_e32 v76, v36
	v_mov_b32_e32 v77, v38
	v_pk_mul_f32 v[12:13], v[0:1], v[12:13] op_sel_hi:[0,1]
	v_mov_b32_e32 v38, v37
	v_pk_mul_f32 v[10:11], v[8:9], v[10:11]
	v_pk_mul_f32 v[24:25], v[76:77], v[24:25]
	v_mov_b32_e32 v77, v42
	v_pk_mul_f32 v[12:13], v[38:39], v[12:13]
	v_pk_mul_f32 v[16:17], v[0:1], v[16:17] op_sel_hi:[0,1]
	v_mov_b32_e32 v42, v41
	v_mov_b32_e32 v41, v50
	v_mov_b32_e32 v50, v47
	v_pk_mul_f32 v[8:9], v[34:35], v[10:11]
	v_pk_mul_f32 v[22:23], v[0:1], v[22:23] op_sel_hi:[0,1]
	v_mov_b32_e32 v76, v40
	v_pk_mul_f32 v[16:17], v[42:43], v[16:17]
	v_mov_b32_e32 v37, v48
	v_mov_b32_e32 v48, v45
	v_mov_b32_e32 v40, v46
	v_pk_mul_f32 v[42:43], v[50:51], v[12:13]
	v_pk_mul_f32 v[6:7], v[32:33], v[74:75]
	v_pk_fma_f32 v[8:9], v[20:21], v[14:15], v[8:9] neg_lo:[0,0,1] neg_hi:[0,0,1]
	v_pk_mul_f32 v[22:23], v[76:77], v[22:23]
	v_mov_b32_e32 v36, v44
	v_pk_mul_f32 v[38:39], v[48:49], v[24:25]
	v_pk_fma_f32 v[42:43], v[40:41], v[16:17], v[42:43] neg_lo:[0,0,1] neg_hi:[0,0,1]
	v_pk_fma_f32 v[6:7], v[18:19], v[72:73], v[6:7] neg_lo:[0,0,1] neg_hi:[0,0,1]
	v_pk_fma_f32 v[38:39], v[36:37], v[22:23], v[38:39] neg_lo:[0,0,1] neg_hi:[0,0,1]
	v_bfe_u32 v44, v43, 16, 1
	v_bfe_u32 v45, v42, 16, 1
	v_bfe_u32 v46, v9, 16, 1
	v_bfe_u32 v47, v8, 16, 1
	v_add3_u32 v47, v8, v47, s54
	v_add3_u32 v46, v9, v46, s54
	v_add3_u32 v8, v42, v45, s54
	v_add3_u32 v9, v43, v44, s54
	v_bfe_u32 v42, v6, 16, 1
	v_bfe_u32 v43, v7, 16, 1
	v_bfe_u32 v44, v38, 16, 1
	v_bfe_u32 v45, v39, 16, 1
	v_add3_u32 v39, v39, v45, s54
	v_add3_u32 v38, v38, v44, s54
	v_add3_u32 v7, v7, v43, s54
	v_add3_u32 v6, v6, v42, s54
	v_lshrrev_b32_e32 v6, 16, v6
	v_lshrrev_b32_e32 v7, 16, v7
	v_lshrrev_b32_e32 v38, 16, v38
	v_lshrrev_b32_e32 v39, 16, v39
	v_and_or_b32 v9, v9, s56, v39
	v_and_or_b32 v8, v8, s56, v38
	v_and_or_b32 v7, v46, s56, v7
	v_and_or_b32 v6, v47, s56, v6
	global_store_dwordx4 v[30:31], v[6:9], off offset:288
	v_lshlrev_b32_e32 v43, 16, v59
	v_lshlrev_b32_e32 v42, 16, v58
	v_pk_mul_f32 v[8:9], v[34:35], v[14:15]
	v_pk_mul_f32 v[14:15], v[50:51], v[16:17]
	v_pk_mul_f32 v[6:7], v[32:33], v[72:73]
	v_pk_fma_f32 v[8:9], v[20:21], v[10:11], v[8:9]
	v_pk_mul_f32 v[10:11], v[48:49], v[22:23]
	v_pk_fma_f32 v[12:13], v[40:41], v[12:13], v[14:15]
	v_pk_fma_f32 v[6:7], v[18:19], v[74:75], v[6:7]
	v_pk_fma_f32 v[10:11], v[36:37], v[24:25], v[10:11]
	v_bfe_u32 v14, v13, 16, 1
	v_bfe_u32 v15, v12, 16, 1
	v_bfe_u32 v16, v9, 16, 1
	v_bfe_u32 v17, v8, 16, 1
	v_add3_u32 v17, v8, v17, s54
	v_add3_u32 v16, v9, v16, s54
	v_add3_u32 v8, v12, v15, s54
	v_add3_u32 v9, v13, v14, s54
	v_bfe_u32 v12, v6, 16, 1
	v_bfe_u32 v13, v7, 16, 1
	v_bfe_u32 v14, v10, 16, 1
	v_bfe_u32 v15, v11, 16, 1
	v_add3_u32 v11, v11, v15, s54
	v_add3_u32 v10, v10, v14, s54
	v_add3_u32 v7, v7, v13, s54
	v_add3_u32 v6, v6, v12, s54
	v_lshrrev_b32_e32 v6, 16, v6
	v_lshrrev_b32_e32 v7, 16, v7
	v_lshrrev_b32_e32 v10, 16, v10
	v_lshrrev_b32_e32 v11, 16, v11
	v_and_or_b32 v9, v9, s56, v11
	v_and_or_b32 v8, v8, s56, v10
	v_and_or_b32 v7, v16, s56, v7
	v_and_or_b32 v6, v17, s56, v6
	global_store_dwordx4 v[30:31], v[6:9], off offset:352
	global_load_dwordx4 v[6:9], v[28:29], off offset:384
	s_nop 0
	global_load_dwordx4 v[10:13], v[28:29], off offset:400
	global_load_dwordx4 v[14:17], v[28:29], off offset:416
	global_load_dwordx4 v[18:21], v[28:29], off offset:432
	v_lshlrev_b32_e32 v29, 16, v57
	v_lshlrev_b32_e32 v28, 16, v56
	v_and_b32_e32 v33, 0xffff0000, v57
	v_and_b32_e32 v32, 0xffff0000, v56
	v_lshlrev_b32_e32 v39, 16, v55
	v_lshlrev_b32_e32 v38, 16, v54
	v_and_b32_e32 v45, 0xffff0000, v59
	v_and_b32_e32 v44, 0xffff0000, v58
	v_pk_mul_f32 v[42:43], v[0:1], v[42:43] op_sel_hi:[0,1]
	v_mov_b32_e32 v46, v64
	v_mov_b32_e32 v47, v66
	v_lshlrev_b32_e32 v23, 16, v53
	v_lshlrev_b32_e32 v22, 16, v52
	v_and_b32_e32 v25, 0xffff0000, v53
	v_and_b32_e32 v24, 0xffff0000, v52
	v_pk_mul_f32 v[28:29], v[0:1], v[28:29] op_sel_hi:[0,1]
	v_mov_b32_e32 v34, v68
	v_mov_b32_e32 v35, v70
	v_pk_mul_f32 v[32:33], v[0:1], v[32:33] op_sel_hi:[0,1]
	v_mov_b32_e32 v70, v69
	v_and_b32_e32 v41, 0xffff0000, v55
	v_and_b32_e32 v40, 0xffff0000, v54
	v_pk_mul_f32 v[42:43], v[46:47], v[42:43]
	v_pk_mul_f32 v[38:39], v[0:1], v[38:39] op_sel_hi:[0,1]
	v_mov_b32_e32 v46, v2
	v_mov_b32_e32 v47, v4
	v_pk_mul_f32 v[44:45], v[0:1], v[44:45] op_sel_hi:[0,1]
	v_mov_b32_e32 v66, v65
	v_pk_mul_f32 v[28:29], v[34:35], v[28:29]
	v_pk_mul_f32 v[22:23], v[0:1], v[22:23] op_sel_hi:[0,1]
	v_mov_b32_e32 v34, v60
	v_mov_b32_e32 v35, v62
	v_pk_mul_f32 v[32:33], v[70:71], v[32:33]
	v_pk_mul_f32 v[24:25], v[0:1], v[24:25] op_sel_hi:[0,1]
	v_mov_b32_e32 v62, v61
	v_pk_mul_f32 v[38:39], v[46:47], v[38:39]
	v_pk_mul_f32 v[44:45], v[66:67], v[44:45]
	v_pk_mul_f32 v[40:41], v[0:1], v[40:41] op_sel_hi:[0,1]
	v_mov_b32_e32 v4, v3
	v_pk_mul_f32 v[22:23], v[34:35], v[22:23]
	v_pk_mul_f32 v[24:25], v[62:63], v[24:25]
	v_pk_mul_f32 v[40:41], v[4:5], v[40:41]
	s_waitcnt vmcnt(0)
; template <int D, int ROT0, int HALF, bool GAIN, bool KEEP = true>
; DI void chunk_nr(u16* p, const float* __restrict__ gain, const float* __restrict__ tab) {
;     ...
;     if (v >= V0 && v < V0 + 2 * NRV) {
;       if (v >= V0 + NRV) continue;
;       const f32x8 x1 = bf8_to_f32(RAWV(v));
;       const f32x8 x2 = bf8_to_f32(RAWV(v + NRV));
;       f32x8 g1, g2;
;       if (GAIN) { g1 = *(const f32x8*)(gain + v * 8); g2 = *(const f32x8*)(gain + (v + NRV) * 8); }
;       const f32x8 t0 = *(const f32x8*)(tab + 2 * (v - V0) * 8);
;       const f32x8 t1 = *(const f32x8*)(tab + 2 * (v - V0) * 8 + 8);
;       f32x8 o1, o2;
; #pragma unroll
;       for (int e = 0; e < 8; ++e) {
;         float y1 = x1[e], y2 = x2[e];
;         if (GAIN) { y1 = y1 * rstd * g1[e]; y2 = y2 * rstd * g2[e]; }
;         const float c = (e < 4) ? t0[2 * e] : t1[2 * (e - 4)];
;         const float sn = (e < 4) ? t0[2 * e + 1] : t1[2 * (e - 4) + 1];
;         o1[e] = y1 * c - y2 * sn;
;         o2[e] = y2 * c + y1 * sn;
;       }
;       *(u32x4*)(p + v * 8) = f32_to_bf8(o1);
;       *(u32x4*)(p + (v + NRV) * 8) = f32_to_bf8(o2);
	v_mov_b32_e32 v36, v8
	v_mov_b32_e32 v37, v12
	v_mov_b32_e32 v12, v9
	v_mov_b32_e32 v47, v18
	v_mov_b32_e32 v18, v15
	v_mov_b32_e32 v15, v20
	v_mov_b32_e32 v20, v17
	v_mov_b32_e32 v35, v10
	v_mov_b32_e32 v10, v7
	v_pk_mul_f32 v[8:9], v[12:13], v[32:33]
	v_mov_b32_e32 v46, v14
	v_mov_b32_e32 v14, v16
	v_pk_mul_f32 v[4:5], v[20:21], v[44:45]
	v_mov_b32_e32 v34, v6
	v_pk_mul_f32 v[6:7], v[10:11], v[28:29]
	v_pk_fma_f32 v[8:9], v[36:37], v[24:25], v[8:9] neg_lo:[0,0,1] neg_hi:[0,0,1]
	v_pk_mul_f32 v[2:3], v[18:19], v[42:43]
	v_pk_fma_f32 v[4:5], v[14:15], v[40:41], v[4:5] neg_lo:[0,0,1] neg_hi:[0,0,1]
	v_pk_fma_f32 v[6:7], v[34:35], v[22:23], v[6:7] neg_lo:[0,0,1] neg_hi:[0,0,1]
	v_pk_fma_f32 v[2:3], v[46:47], v[38:39], v[2:3] neg_lo:[0,0,1] neg_hi:[0,0,1]
	v_bfe_u32 v0, v5, 16, 1
	v_bfe_u32 v16, v4, 16, 1
	v_bfe_u32 v17, v9, 16, 1
	v_bfe_u32 v48, v8, 16, 1
	v_add3_u32 v8, v8, v48, s54
	v_add3_u32 v9, v9, v17, s54
	v_add3_u32 v4, v4, v16, s54
	v_add3_u32 v0, v5, v0, s54
	v_bfe_u32 v5, v6, 16, 1
	v_bfe_u32 v16, v7, 16, 1
	v_bfe_u32 v17, v2, 16, 1
	v_bfe_u32 v48, v3, 16, 1
	v_add3_u32 v3, v3, v48, s54
	v_add3_u32 v2, v2, v17, s54
	v_add3_u32 v7, v7, v16, s54
	v_add3_u32 v5, v6, v5, s54
	v_lshrrev_b32_e32 v6, 16, v5
	v_lshrrev_b32_e32 v7, 16, v7
	v_lshrrev_b32_e32 v2, 16, v2
	v_lshrrev_b32_e32 v3, 16, v3
	v_and_or_b32 v5, v0, s56, v3
	v_and_or_b32 v4, v4, s56, v2
	v_and_or_b32 v3, v9, s56, v7
	v_and_or_b32 v2, v8, s56, v6
	global_store_dwordx4 v[30:31], v[2:5], off offset:304
	v_pk_mul_f32 v[8:9], v[20:21], v[40:41]
	v_pk_mul_f32 v[6:7], v[18:19], v[38:39]
	v_pk_mul_f32 v[4:5], v[12:13], v[24:25]
	v_pk_mul_f32 v[2:3], v[10:11], v[22:23]
	v_pk_fma_f32 v[4:5], v[36:37], v[32:33], v[4:5]
	v_pk_fma_f32 v[8:9], v[14:15], v[44:45], v[8:9]
	v_pk_fma_f32 v[2:3], v[34:35], v[28:29], v[2:3]
	v_pk_fma_f32 v[6:7], v[46:47], v[42:43], v[6:7]
	v_bfe_u32 v0, v9, 16, 1
	v_bfe_u32 v10, v8, 16, 1
	v_bfe_u32 v11, v5, 16, 1
	v_bfe_u32 v12, v4, 16, 1
	v_add3_u32 v12, v4, v12, s54
	v_add3_u32 v11, v5, v11, s54
	v_add3_u32 v4, v8, v10, s54
	v_add3_u32 v0, v9, v0, s54
	v_bfe_u32 v5, v2, 16, 1
	v_bfe_u32 v8, v3, 16, 1
	v_bfe_u32 v9, v6, 16, 1
	v_bfe_u32 v10, v7, 16, 1
	v_add3_u32 v7, v7, v10, s54
	v_add3_u32 v6, v6, v9, s54
	v_add3_u32 v3, v3, v8, s54
	v_add3_u32 v2, v2, v5, s54
	v_lshrrev_b32_e32 v2, 16, v2
	v_lshrrev_b32_e32 v3, 16, v3
	v_lshrrev_b32_e32 v6, 16, v6
	v_lshrrev_b32_e32 v5, 16, v7
	v_and_or_b32 v5, v0, s56, v5
	v_and_or_b32 v4, v4, s56, v6
	v_and_or_b32 v3, v11, s56, v3
	v_and_or_b32 v2, v12, s56, v2
	global_store_dwordx4 v[30:31], v[2:5], off offset:368
	s_branch .LBB0_190
